# rows: nt hint on X loads and X stores
# speedup vs baseline: 1.0277x; 1.0027x over previous
_Z10fwd_kernelILi4ELi5EEv4Args:
	s_load_dword s3, s[0:1], 0xe8
	s_load_dwordx4 s[4:7], s[0:1], 0xd0
	s_load_dwordx2 s[8:9], s[0:1], 0xa8
	s_load_dwordx2 s[10:11], s[0:1], 0xb0
	s_load_dwordx4 s[12:15], s[0:1], 0x0
	s_waitcnt lgkmcnt(0)
	s_cmp_lg_u32 s3, 0x100
	s_cbranch_scc1 .Lrows4_orig
	v_readfirstlane_b32 s16, v0
	s_lshr_b32 s16, s16, 6
	s_lshl_b32 s18, s2, 3
	s_add_u32 s16, s16, s18
	s_mov_b32 s17, 0x3a800000
	v_mov_b32_e32 v3, 0x358637bd
	v_and_b32_e32 v10, 63, v0
	v_lshlrev_b32_e32 v1, 4, v10
	v_lshlrev_b32_e32 v2, 3, v10
	v_xor_b32_e32 v4, 1, v10
	v_xor_b32_e32 v5, 2, v10
	v_xor_b32_e32 v6, 4, v10
	v_xor_b32_e32 v7, 8, v10
	v_xor_b32_e32 v8, 16, v10
	v_xor_b32_e32 v9, 32, v10
	v_lshlrev_b32_e32 v4, 2, v4
	v_lshlrev_b32_e32 v5, 2, v5
	v_lshlrev_b32_e32 v6, 2, v6
	v_lshlrev_b32_e32 v7, 2, v7
	v_lshlrev_b32_e32 v8, 2, v8
	v_lshlrev_b32_e32 v9, 2, v9
	global_load_dwordx4 v[20:23], v1, s[8:9] offset:0
	global_load_dwordx4 v[24:27], v1, s[8:9] offset:1024
	global_load_dwordx4 v[28:31], v1, s[8:9] offset:2048
	global_load_dwordx4 v[32:35], v1, s[8:9] offset:3072
	global_load_dwordx4 v[36:39], v1, s[10:11] offset:0
	global_load_dwordx4 v[40:43], v1, s[10:11] offset:1024
	global_load_dwordx4 v[44:47], v1, s[10:11] offset:2048
	global_load_dwordx4 v[48:51], v1, s[10:11] offset:3072
	s_lshr_b32 s54, s16, 2
	s_and_b32 s55, s16, 3
	s_lshl_b32 s55, s55, 10
	s_lshl_b32 s18, s54, 12
	s_add_u32 s18, s18, s55
	s_add_u32 s56, s6, s18
	s_addc_u32 s57, s7, 0
	s_add_u32 s56, s56, 0x7400000
	s_addc_u32 s57, s57, 0
	global_load_dwordx4 v[208:211], v1, s[56:57]
	s_add_u32 s56, s56, 0x200000
	s_addc_u32 s57, s57, 0
	global_load_dwordx4 v[212:215], v1, s[56:57]
	s_add_u32 s56, s14, s18
	s_addc_u32 s57, s15, 0
	global_load_dwordx4 v[240:243], v1, s[56:57]
	s_add_u32 s56, s8, s55
	s_addc_u32 s57, s9, 0
	global_load_dwordx4 v[244:247], v1, s[56:57]
	s_add_u32 s56, s10, s55
	s_addc_u32 s57, s11, 0
	global_load_dwordx4 v[248:251], v1, s[56:57]
	s_add_u32 s53, s16, 0x0
	s_lshl_b32 s18, s53, 12
	s_lshl_b32 s19, s53, 11
	s_add_u32 s20, s12, s18
	s_addc_u32 s21, s13, 0
	s_add_u32 s22, s6, s19
	s_addc_u32 s23, s7, 0
	s_add_u32 s22, s22, 0x5200000
	s_addc_u32 s23, s23, 0
	s_add_u32 s24, s4, s18
	s_addc_u32 s25, s5, 0
	s_add_u32 s26, s6, s19
	s_addc_u32 s27, s7, 0
	s_add_u32 s26, s26, 0x3100000
	s_addc_u32 s27, s27, 0
	global_load_dwordx2 v[66:67], v2, s[22:23] offset:0
	global_load_dwordx2 v[70:71], v2, s[22:23] offset:512
	global_load_dwordx2 v[74:75], v2, s[22:23] offset:1024
	global_load_dwordx2 v[78:79], v2, s[22:23] offset:1536
	global_load_dwordx4 v[80:83], v1, s[20:21] offset:0 nt
	global_load_dwordx4 v[84:87], v1, s[20:21] offset:1024 nt
	global_load_dwordx4 v[88:91], v1, s[20:21] offset:2048 nt
	global_load_dwordx4 v[92:95], v1, s[20:21] offset:3072 nt
	s_add_u32 s53, s16, 0x800
	s_lshl_b32 s18, s53, 12
	s_lshl_b32 s19, s53, 11
	s_add_u32 s28, s12, s18
	s_addc_u32 s29, s13, 0
	s_add_u32 s30, s6, s19
	s_addc_u32 s31, s7, 0
	s_add_u32 s30, s30, 0x5200000
	s_addc_u32 s31, s31, 0
	s_add_u32 s32, s4, s18
	s_addc_u32 s33, s5, 0
	s_add_u32 s34, s6, s19
	s_addc_u32 s35, s7, 0
	s_add_u32 s34, s34, 0x3100000
	s_addc_u32 s35, s35, 0
	global_load_dwordx2 v[98:99], v2, s[30:31] offset:0
	global_load_dwordx2 v[102:103], v2, s[30:31] offset:512
	global_load_dwordx2 v[106:107], v2, s[30:31] offset:1024
	global_load_dwordx2 v[110:111], v2, s[30:31] offset:1536
	global_load_dwordx4 v[112:115], v1, s[28:29] offset:0 nt
	global_load_dwordx4 v[116:119], v1, s[28:29] offset:1024 nt
	global_load_dwordx4 v[120:123], v1, s[28:29] offset:2048 nt
	global_load_dwordx4 v[124:127], v1, s[28:29] offset:3072 nt
	s_add_u32 s53, s16, 0x1000
	s_lshl_b32 s18, s53, 12
	s_lshl_b32 s19, s53, 11
	s_add_u32 s36, s12, s18
	s_addc_u32 s37, s13, 0
	s_add_u32 s38, s6, s19
	s_addc_u32 s39, s7, 0
	s_add_u32 s38, s38, 0x5200000
	s_addc_u32 s39, s39, 0
	s_add_u32 s40, s4, s18
	s_addc_u32 s41, s5, 0
	s_add_u32 s42, s6, s19
	s_addc_u32 s43, s7, 0
	s_add_u32 s42, s42, 0x3100000
	s_addc_u32 s43, s43, 0
	global_load_dwordx2 v[130:131], v2, s[38:39] offset:0
	global_load_dwordx2 v[134:135], v2, s[38:39] offset:512
	global_load_dwordx2 v[138:139], v2, s[38:39] offset:1024
	global_load_dwordx2 v[142:143], v2, s[38:39] offset:1536
	global_load_dwordx4 v[144:147], v1, s[36:37] offset:0 nt
	global_load_dwordx4 v[148:151], v1, s[36:37] offset:1024 nt
	global_load_dwordx4 v[152:155], v1, s[36:37] offset:2048 nt
	global_load_dwordx4 v[156:159], v1, s[36:37] offset:3072 nt
	s_add_u32 s53, s16, 0x1800
	s_lshl_b32 s18, s53, 12
	s_lshl_b32 s19, s53, 11
	s_add_u32 s44, s12, s18
	s_addc_u32 s45, s13, 0
	s_add_u32 s46, s6, s19
	s_addc_u32 s47, s7, 0
	s_add_u32 s46, s46, 0x5200000
	s_addc_u32 s47, s47, 0
	s_add_u32 s48, s4, s18
	s_addc_u32 s49, s5, 0
	s_add_u32 s50, s6, s19
	s_addc_u32 s51, s7, 0
	s_add_u32 s50, s50, 0x3100000
	s_addc_u32 s51, s51, 0
	global_load_dwordx2 v[162:163], v2, s[46:47] offset:0
	global_load_dwordx2 v[166:167], v2, s[46:47] offset:512
	global_load_dwordx2 v[170:171], v2, s[46:47] offset:1024
	global_load_dwordx2 v[174:175], v2, s[46:47] offset:1536
	global_load_dwordx4 v[176:179], v1, s[44:45] offset:0 nt
	global_load_dwordx4 v[180:183], v1, s[44:45] offset:1024 nt
	global_load_dwordx4 v[184:187], v1, s[44:45] offset:2048 nt
	global_load_dwordx4 v[188:191], v1, s[44:45] offset:3072 nt
	s_waitcnt vmcnt(16)
	v_lshlrev_b32_e32 v64, 16, v66
	v_and_b32_e32 v65, 0xffff0000, v66
	v_lshlrev_b32_e32 v66, 16, v67
	v_and_b32_e32 v67, 0xffff0000, v67
	v_lshlrev_b32_e32 v68, 16, v70
	v_and_b32_e32 v69, 0xffff0000, v70
	v_lshlrev_b32_e32 v70, 16, v71
	v_and_b32_e32 v71, 0xffff0000, v71
	v_lshlrev_b32_e32 v72, 16, v74
	v_and_b32_e32 v73, 0xffff0000, v74
	v_lshlrev_b32_e32 v74, 16, v75
	v_and_b32_e32 v75, 0xffff0000, v75
	v_lshlrev_b32_e32 v76, 16, v78
	v_and_b32_e32 v77, 0xffff0000, v78
	v_lshlrev_b32_e32 v78, 16, v79
	v_and_b32_e32 v79, 0xffff0000, v79
	v_lshlrev_b32_e32 v96, 16, v98
	v_and_b32_e32 v97, 0xffff0000, v98
	v_lshlrev_b32_e32 v98, 16, v99
	v_and_b32_e32 v99, 0xffff0000, v99
	v_lshlrev_b32_e32 v100, 16, v102
	v_and_b32_e32 v101, 0xffff0000, v102
	v_lshlrev_b32_e32 v102, 16, v103
	v_and_b32_e32 v103, 0xffff0000, v103
	v_lshlrev_b32_e32 v104, 16, v106
	v_and_b32_e32 v105, 0xffff0000, v106
	v_lshlrev_b32_e32 v106, 16, v107
	v_and_b32_e32 v107, 0xffff0000, v107
	v_lshlrev_b32_e32 v108, 16, v110
	v_and_b32_e32 v109, 0xffff0000, v110
	v_lshlrev_b32_e32 v110, 16, v111
	v_and_b32_e32 v111, 0xffff0000, v111
	v_mul_f32_e32 v10, v64, v64
	v_fmac_f32_e32 v10, v65, v65
	v_fmac_f32_e32 v10, v66, v66
	v_fmac_f32_e32 v10, v67, v67
	v_fmac_f32_e32 v10, v68, v68
	v_fmac_f32_e32 v10, v69, v69
	v_fmac_f32_e32 v10, v70, v70
	v_fmac_f32_e32 v10, v71, v71
	v_fmac_f32_e32 v10, v72, v72
	v_fmac_f32_e32 v10, v73, v73
	v_fmac_f32_e32 v10, v74, v74
	v_fmac_f32_e32 v10, v75, v75
	v_fmac_f32_e32 v10, v76, v76
	v_fmac_f32_e32 v10, v77, v77
	v_fmac_f32_e32 v10, v78, v78
	v_fmac_f32_e32 v10, v79, v79
	v_mul_f32_e32 v11, v96, v96
	v_fmac_f32_e32 v11, v97, v97
	v_fmac_f32_e32 v11, v98, v98
	v_fmac_f32_e32 v11, v99, v99
	v_fmac_f32_e32 v11, v100, v100
	v_fmac_f32_e32 v11, v101, v101
	v_fmac_f32_e32 v11, v102, v102
	v_fmac_f32_e32 v11, v103, v103
	v_fmac_f32_e32 v11, v104, v104
	v_fmac_f32_e32 v11, v105, v105
	v_fmac_f32_e32 v11, v106, v106
	v_fmac_f32_e32 v11, v107, v107
	v_fmac_f32_e32 v11, v108, v108
	v_fmac_f32_e32 v11, v109, v109
	v_fmac_f32_e32 v11, v110, v110
	v_fmac_f32_e32 v11, v111, v111
	ds_bpermute_b32 v12, v4, v10
	ds_bpermute_b32 v13, v4, v11
	s_waitcnt lgkmcnt(0)
	v_add_f32_e32 v10, v10, v12
	v_add_f32_e32 v11, v11, v13
	ds_bpermute_b32 v12, v5, v10
	ds_bpermute_b32 v13, v5, v11
	s_waitcnt lgkmcnt(0)
	v_add_f32_e32 v10, v10, v12
	v_add_f32_e32 v11, v11, v13
	ds_bpermute_b32 v12, v6, v10
	ds_bpermute_b32 v13, v6, v11
	s_waitcnt lgkmcnt(0)
	v_add_f32_e32 v10, v10, v12
	v_add_f32_e32 v11, v11, v13
	ds_bpermute_b32 v12, v7, v10
	ds_bpermute_b32 v13, v7, v11
	s_waitcnt lgkmcnt(0)
	v_add_f32_e32 v10, v10, v12
	v_add_f32_e32 v11, v11, v13
	ds_bpermute_b32 v12, v8, v10
	ds_bpermute_b32 v13, v8, v11
	s_waitcnt lgkmcnt(0)
	v_add_f32_e32 v10, v10, v12
	v_add_f32_e32 v11, v11, v13
	ds_bpermute_b32 v12, v9, v10
	ds_bpermute_b32 v13, v9, v11
	s_waitcnt lgkmcnt(0)
	v_add_f32_e32 v10, v10, v12
	v_add_f32_e32 v11, v11, v13
	v_fma_f32 v14, v10, s17, v3
	v_fma_f32 v15, v11, s17, v3
	v_rsq_f32_e32 v14, v14
	v_rsq_f32_e32 v15, v15
	s_nop 0
	v_mul_f32_e32 v64, v64, v14
	v_mul_f32_e32 v65, v65, v14
	v_mul_f32_e32 v66, v66, v14
	v_mul_f32_e32 v67, v67, v14
	v_mul_f32_e32 v68, v68, v14
	v_mul_f32_e32 v69, v69, v14
	v_mul_f32_e32 v70, v70, v14
	v_mul_f32_e32 v71, v71, v14
	v_mul_f32_e32 v72, v72, v14
	v_mul_f32_e32 v73, v73, v14
	v_mul_f32_e32 v74, v74, v14
	v_mul_f32_e32 v75, v75, v14
	v_mul_f32_e32 v76, v76, v14
	v_mul_f32_e32 v77, v77, v14
	v_mul_f32_e32 v78, v78, v14
	v_mul_f32_e32 v79, v79, v14
	v_fmac_f32_e32 v80, v64, v20
	v_fmac_f32_e32 v81, v65, v21
	v_fmac_f32_e32 v82, v66, v22
	v_fmac_f32_e32 v83, v67, v23
	v_fmac_f32_e32 v84, v68, v24
	v_fmac_f32_e32 v85, v69, v25
	v_fmac_f32_e32 v86, v70, v26
	v_fmac_f32_e32 v87, v71, v27
	v_fmac_f32_e32 v88, v72, v28
	v_fmac_f32_e32 v89, v73, v29
	v_fmac_f32_e32 v90, v74, v30
	v_fmac_f32_e32 v91, v75, v31
	v_fmac_f32_e32 v92, v76, v32
	v_fmac_f32_e32 v93, v77, v33
	v_fmac_f32_e32 v94, v78, v34
	v_fmac_f32_e32 v95, v79, v35
	global_store_dwordx4 v1, v[80:83], s[24:25] offset:0 nt
	global_store_dwordx4 v1, v[84:87], s[24:25] offset:1024 nt
	global_store_dwordx4 v1, v[88:91], s[24:25] offset:2048 nt
	global_store_dwordx4 v1, v[92:95], s[24:25] offset:3072 nt
	v_mul_f32_e32 v96, v96, v15
	v_mul_f32_e32 v97, v97, v15
	v_mul_f32_e32 v98, v98, v15
	v_mul_f32_e32 v99, v99, v15
	v_mul_f32_e32 v100, v100, v15
	v_mul_f32_e32 v101, v101, v15
	v_mul_f32_e32 v102, v102, v15
	v_mul_f32_e32 v103, v103, v15
	v_mul_f32_e32 v104, v104, v15
	v_mul_f32_e32 v105, v105, v15
	v_mul_f32_e32 v106, v106, v15
	v_mul_f32_e32 v107, v107, v15
	v_mul_f32_e32 v108, v108, v15
	v_mul_f32_e32 v109, v109, v15
	v_mul_f32_e32 v110, v110, v15
	v_mul_f32_e32 v111, v111, v15
	v_fmac_f32_e32 v112, v96, v20
	v_fmac_f32_e32 v113, v97, v21
	v_fmac_f32_e32 v114, v98, v22
	v_fmac_f32_e32 v115, v99, v23
	v_fmac_f32_e32 v116, v100, v24
	v_fmac_f32_e32 v117, v101, v25
	v_fmac_f32_e32 v118, v102, v26
	v_fmac_f32_e32 v119, v103, v27
	v_fmac_f32_e32 v120, v104, v28
	v_fmac_f32_e32 v121, v105, v29
	v_fmac_f32_e32 v122, v106, v30
	v_fmac_f32_e32 v123, v107, v31
	v_fmac_f32_e32 v124, v108, v32
	v_fmac_f32_e32 v125, v109, v33
	v_fmac_f32_e32 v126, v110, v34
	v_fmac_f32_e32 v127, v111, v35
	global_store_dwordx4 v1, v[112:115], s[32:33] offset:0 nt
	global_store_dwordx4 v1, v[116:119], s[32:33] offset:1024 nt
	global_store_dwordx4 v1, v[120:123], s[32:33] offset:2048 nt
	global_store_dwordx4 v1, v[124:127], s[32:33] offset:3072 nt
	v_mul_f32_e32 v10, v80, v80
	v_fmac_f32_e32 v10, v81, v81
	v_fmac_f32_e32 v10, v82, v82
	v_fmac_f32_e32 v10, v83, v83
	v_fmac_f32_e32 v10, v84, v84
	v_fmac_f32_e32 v10, v85, v85
	v_fmac_f32_e32 v10, v86, v86
	v_fmac_f32_e32 v10, v87, v87
	v_fmac_f32_e32 v10, v88, v88
	v_fmac_f32_e32 v10, v89, v89
	v_fmac_f32_e32 v10, v90, v90
	v_fmac_f32_e32 v10, v91, v91
	v_fmac_f32_e32 v10, v92, v92
	v_fmac_f32_e32 v10, v93, v93
	v_fmac_f32_e32 v10, v94, v94
	v_fmac_f32_e32 v10, v95, v95
	v_mul_f32_e32 v11, v112, v112
	v_fmac_f32_e32 v11, v113, v113
	v_fmac_f32_e32 v11, v114, v114
	v_fmac_f32_e32 v11, v115, v115
	v_fmac_f32_e32 v11, v116, v116
	v_fmac_f32_e32 v11, v117, v117
	v_fmac_f32_e32 v11, v118, v118
	v_fmac_f32_e32 v11, v119, v119
	v_fmac_f32_e32 v11, v120, v120
	v_fmac_f32_e32 v11, v121, v121
	v_fmac_f32_e32 v11, v122, v122
	v_fmac_f32_e32 v11, v123, v123
	v_fmac_f32_e32 v11, v124, v124
	v_fmac_f32_e32 v11, v125, v125
	v_fmac_f32_e32 v11, v126, v126
	v_fmac_f32_e32 v11, v127, v127
	ds_bpermute_b32 v12, v4, v10
	ds_bpermute_b32 v13, v4, v11
	s_waitcnt lgkmcnt(0)
	v_add_f32_e32 v10, v10, v12
	v_add_f32_e32 v11, v11, v13
	ds_bpermute_b32 v12, v5, v10
	ds_bpermute_b32 v13, v5, v11
	s_waitcnt lgkmcnt(0)
	v_add_f32_e32 v10, v10, v12
	v_add_f32_e32 v11, v11, v13
	ds_bpermute_b32 v12, v6, v10
	ds_bpermute_b32 v13, v6, v11
	s_waitcnt lgkmcnt(0)
	v_add_f32_e32 v10, v10, v12
	v_add_f32_e32 v11, v11, v13
	ds_bpermute_b32 v12, v7, v10
	ds_bpermute_b32 v13, v7, v11
	s_waitcnt lgkmcnt(0)
	v_add_f32_e32 v10, v10, v12
	v_add_f32_e32 v11, v11, v13
	ds_bpermute_b32 v12, v8, v10
	ds_bpermute_b32 v13, v8, v11
	s_waitcnt lgkmcnt(0)
	v_add_f32_e32 v10, v10, v12
	v_add_f32_e32 v11, v11, v13
	ds_bpermute_b32 v12, v9, v10
	ds_bpermute_b32 v13, v9, v11
	s_waitcnt lgkmcnt(0)
	v_add_f32_e32 v10, v10, v12
	v_add_f32_e32 v11, v11, v13
	v_fma_f32 v14, v10, s17, v3
	v_fma_f32 v15, v11, s17, v3
	v_rsq_f32_e32 v14, v14
	v_rsq_f32_e32 v15, v15
	s_nop 0
	v_mul_f32_e32 v64, v80, v14
	v_mul_f32_e32 v65, v81, v14
	v_mul_f32_e32 v66, v82, v14
	v_mul_f32_e32 v67, v83, v14
	v_mul_f32_e32 v68, v84, v14
	v_mul_f32_e32 v69, v85, v14
	v_mul_f32_e32 v70, v86, v14
	v_mul_f32_e32 v71, v87, v14
	v_mul_f32_e32 v72, v88, v14
	v_mul_f32_e32 v73, v89, v14
	v_mul_f32_e32 v74, v90, v14
	v_mul_f32_e32 v75, v91, v14
	v_mul_f32_e32 v76, v92, v14
	v_mul_f32_e32 v77, v93, v14
	v_mul_f32_e32 v78, v94, v14
	v_mul_f32_e32 v79, v95, v14
	v_mul_f32_e32 v64, v64, v36
	v_mul_f32_e32 v65, v65, v37
	v_mul_f32_e32 v66, v66, v38
	v_mul_f32_e32 v67, v67, v39
	v_mul_f32_e32 v68, v68, v40
	v_mul_f32_e32 v69, v69, v41
	v_mul_f32_e32 v70, v70, v42
	v_mul_f32_e32 v71, v71, v43
	v_mul_f32_e32 v72, v72, v44
	v_mul_f32_e32 v73, v73, v45
	v_mul_f32_e32 v74, v74, v46
	v_mul_f32_e32 v75, v75, v47
	v_mul_f32_e32 v76, v76, v48
	v_mul_f32_e32 v77, v77, v49
	v_mul_f32_e32 v78, v78, v50
	v_mul_f32_e32 v79, v79, v51
	v_cvt_pk_bf16_f32 v64, v64, v65
	v_cvt_pk_bf16_f32 v65, v66, v67
	v_cvt_pk_bf16_f32 v68, v68, v69
	v_cvt_pk_bf16_f32 v69, v70, v71
	v_cvt_pk_bf16_f32 v72, v72, v73
	v_cvt_pk_bf16_f32 v73, v74, v75
	v_cvt_pk_bf16_f32 v76, v76, v77
	v_cvt_pk_bf16_f32 v77, v78, v79
	global_store_dwordx2 v2, v[64:65], s[26:27] offset:0
	global_store_dwordx2 v2, v[68:69], s[26:27] offset:512
	global_store_dwordx2 v2, v[72:73], s[26:27] offset:1024
	global_store_dwordx2 v2, v[76:77], s[26:27] offset:1536
	v_mul_f32_e32 v96, v112, v15
	v_mul_f32_e32 v97, v113, v15
	v_mul_f32_e32 v98, v114, v15
	v_mul_f32_e32 v99, v115, v15
	v_mul_f32_e32 v100, v116, v15
	v_mul_f32_e32 v101, v117, v15
	v_mul_f32_e32 v102, v118, v15
	v_mul_f32_e32 v103, v119, v15
	v_mul_f32_e32 v104, v120, v15
	v_mul_f32_e32 v105, v121, v15
	v_mul_f32_e32 v106, v122, v15
	v_mul_f32_e32 v107, v123, v15
	v_mul_f32_e32 v108, v124, v15
	v_mul_f32_e32 v109, v125, v15
	v_mul_f32_e32 v110, v126, v15
	v_mul_f32_e32 v111, v127, v15
	v_mul_f32_e32 v96, v96, v36
	v_mul_f32_e32 v97, v97, v37
	v_mul_f32_e32 v98, v98, v38
	v_mul_f32_e32 v99, v99, v39
	v_mul_f32_e32 v100, v100, v40
	v_mul_f32_e32 v101, v101, v41
	v_mul_f32_e32 v102, v102, v42
	v_mul_f32_e32 v103, v103, v43
	v_mul_f32_e32 v104, v104, v44
	v_mul_f32_e32 v105, v105, v45
	v_mul_f32_e32 v106, v106, v46
	v_mul_f32_e32 v107, v107, v47
	v_mul_f32_e32 v108, v108, v48
	v_mul_f32_e32 v109, v109, v49
	v_mul_f32_e32 v110, v110, v50
	v_mul_f32_e32 v111, v111, v51
	v_cvt_pk_bf16_f32 v96, v96, v97
	v_cvt_pk_bf16_f32 v97, v98, v99
	v_cvt_pk_bf16_f32 v100, v100, v101
	v_cvt_pk_bf16_f32 v101, v102, v103
	v_cvt_pk_bf16_f32 v104, v104, v105
	v_cvt_pk_bf16_f32 v105, v106, v107
	v_cvt_pk_bf16_f32 v108, v108, v109
	v_cvt_pk_bf16_f32 v109, v110, v111
	global_store_dwordx2 v2, v[96:97], s[34:35] offset:0
	global_store_dwordx2 v2, v[100:101], s[34:35] offset:512
	global_store_dwordx2 v2, v[104:105], s[34:35] offset:1024
	global_store_dwordx2 v2, v[108:109], s[34:35] offset:1536
	s_add_u32 s53, s16, 0x2000
	s_lshl_b32 s18, s53, 12
	s_lshl_b32 s19, s53, 11
	s_add_u32 s20, s12, s18
	s_addc_u32 s21, s13, 0
	s_add_u32 s22, s6, s19
	s_addc_u32 s23, s7, 0
	s_add_u32 s22, s22, 0x5200000
	s_addc_u32 s23, s23, 0
	s_add_u32 s24, s4, s18
	s_addc_u32 s25, s5, 0
	s_add_u32 s26, s6, s19
	s_addc_u32 s27, s7, 0
	s_add_u32 s26, s26, 0x3100000
	s_addc_u32 s27, s27, 0
	global_load_dwordx2 v[66:67], v2, s[22:23] offset:0
	global_load_dwordx2 v[70:71], v2, s[22:23] offset:512
	global_load_dwordx2 v[74:75], v2, s[22:23] offset:1024
	global_load_dwordx2 v[78:79], v2, s[22:23] offset:1536
	global_load_dwordx4 v[80:83], v1, s[20:21] offset:0 nt
	global_load_dwordx4 v[84:87], v1, s[20:21] offset:1024 nt
	global_load_dwordx4 v[88:91], v1, s[20:21] offset:2048 nt
	global_load_dwordx4 v[92:95], v1, s[20:21] offset:3072 nt
	s_add_u32 s53, s16, 0x2800
	s_lshl_b32 s18, s53, 12
	s_lshl_b32 s19, s53, 11
	s_add_u32 s28, s12, s18
	s_addc_u32 s29, s13, 0
	s_add_u32 s30, s6, s19
	s_addc_u32 s31, s7, 0
	s_add_u32 s30, s30, 0x5200000
	s_addc_u32 s31, s31, 0
	s_add_u32 s32, s4, s18
	s_addc_u32 s33, s5, 0
	s_add_u32 s34, s6, s19
	s_addc_u32 s35, s7, 0
	s_add_u32 s34, s34, 0x3100000
	s_addc_u32 s35, s35, 0
	global_load_dwordx2 v[98:99], v2, s[30:31] offset:0
	global_load_dwordx2 v[102:103], v2, s[30:31] offset:512
	global_load_dwordx2 v[106:107], v2, s[30:31] offset:1024
	global_load_dwordx2 v[110:111], v2, s[30:31] offset:1536
	global_load_dwordx4 v[112:115], v1, s[28:29] offset:0 nt
	global_load_dwordx4 v[116:119], v1, s[28:29] offset:1024 nt
	global_load_dwordx4 v[120:123], v1, s[28:29] offset:2048 nt
	global_load_dwordx4 v[124:127], v1, s[28:29] offset:3072 nt
	s_waitcnt vmcnt(32)
	v_lshlrev_b32_e32 v128, 16, v130
	v_and_b32_e32 v129, 0xffff0000, v130
	v_lshlrev_b32_e32 v130, 16, v131
	v_and_b32_e32 v131, 0xffff0000, v131
	v_lshlrev_b32_e32 v132, 16, v134
	v_and_b32_e32 v133, 0xffff0000, v134
	v_lshlrev_b32_e32 v134, 16, v135
	v_and_b32_e32 v135, 0xffff0000, v135
	v_lshlrev_b32_e32 v136, 16, v138
	v_and_b32_e32 v137, 0xffff0000, v138
	v_lshlrev_b32_e32 v138, 16, v139
	v_and_b32_e32 v139, 0xffff0000, v139
	v_lshlrev_b32_e32 v140, 16, v142
	v_and_b32_e32 v141, 0xffff0000, v142
	v_lshlrev_b32_e32 v142, 16, v143
	v_and_b32_e32 v143, 0xffff0000, v143
	v_lshlrev_b32_e32 v160, 16, v162
	v_and_b32_e32 v161, 0xffff0000, v162
	v_lshlrev_b32_e32 v162, 16, v163
	v_and_b32_e32 v163, 0xffff0000, v163
	v_lshlrev_b32_e32 v164, 16, v166
	v_and_b32_e32 v165, 0xffff0000, v166
	v_lshlrev_b32_e32 v166, 16, v167
	v_and_b32_e32 v167, 0xffff0000, v167
	v_lshlrev_b32_e32 v168, 16, v170
	v_and_b32_e32 v169, 0xffff0000, v170
	v_lshlrev_b32_e32 v170, 16, v171
	v_and_b32_e32 v171, 0xffff0000, v171
	v_lshlrev_b32_e32 v172, 16, v174
	v_and_b32_e32 v173, 0xffff0000, v174
	v_lshlrev_b32_e32 v174, 16, v175
	v_and_b32_e32 v175, 0xffff0000, v175
	v_mul_f32_e32 v10, v128, v128
	v_fmac_f32_e32 v10, v129, v129
	v_fmac_f32_e32 v10, v130, v130
	v_fmac_f32_e32 v10, v131, v131
	v_fmac_f32_e32 v10, v132, v132
	v_fmac_f32_e32 v10, v133, v133
	v_fmac_f32_e32 v10, v134, v134
	v_fmac_f32_e32 v10, v135, v135
	v_fmac_f32_e32 v10, v136, v136
	v_fmac_f32_e32 v10, v137, v137
	v_fmac_f32_e32 v10, v138, v138
	v_fmac_f32_e32 v10, v139, v139
	v_fmac_f32_e32 v10, v140, v140
	v_fmac_f32_e32 v10, v141, v141
	v_fmac_f32_e32 v10, v142, v142
	v_fmac_f32_e32 v10, v143, v143
	v_mul_f32_e32 v11, v160, v160
	v_fmac_f32_e32 v11, v161, v161
	v_fmac_f32_e32 v11, v162, v162
	v_fmac_f32_e32 v11, v163, v163
	v_fmac_f32_e32 v11, v164, v164
	v_fmac_f32_e32 v11, v165, v165
	v_fmac_f32_e32 v11, v166, v166
	v_fmac_f32_e32 v11, v167, v167
	v_fmac_f32_e32 v11, v168, v168
	v_fmac_f32_e32 v11, v169, v169
	v_fmac_f32_e32 v11, v170, v170
	v_fmac_f32_e32 v11, v171, v171
	v_fmac_f32_e32 v11, v172, v172
	v_fmac_f32_e32 v11, v173, v173
	v_fmac_f32_e32 v11, v174, v174
	v_fmac_f32_e32 v11, v175, v175
	ds_bpermute_b32 v12, v4, v10
	ds_bpermute_b32 v13, v4, v11
	s_waitcnt lgkmcnt(0)
	v_add_f32_e32 v10, v10, v12
	v_add_f32_e32 v11, v11, v13
	ds_bpermute_b32 v12, v5, v10
	ds_bpermute_b32 v13, v5, v11
	s_waitcnt lgkmcnt(0)
	v_add_f32_e32 v10, v10, v12
	v_add_f32_e32 v11, v11, v13
	ds_bpermute_b32 v12, v6, v10
	ds_bpermute_b32 v13, v6, v11
	s_waitcnt lgkmcnt(0)
	v_add_f32_e32 v10, v10, v12
	v_add_f32_e32 v11, v11, v13
	ds_bpermute_b32 v12, v7, v10
	ds_bpermute_b32 v13, v7, v11
	s_waitcnt lgkmcnt(0)
	v_add_f32_e32 v10, v10, v12
	v_add_f32_e32 v11, v11, v13
	ds_bpermute_b32 v12, v8, v10
	ds_bpermute_b32 v13, v8, v11
	s_waitcnt lgkmcnt(0)
	v_add_f32_e32 v10, v10, v12
	v_add_f32_e32 v11, v11, v13
	ds_bpermute_b32 v12, v9, v10
	ds_bpermute_b32 v13, v9, v11
	s_waitcnt lgkmcnt(0)
	v_add_f32_e32 v10, v10, v12
	v_add_f32_e32 v11, v11, v13
	v_fma_f32 v14, v10, s17, v3
	v_fma_f32 v15, v11, s17, v3
	v_rsq_f32_e32 v14, v14
	v_rsq_f32_e32 v15, v15
	s_nop 0
	v_mul_f32_e32 v128, v128, v14
	v_mul_f32_e32 v129, v129, v14
	v_mul_f32_e32 v130, v130, v14
	v_mul_f32_e32 v131, v131, v14
	v_mul_f32_e32 v132, v132, v14
	v_mul_f32_e32 v133, v133, v14
	v_mul_f32_e32 v134, v134, v14
	v_mul_f32_e32 v135, v135, v14
	v_mul_f32_e32 v136, v136, v14
	v_mul_f32_e32 v137, v137, v14
	v_mul_f32_e32 v138, v138, v14
	v_mul_f32_e32 v139, v139, v14
	v_mul_f32_e32 v140, v140, v14
	v_mul_f32_e32 v141, v141, v14
	v_mul_f32_e32 v142, v142, v14
	v_mul_f32_e32 v143, v143, v14
	v_fmac_f32_e32 v144, v128, v20
	v_fmac_f32_e32 v145, v129, v21
	v_fmac_f32_e32 v146, v130, v22
	v_fmac_f32_e32 v147, v131, v23
	v_fmac_f32_e32 v148, v132, v24
	v_fmac_f32_e32 v149, v133, v25
	v_fmac_f32_e32 v150, v134, v26
	v_fmac_f32_e32 v151, v135, v27
	v_fmac_f32_e32 v152, v136, v28
	v_fmac_f32_e32 v153, v137, v29
	v_fmac_f32_e32 v154, v138, v30
	v_fmac_f32_e32 v155, v139, v31
	v_fmac_f32_e32 v156, v140, v32
	v_fmac_f32_e32 v157, v141, v33
	v_fmac_f32_e32 v158, v142, v34
	v_fmac_f32_e32 v159, v143, v35
	global_store_dwordx4 v1, v[144:147], s[40:41] offset:0 nt
	global_store_dwordx4 v1, v[148:151], s[40:41] offset:1024 nt
	global_store_dwordx4 v1, v[152:155], s[40:41] offset:2048 nt
	global_store_dwordx4 v1, v[156:159], s[40:41] offset:3072 nt
	v_mul_f32_e32 v160, v160, v15
	v_mul_f32_e32 v161, v161, v15
	v_mul_f32_e32 v162, v162, v15
	v_mul_f32_e32 v163, v163, v15
	v_mul_f32_e32 v164, v164, v15
	v_mul_f32_e32 v165, v165, v15
	v_mul_f32_e32 v166, v166, v15
	v_mul_f32_e32 v167, v167, v15
	v_mul_f32_e32 v168, v168, v15
	v_mul_f32_e32 v169, v169, v15
	v_mul_f32_e32 v170, v170, v15
	v_mul_f32_e32 v171, v171, v15
	v_mul_f32_e32 v172, v172, v15
	v_mul_f32_e32 v173, v173, v15
	v_mul_f32_e32 v174, v174, v15
	v_mul_f32_e32 v175, v175, v15
	v_fmac_f32_e32 v176, v160, v20
	v_fmac_f32_e32 v177, v161, v21
	v_fmac_f32_e32 v178, v162, v22
	v_fmac_f32_e32 v179, v163, v23
	v_fmac_f32_e32 v180, v164, v24
	v_fmac_f32_e32 v181, v165, v25
	v_fmac_f32_e32 v182, v166, v26
	v_fmac_f32_e32 v183, v167, v27
	v_fmac_f32_e32 v184, v168, v28
	v_fmac_f32_e32 v185, v169, v29
	v_fmac_f32_e32 v186, v170, v30
	v_fmac_f32_e32 v187, v171, v31
	v_fmac_f32_e32 v188, v172, v32
	v_fmac_f32_e32 v189, v173, v33
	v_fmac_f32_e32 v190, v174, v34
	v_fmac_f32_e32 v191, v175, v35
	global_store_dwordx4 v1, v[176:179], s[48:49] offset:0 nt
	global_store_dwordx4 v1, v[180:183], s[48:49] offset:1024 nt
	global_store_dwordx4 v1, v[184:187], s[48:49] offset:2048 nt
	global_store_dwordx4 v1, v[188:191], s[48:49] offset:3072 nt
	v_mul_f32_e32 v10, v144, v144
	v_fmac_f32_e32 v10, v145, v145
	v_fmac_f32_e32 v10, v146, v146
	v_fmac_f32_e32 v10, v147, v147
	v_fmac_f32_e32 v10, v148, v148
	v_fmac_f32_e32 v10, v149, v149
	v_fmac_f32_e32 v10, v150, v150
	v_fmac_f32_e32 v10, v151, v151
	v_fmac_f32_e32 v10, v152, v152
	v_fmac_f32_e32 v10, v153, v153
	v_fmac_f32_e32 v10, v154, v154
	v_fmac_f32_e32 v10, v155, v155
	v_fmac_f32_e32 v10, v156, v156
	v_fmac_f32_e32 v10, v157, v157
	v_fmac_f32_e32 v10, v158, v158
	v_fmac_f32_e32 v10, v159, v159
	v_mul_f32_e32 v11, v176, v176
	v_fmac_f32_e32 v11, v177, v177
	v_fmac_f32_e32 v11, v178, v178
	v_fmac_f32_e32 v11, v179, v179
	v_fmac_f32_e32 v11, v180, v180
	v_fmac_f32_e32 v11, v181, v181
	v_fmac_f32_e32 v11, v182, v182
	v_fmac_f32_e32 v11, v183, v183
	v_fmac_f32_e32 v11, v184, v184
	v_fmac_f32_e32 v11, v185, v185
	v_fmac_f32_e32 v11, v186, v186
	v_fmac_f32_e32 v11, v187, v187
	v_fmac_f32_e32 v11, v188, v188
	v_fmac_f32_e32 v11, v189, v189
	v_fmac_f32_e32 v11, v190, v190
	v_fmac_f32_e32 v11, v191, v191
	ds_bpermute_b32 v12, v4, v10
	ds_bpermute_b32 v13, v4, v11
	s_waitcnt lgkmcnt(0)
	v_add_f32_e32 v10, v10, v12
	v_add_f32_e32 v11, v11, v13
	ds_bpermute_b32 v12, v5, v10
	ds_bpermute_b32 v13, v5, v11
	s_waitcnt lgkmcnt(0)
	v_add_f32_e32 v10, v10, v12
	v_add_f32_e32 v11, v11, v13
	ds_bpermute_b32 v12, v6, v10
	ds_bpermute_b32 v13, v6, v11
	s_waitcnt lgkmcnt(0)
	v_add_f32_e32 v10, v10, v12
	v_add_f32_e32 v11, v11, v13
	ds_bpermute_b32 v12, v7, v10
	ds_bpermute_b32 v13, v7, v11
	s_waitcnt lgkmcnt(0)
	v_add_f32_e32 v10, v10, v12
	v_add_f32_e32 v11, v11, v13
	ds_bpermute_b32 v12, v8, v10
	ds_bpermute_b32 v13, v8, v11
	s_waitcnt lgkmcnt(0)
	v_add_f32_e32 v10, v10, v12
	v_add_f32_e32 v11, v11, v13
	ds_bpermute_b32 v12, v9, v10
	ds_bpermute_b32 v13, v9, v11
	s_waitcnt lgkmcnt(0)
	v_add_f32_e32 v10, v10, v12
	v_add_f32_e32 v11, v11, v13
	v_fma_f32 v14, v10, s17, v3
	v_fma_f32 v15, v11, s17, v3
	v_rsq_f32_e32 v14, v14
	v_rsq_f32_e32 v15, v15
	s_nop 0
	v_mul_f32_e32 v128, v144, v14
	v_mul_f32_e32 v129, v145, v14
	v_mul_f32_e32 v130, v146, v14
	v_mul_f32_e32 v131, v147, v14
	v_mul_f32_e32 v132, v148, v14
	v_mul_f32_e32 v133, v149, v14
	v_mul_f32_e32 v134, v150, v14
	v_mul_f32_e32 v135, v151, v14
	v_mul_f32_e32 v136, v152, v14
	v_mul_f32_e32 v137, v153, v14
	v_mul_f32_e32 v138, v154, v14
	v_mul_f32_e32 v139, v155, v14
	v_mul_f32_e32 v140, v156, v14
	v_mul_f32_e32 v141, v157, v14
	v_mul_f32_e32 v142, v158, v14
	v_mul_f32_e32 v143, v159, v14
	v_mul_f32_e32 v128, v128, v36
	v_mul_f32_e32 v129, v129, v37
	v_mul_f32_e32 v130, v130, v38
	v_mul_f32_e32 v131, v131, v39
	v_mul_f32_e32 v132, v132, v40
	v_mul_f32_e32 v133, v133, v41
	v_mul_f32_e32 v134, v134, v42
	v_mul_f32_e32 v135, v135, v43
	v_mul_f32_e32 v136, v136, v44
	v_mul_f32_e32 v137, v137, v45
	v_mul_f32_e32 v138, v138, v46
	v_mul_f32_e32 v139, v139, v47
	v_mul_f32_e32 v140, v140, v48
	v_mul_f32_e32 v141, v141, v49
	v_mul_f32_e32 v142, v142, v50
	v_mul_f32_e32 v143, v143, v51
	v_cvt_pk_bf16_f32 v128, v128, v129
	v_cvt_pk_bf16_f32 v129, v130, v131
	v_cvt_pk_bf16_f32 v132, v132, v133
	v_cvt_pk_bf16_f32 v133, v134, v135
	v_cvt_pk_bf16_f32 v136, v136, v137
	v_cvt_pk_bf16_f32 v137, v138, v139
	v_cvt_pk_bf16_f32 v140, v140, v141
	v_cvt_pk_bf16_f32 v141, v142, v143
	global_store_dwordx2 v2, v[128:129], s[42:43] offset:0
	global_store_dwordx2 v2, v[132:133], s[42:43] offset:512
	global_store_dwordx2 v2, v[136:137], s[42:43] offset:1024
	global_store_dwordx2 v2, v[140:141], s[42:43] offset:1536
	v_mul_f32_e32 v160, v176, v15
	v_mul_f32_e32 v161, v177, v15
	v_mul_f32_e32 v162, v178, v15
	v_mul_f32_e32 v163, v179, v15
	v_mul_f32_e32 v164, v180, v15
	v_mul_f32_e32 v165, v181, v15
	v_mul_f32_e32 v166, v182, v15
	v_mul_f32_e32 v167, v183, v15
	v_mul_f32_e32 v168, v184, v15
	v_mul_f32_e32 v169, v185, v15
	v_mul_f32_e32 v170, v186, v15
	v_mul_f32_e32 v171, v187, v15
	v_mul_f32_e32 v172, v188, v15
	v_mul_f32_e32 v173, v189, v15
	v_mul_f32_e32 v174, v190, v15
	v_mul_f32_e32 v175, v191, v15
	v_mul_f32_e32 v160, v160, v36
	v_mul_f32_e32 v161, v161, v37
	v_mul_f32_e32 v162, v162, v38
	v_mul_f32_e32 v163, v163, v39
	v_mul_f32_e32 v164, v164, v40
	v_mul_f32_e32 v165, v165, v41
	v_mul_f32_e32 v166, v166, v42
	v_mul_f32_e32 v167, v167, v43
	v_mul_f32_e32 v168, v168, v44
	v_mul_f32_e32 v169, v169, v45
	v_mul_f32_e32 v170, v170, v46
	v_mul_f32_e32 v171, v171, v47
	v_mul_f32_e32 v172, v172, v48
	v_mul_f32_e32 v173, v173, v49
	v_mul_f32_e32 v174, v174, v50
	v_mul_f32_e32 v175, v175, v51
	v_cvt_pk_bf16_f32 v160, v160, v161
	v_cvt_pk_bf16_f32 v161, v162, v163
	v_cvt_pk_bf16_f32 v164, v164, v165
	v_cvt_pk_bf16_f32 v165, v166, v167
	v_cvt_pk_bf16_f32 v168, v168, v169
	v_cvt_pk_bf16_f32 v169, v170, v171
	v_cvt_pk_bf16_f32 v172, v172, v173
	v_cvt_pk_bf16_f32 v173, v174, v175
	global_store_dwordx2 v2, v[160:161], s[50:51] offset:0
	global_store_dwordx2 v2, v[164:165], s[50:51] offset:512
	global_store_dwordx2 v2, v[168:169], s[50:51] offset:1024
	global_store_dwordx2 v2, v[172:173], s[50:51] offset:1536
	s_add_u32 s53, s16, 0x3000
	s_lshl_b32 s18, s53, 12
	s_lshl_b32 s19, s53, 11
	s_add_u32 s36, s12, s18
	s_addc_u32 s37, s13, 0
	s_add_u32 s38, s6, s19
	s_addc_u32 s39, s7, 0
	s_add_u32 s38, s38, 0x5200000
	s_addc_u32 s39, s39, 0
	s_add_u32 s40, s4, s18
	s_addc_u32 s41, s5, 0
	s_add_u32 s42, s6, s19
	s_addc_u32 s43, s7, 0
	s_add_u32 s42, s42, 0x3100000
	s_addc_u32 s43, s43, 0
	global_load_dwordx2 v[130:131], v2, s[38:39] offset:0
	global_load_dwordx2 v[134:135], v2, s[38:39] offset:512
	global_load_dwordx2 v[138:139], v2, s[38:39] offset:1024
	global_load_dwordx2 v[142:143], v2, s[38:39] offset:1536
	global_load_dwordx4 v[144:147], v1, s[36:37] offset:0 nt
	global_load_dwordx4 v[148:151], v1, s[36:37] offset:1024 nt
	global_load_dwordx4 v[152:155], v1, s[36:37] offset:2048 nt
	global_load_dwordx4 v[156:159], v1, s[36:37] offset:3072 nt
	s_add_u32 s53, s16, 0x3800
	s_lshl_b32 s18, s53, 12
	s_lshl_b32 s19, s53, 11
	s_add_u32 s44, s12, s18
	s_addc_u32 s45, s13, 0
	s_add_u32 s46, s6, s19
	s_addc_u32 s47, s7, 0
	s_add_u32 s46, s46, 0x5200000
	s_addc_u32 s47, s47, 0
	s_add_u32 s48, s4, s18
	s_addc_u32 s49, s5, 0
	s_add_u32 s50, s6, s19
	s_addc_u32 s51, s7, 0
	s_add_u32 s50, s50, 0x3100000
	s_addc_u32 s51, s51, 0
	global_load_dwordx2 v[162:163], v2, s[46:47] offset:0
	global_load_dwordx2 v[166:167], v2, s[46:47] offset:512
	global_load_dwordx2 v[170:171], v2, s[46:47] offset:1024
	global_load_dwordx2 v[174:175], v2, s[46:47] offset:1536
	global_load_dwordx4 v[176:179], v1, s[44:45] offset:0 nt
	global_load_dwordx4 v[180:183], v1, s[44:45] offset:1024 nt
	global_load_dwordx4 v[184:187], v1, s[44:45] offset:2048 nt
	global_load_dwordx4 v[188:191], v1, s[44:45] offset:3072 nt
	s_waitcnt vmcnt(32)
	v_lshlrev_b32_e32 v64, 16, v66
	v_and_b32_e32 v65, 0xffff0000, v66
	v_lshlrev_b32_e32 v66, 16, v67
	v_and_b32_e32 v67, 0xffff0000, v67
	v_lshlrev_b32_e32 v68, 16, v70
	v_and_b32_e32 v69, 0xffff0000, v70
	v_lshlrev_b32_e32 v70, 16, v71
	v_and_b32_e32 v71, 0xffff0000, v71
	v_lshlrev_b32_e32 v72, 16, v74
	v_and_b32_e32 v73, 0xffff0000, v74
	v_lshlrev_b32_e32 v74, 16, v75
	v_and_b32_e32 v75, 0xffff0000, v75
	v_lshlrev_b32_e32 v76, 16, v78
	v_and_b32_e32 v77, 0xffff0000, v78
	v_lshlrev_b32_e32 v78, 16, v79
	v_and_b32_e32 v79, 0xffff0000, v79
	v_lshlrev_b32_e32 v96, 16, v98
	v_and_b32_e32 v97, 0xffff0000, v98
	v_lshlrev_b32_e32 v98, 16, v99
	v_and_b32_e32 v99, 0xffff0000, v99
	v_lshlrev_b32_e32 v100, 16, v102
	v_and_b32_e32 v101, 0xffff0000, v102
	v_lshlrev_b32_e32 v102, 16, v103
	v_and_b32_e32 v103, 0xffff0000, v103
	v_lshlrev_b32_e32 v104, 16, v106
	v_and_b32_e32 v105, 0xffff0000, v106
	v_lshlrev_b32_e32 v106, 16, v107
	v_and_b32_e32 v107, 0xffff0000, v107
	v_lshlrev_b32_e32 v108, 16, v110
	v_and_b32_e32 v109, 0xffff0000, v110
	v_lshlrev_b32_e32 v110, 16, v111
	v_and_b32_e32 v111, 0xffff0000, v111
	v_mul_f32_e32 v10, v64, v64
	v_fmac_f32_e32 v10, v65, v65
	v_fmac_f32_e32 v10, v66, v66
	v_fmac_f32_e32 v10, v67, v67
	v_fmac_f32_e32 v10, v68, v68
	v_fmac_f32_e32 v10, v69, v69
	v_fmac_f32_e32 v10, v70, v70
	v_fmac_f32_e32 v10, v71, v71
	v_fmac_f32_e32 v10, v72, v72
	v_fmac_f32_e32 v10, v73, v73
	v_fmac_f32_e32 v10, v74, v74
	v_fmac_f32_e32 v10, v75, v75
	v_fmac_f32_e32 v10, v76, v76
	v_fmac_f32_e32 v10, v77, v77
	v_fmac_f32_e32 v10, v78, v78
	v_fmac_f32_e32 v10, v79, v79
	v_mul_f32_e32 v11, v96, v96
	v_fmac_f32_e32 v11, v97, v97
	v_fmac_f32_e32 v11, v98, v98
	v_fmac_f32_e32 v11, v99, v99
	v_fmac_f32_e32 v11, v100, v100
	v_fmac_f32_e32 v11, v101, v101
	v_fmac_f32_e32 v11, v102, v102
	v_fmac_f32_e32 v11, v103, v103
	v_fmac_f32_e32 v11, v104, v104
	v_fmac_f32_e32 v11, v105, v105
	v_fmac_f32_e32 v11, v106, v106
	v_fmac_f32_e32 v11, v107, v107
	v_fmac_f32_e32 v11, v108, v108
	v_fmac_f32_e32 v11, v109, v109
	v_fmac_f32_e32 v11, v110, v110
	v_fmac_f32_e32 v11, v111, v111
	ds_bpermute_b32 v12, v4, v10
	ds_bpermute_b32 v13, v4, v11
	s_waitcnt lgkmcnt(0)
	v_add_f32_e32 v10, v10, v12
	v_add_f32_e32 v11, v11, v13
	ds_bpermute_b32 v12, v5, v10
	ds_bpermute_b32 v13, v5, v11
	s_waitcnt lgkmcnt(0)
	v_add_f32_e32 v10, v10, v12
	v_add_f32_e32 v11, v11, v13
	ds_bpermute_b32 v12, v6, v10
	ds_bpermute_b32 v13, v6, v11
	s_waitcnt lgkmcnt(0)
	v_add_f32_e32 v10, v10, v12
	v_add_f32_e32 v11, v11, v13
	ds_bpermute_b32 v12, v7, v10
	ds_bpermute_b32 v13, v7, v11
	s_waitcnt lgkmcnt(0)
	v_add_f32_e32 v10, v10, v12
	v_add_f32_e32 v11, v11, v13
	ds_bpermute_b32 v12, v8, v10
	ds_bpermute_b32 v13, v8, v11
	s_waitcnt lgkmcnt(0)
	v_add_f32_e32 v10, v10, v12
	v_add_f32_e32 v11, v11, v13
	ds_bpermute_b32 v12, v9, v10
	ds_bpermute_b32 v13, v9, v11
	s_waitcnt lgkmcnt(0)
	v_add_f32_e32 v10, v10, v12
	v_add_f32_e32 v11, v11, v13
	v_fma_f32 v14, v10, s17, v3
	v_fma_f32 v15, v11, s17, v3
	v_rsq_f32_e32 v14, v14
	v_rsq_f32_e32 v15, v15
	s_nop 0
	v_mul_f32_e32 v64, v64, v14
	v_mul_f32_e32 v65, v65, v14
	v_mul_f32_e32 v66, v66, v14
	v_mul_f32_e32 v67, v67, v14
	v_mul_f32_e32 v68, v68, v14
	v_mul_f32_e32 v69, v69, v14
	v_mul_f32_e32 v70, v70, v14
	v_mul_f32_e32 v71, v71, v14
	v_mul_f32_e32 v72, v72, v14
	v_mul_f32_e32 v73, v73, v14
	v_mul_f32_e32 v74, v74, v14
	v_mul_f32_e32 v75, v75, v14
	v_mul_f32_e32 v76, v76, v14
	v_mul_f32_e32 v77, v77, v14
	v_mul_f32_e32 v78, v78, v14
	v_mul_f32_e32 v79, v79, v14
	v_fmac_f32_e32 v80, v64, v20
	v_fmac_f32_e32 v81, v65, v21
	v_fmac_f32_e32 v82, v66, v22
	v_fmac_f32_e32 v83, v67, v23
	v_fmac_f32_e32 v84, v68, v24
	v_fmac_f32_e32 v85, v69, v25
	v_fmac_f32_e32 v86, v70, v26
	v_fmac_f32_e32 v87, v71, v27
	v_fmac_f32_e32 v88, v72, v28
	v_fmac_f32_e32 v89, v73, v29
	v_fmac_f32_e32 v90, v74, v30
	v_fmac_f32_e32 v91, v75, v31
	v_fmac_f32_e32 v92, v76, v32
	v_fmac_f32_e32 v93, v77, v33
	v_fmac_f32_e32 v94, v78, v34
	v_fmac_f32_e32 v95, v79, v35
	global_store_dwordx4 v1, v[80:83], s[24:25] offset:0 nt
	global_store_dwordx4 v1, v[84:87], s[24:25] offset:1024 nt
	global_store_dwordx4 v1, v[88:91], s[24:25] offset:2048 nt
	global_store_dwordx4 v1, v[92:95], s[24:25] offset:3072 nt
	v_mul_f32_e32 v96, v96, v15
	v_mul_f32_e32 v97, v97, v15
	v_mul_f32_e32 v98, v98, v15
	v_mul_f32_e32 v99, v99, v15
	v_mul_f32_e32 v100, v100, v15
	v_mul_f32_e32 v101, v101, v15
	v_mul_f32_e32 v102, v102, v15
	v_mul_f32_e32 v103, v103, v15
	v_mul_f32_e32 v104, v104, v15
	v_mul_f32_e32 v105, v105, v15
	v_mul_f32_e32 v106, v106, v15
	v_mul_f32_e32 v107, v107, v15
	v_mul_f32_e32 v108, v108, v15
	v_mul_f32_e32 v109, v109, v15
	v_mul_f32_e32 v110, v110, v15
	v_mul_f32_e32 v111, v111, v15
	v_fmac_f32_e32 v112, v96, v20
	v_fmac_f32_e32 v113, v97, v21
	v_fmac_f32_e32 v114, v98, v22
	v_fmac_f32_e32 v115, v99, v23
	v_fmac_f32_e32 v116, v100, v24
	v_fmac_f32_e32 v117, v101, v25
	v_fmac_f32_e32 v118, v102, v26
	v_fmac_f32_e32 v119, v103, v27
	v_fmac_f32_e32 v120, v104, v28
	v_fmac_f32_e32 v121, v105, v29
	v_fmac_f32_e32 v122, v106, v30
	v_fmac_f32_e32 v123, v107, v31
	v_fmac_f32_e32 v124, v108, v32
	v_fmac_f32_e32 v125, v109, v33
	v_fmac_f32_e32 v126, v110, v34
	v_fmac_f32_e32 v127, v111, v35
	global_store_dwordx4 v1, v[112:115], s[32:33] offset:0 nt
	global_store_dwordx4 v1, v[116:119], s[32:33] offset:1024 nt
	global_store_dwordx4 v1, v[120:123], s[32:33] offset:2048 nt
	global_store_dwordx4 v1, v[124:127], s[32:33] offset:3072 nt
	v_mul_f32_e32 v10, v80, v80
	v_fmac_f32_e32 v10, v81, v81
	v_fmac_f32_e32 v10, v82, v82
	v_fmac_f32_e32 v10, v83, v83
	v_fmac_f32_e32 v10, v84, v84
	v_fmac_f32_e32 v10, v85, v85
	v_fmac_f32_e32 v10, v86, v86
	v_fmac_f32_e32 v10, v87, v87
	v_fmac_f32_e32 v10, v88, v88
	v_fmac_f32_e32 v10, v89, v89
	v_fmac_f32_e32 v10, v90, v90
	v_fmac_f32_e32 v10, v91, v91
	v_fmac_f32_e32 v10, v92, v92
	v_fmac_f32_e32 v10, v93, v93
	v_fmac_f32_e32 v10, v94, v94
	v_fmac_f32_e32 v10, v95, v95
	v_mul_f32_e32 v11, v112, v112
	v_fmac_f32_e32 v11, v113, v113
	v_fmac_f32_e32 v11, v114, v114
	v_fmac_f32_e32 v11, v115, v115
	v_fmac_f32_e32 v11, v116, v116
	v_fmac_f32_e32 v11, v117, v117
	v_fmac_f32_e32 v11, v118, v118
	v_fmac_f32_e32 v11, v119, v119
	v_fmac_f32_e32 v11, v120, v120
	v_fmac_f32_e32 v11, v121, v121
	v_fmac_f32_e32 v11, v122, v122
	v_fmac_f32_e32 v11, v123, v123
	v_fmac_f32_e32 v11, v124, v124
	v_fmac_f32_e32 v11, v125, v125
	v_fmac_f32_e32 v11, v126, v126
	v_fmac_f32_e32 v11, v127, v127
	ds_bpermute_b32 v12, v4, v10
	ds_bpermute_b32 v13, v4, v11
	s_waitcnt lgkmcnt(0)
	v_add_f32_e32 v10, v10, v12
	v_add_f32_e32 v11, v11, v13
	ds_bpermute_b32 v12, v5, v10
	ds_bpermute_b32 v13, v5, v11
	s_waitcnt lgkmcnt(0)
	v_add_f32_e32 v10, v10, v12
	v_add_f32_e32 v11, v11, v13
	ds_bpermute_b32 v12, v6, v10
	ds_bpermute_b32 v13, v6, v11
	s_waitcnt lgkmcnt(0)
	v_add_f32_e32 v10, v10, v12
	v_add_f32_e32 v11, v11, v13
	ds_bpermute_b32 v12, v7, v10
	ds_bpermute_b32 v13, v7, v11
	s_waitcnt lgkmcnt(0)
	v_add_f32_e32 v10, v10, v12
	v_add_f32_e32 v11, v11, v13
	ds_bpermute_b32 v12, v8, v10
	ds_bpermute_b32 v13, v8, v11
	s_waitcnt lgkmcnt(0)
	v_add_f32_e32 v10, v10, v12
	v_add_f32_e32 v11, v11, v13
	ds_bpermute_b32 v12, v9, v10
	ds_bpermute_b32 v13, v9, v11
	s_waitcnt lgkmcnt(0)
	v_add_f32_e32 v10, v10, v12
	v_add_f32_e32 v11, v11, v13
	v_fma_f32 v14, v10, s17, v3
	v_fma_f32 v15, v11, s17, v3
	v_rsq_f32_e32 v14, v14
	v_rsq_f32_e32 v15, v15
	s_nop 0
	v_mul_f32_e32 v64, v80, v14
	v_mul_f32_e32 v65, v81, v14
	v_mul_f32_e32 v66, v82, v14
	v_mul_f32_e32 v67, v83, v14
	v_mul_f32_e32 v68, v84, v14
	v_mul_f32_e32 v69, v85, v14
	v_mul_f32_e32 v70, v86, v14
	v_mul_f32_e32 v71, v87, v14
	v_mul_f32_e32 v72, v88, v14
	v_mul_f32_e32 v73, v89, v14
	v_mul_f32_e32 v74, v90, v14
	v_mul_f32_e32 v75, v91, v14
	v_mul_f32_e32 v76, v92, v14
	v_mul_f32_e32 v77, v93, v14
	v_mul_f32_e32 v78, v94, v14
	v_mul_f32_e32 v79, v95, v14
	v_mul_f32_e32 v64, v64, v36
	v_mul_f32_e32 v65, v65, v37
	v_mul_f32_e32 v66, v66, v38
	v_mul_f32_e32 v67, v67, v39
	v_mul_f32_e32 v68, v68, v40
	v_mul_f32_e32 v69, v69, v41
	v_mul_f32_e32 v70, v70, v42
	v_mul_f32_e32 v71, v71, v43
	v_mul_f32_e32 v72, v72, v44
	v_mul_f32_e32 v73, v73, v45
	v_mul_f32_e32 v74, v74, v46
	v_mul_f32_e32 v75, v75, v47
	v_mul_f32_e32 v76, v76, v48
	v_mul_f32_e32 v77, v77, v49
	v_mul_f32_e32 v78, v78, v50
	v_mul_f32_e32 v79, v79, v51
	v_cvt_pk_bf16_f32 v64, v64, v65
	v_cvt_pk_bf16_f32 v65, v66, v67
	v_cvt_pk_bf16_f32 v68, v68, v69
	v_cvt_pk_bf16_f32 v69, v70, v71
	v_cvt_pk_bf16_f32 v72, v72, v73
	v_cvt_pk_bf16_f32 v73, v74, v75
	v_cvt_pk_bf16_f32 v76, v76, v77
	v_cvt_pk_bf16_f32 v77, v78, v79
	global_store_dwordx2 v2, v[64:65], s[26:27] offset:0
	global_store_dwordx2 v2, v[68:69], s[26:27] offset:512
	global_store_dwordx2 v2, v[72:73], s[26:27] offset:1024
	global_store_dwordx2 v2, v[76:77], s[26:27] offset:1536
	v_mul_f32_e32 v96, v112, v15
	v_mul_f32_e32 v97, v113, v15
	v_mul_f32_e32 v98, v114, v15
	v_mul_f32_e32 v99, v115, v15
	v_mul_f32_e32 v100, v116, v15
	v_mul_f32_e32 v101, v117, v15
	v_mul_f32_e32 v102, v118, v15
	v_mul_f32_e32 v103, v119, v15
	v_mul_f32_e32 v104, v120, v15
	v_mul_f32_e32 v105, v121, v15
	v_mul_f32_e32 v106, v122, v15
	v_mul_f32_e32 v107, v123, v15
	v_mul_f32_e32 v108, v124, v15
	v_mul_f32_e32 v109, v125, v15
	v_mul_f32_e32 v110, v126, v15
	v_mul_f32_e32 v111, v127, v15
	v_mul_f32_e32 v96, v96, v36
	v_mul_f32_e32 v97, v97, v37
	v_mul_f32_e32 v98, v98, v38
	v_mul_f32_e32 v99, v99, v39
	v_mul_f32_e32 v100, v100, v40
	v_mul_f32_e32 v101, v101, v41
	v_mul_f32_e32 v102, v102, v42
	v_mul_f32_e32 v103, v103, v43
	v_mul_f32_e32 v104, v104, v44
	v_mul_f32_e32 v105, v105, v45
	v_mul_f32_e32 v106, v106, v46
	v_mul_f32_e32 v107, v107, v47
	v_mul_f32_e32 v108, v108, v48
	v_mul_f32_e32 v109, v109, v49
	v_mul_f32_e32 v110, v110, v50
	v_mul_f32_e32 v111, v111, v51
	v_cvt_pk_bf16_f32 v96, v96, v97
	v_cvt_pk_bf16_f32 v97, v98, v99
	v_cvt_pk_bf16_f32 v100, v100, v101
	v_cvt_pk_bf16_f32 v101, v102, v103
	v_cvt_pk_bf16_f32 v104, v104, v105
	v_cvt_pk_bf16_f32 v105, v106, v107
	v_cvt_pk_bf16_f32 v108, v108, v109
	v_cvt_pk_bf16_f32 v109, v110, v111
	global_store_dwordx2 v2, v[96:97], s[34:35] offset:0
	global_store_dwordx2 v2, v[100:101], s[34:35] offset:512
	global_store_dwordx2 v2, v[104:105], s[34:35] offset:1024
	global_store_dwordx2 v2, v[108:109], s[34:35] offset:1536
	s_waitcnt vmcnt(16)
	v_lshlrev_b32_e32 v128, 16, v130
	v_and_b32_e32 v129, 0xffff0000, v130
	v_lshlrev_b32_e32 v130, 16, v131
	v_and_b32_e32 v131, 0xffff0000, v131
	v_lshlrev_b32_e32 v132, 16, v134
	v_and_b32_e32 v133, 0xffff0000, v134
	v_lshlrev_b32_e32 v134, 16, v135
	v_and_b32_e32 v135, 0xffff0000, v135
	v_lshlrev_b32_e32 v136, 16, v138
	v_and_b32_e32 v137, 0xffff0000, v138
	v_lshlrev_b32_e32 v138, 16, v139
	v_and_b32_e32 v139, 0xffff0000, v139
	v_lshlrev_b32_e32 v140, 16, v142
	v_and_b32_e32 v141, 0xffff0000, v142
	v_lshlrev_b32_e32 v142, 16, v143
	v_and_b32_e32 v143, 0xffff0000, v143
	v_lshlrev_b32_e32 v160, 16, v162
	v_and_b32_e32 v161, 0xffff0000, v162
	v_lshlrev_b32_e32 v162, 16, v163
	v_and_b32_e32 v163, 0xffff0000, v163
	v_lshlrev_b32_e32 v164, 16, v166
	v_and_b32_e32 v165, 0xffff0000, v166
	v_lshlrev_b32_e32 v166, 16, v167
	v_and_b32_e32 v167, 0xffff0000, v167
	v_lshlrev_b32_e32 v168, 16, v170
	v_and_b32_e32 v169, 0xffff0000, v170
	v_lshlrev_b32_e32 v170, 16, v171
	v_and_b32_e32 v171, 0xffff0000, v171
	v_lshlrev_b32_e32 v172, 16, v174
	v_and_b32_e32 v173, 0xffff0000, v174
	v_lshlrev_b32_e32 v174, 16, v175
	v_and_b32_e32 v175, 0xffff0000, v175
	v_mul_f32_e32 v10, v128, v128
	v_fmac_f32_e32 v10, v129, v129
	v_fmac_f32_e32 v10, v130, v130
	v_fmac_f32_e32 v10, v131, v131
	v_fmac_f32_e32 v10, v132, v132
	v_fmac_f32_e32 v10, v133, v133
	v_fmac_f32_e32 v10, v134, v134
	v_fmac_f32_e32 v10, v135, v135
	v_fmac_f32_e32 v10, v136, v136
	v_fmac_f32_e32 v10, v137, v137
	v_fmac_f32_e32 v10, v138, v138
	v_fmac_f32_e32 v10, v139, v139
	v_fmac_f32_e32 v10, v140, v140
	v_fmac_f32_e32 v10, v141, v141
	v_fmac_f32_e32 v10, v142, v142
	v_fmac_f32_e32 v10, v143, v143
	v_mul_f32_e32 v11, v160, v160
	v_fmac_f32_e32 v11, v161, v161
	v_fmac_f32_e32 v11, v162, v162
	v_fmac_f32_e32 v11, v163, v163
	v_fmac_f32_e32 v11, v164, v164
	v_fmac_f32_e32 v11, v165, v165
	v_fmac_f32_e32 v11, v166, v166
	v_fmac_f32_e32 v11, v167, v167
	v_fmac_f32_e32 v11, v168, v168
	v_fmac_f32_e32 v11, v169, v169
	v_fmac_f32_e32 v11, v170, v170
	v_fmac_f32_e32 v11, v171, v171
	v_fmac_f32_e32 v11, v172, v172
	v_fmac_f32_e32 v11, v173, v173
	v_fmac_f32_e32 v11, v174, v174
	v_fmac_f32_e32 v11, v175, v175
	ds_bpermute_b32 v12, v4, v10
	ds_bpermute_b32 v13, v4, v11
	s_waitcnt lgkmcnt(0)
	v_add_f32_e32 v10, v10, v12
	v_add_f32_e32 v11, v11, v13
	ds_bpermute_b32 v12, v5, v10
	ds_bpermute_b32 v13, v5, v11
	s_waitcnt lgkmcnt(0)
	v_add_f32_e32 v10, v10, v12
	v_add_f32_e32 v11, v11, v13
	ds_bpermute_b32 v12, v6, v10
	ds_bpermute_b32 v13, v6, v11
	s_waitcnt lgkmcnt(0)
	v_add_f32_e32 v10, v10, v12
	v_add_f32_e32 v11, v11, v13
	ds_bpermute_b32 v12, v7, v10
	ds_bpermute_b32 v13, v7, v11
	s_waitcnt lgkmcnt(0)
	v_add_f32_e32 v10, v10, v12
	v_add_f32_e32 v11, v11, v13
	ds_bpermute_b32 v12, v8, v10
	ds_bpermute_b32 v13, v8, v11
	s_waitcnt lgkmcnt(0)
	v_add_f32_e32 v10, v10, v12
	v_add_f32_e32 v11, v11, v13
	ds_bpermute_b32 v12, v9, v10
	ds_bpermute_b32 v13, v9, v11
	s_waitcnt lgkmcnt(0)
	v_add_f32_e32 v10, v10, v12
	v_add_f32_e32 v11, v11, v13
	v_fma_f32 v14, v10, s17, v3
	v_fma_f32 v15, v11, s17, v3
	v_rsq_f32_e32 v14, v14
	v_rsq_f32_e32 v15, v15
	s_nop 0
	v_mul_f32_e32 v128, v128, v14
	v_mul_f32_e32 v129, v129, v14
	v_mul_f32_e32 v130, v130, v14
	v_mul_f32_e32 v131, v131, v14
	v_mul_f32_e32 v132, v132, v14
	v_mul_f32_e32 v133, v133, v14
	v_mul_f32_e32 v134, v134, v14
	v_mul_f32_e32 v135, v135, v14
	v_mul_f32_e32 v136, v136, v14
	v_mul_f32_e32 v137, v137, v14
	v_mul_f32_e32 v138, v138, v14
	v_mul_f32_e32 v139, v139, v14
	v_mul_f32_e32 v140, v140, v14
	v_mul_f32_e32 v141, v141, v14
	v_mul_f32_e32 v142, v142, v14
	v_mul_f32_e32 v143, v143, v14
	v_fmac_f32_e32 v144, v128, v20
	v_fmac_f32_e32 v145, v129, v21
	v_fmac_f32_e32 v146, v130, v22
	v_fmac_f32_e32 v147, v131, v23
	v_fmac_f32_e32 v148, v132, v24
	v_fmac_f32_e32 v149, v133, v25
	v_fmac_f32_e32 v150, v134, v26
	v_fmac_f32_e32 v151, v135, v27
	v_fmac_f32_e32 v152, v136, v28
	v_fmac_f32_e32 v153, v137, v29
	v_fmac_f32_e32 v154, v138, v30
	v_fmac_f32_e32 v155, v139, v31
	v_fmac_f32_e32 v156, v140, v32
	v_fmac_f32_e32 v157, v141, v33
	v_fmac_f32_e32 v158, v142, v34
	v_fmac_f32_e32 v159, v143, v35
	global_store_dwordx4 v1, v[144:147], s[40:41] offset:0 nt
	global_store_dwordx4 v1, v[148:151], s[40:41] offset:1024 nt
	global_store_dwordx4 v1, v[152:155], s[40:41] offset:2048 nt
	global_store_dwordx4 v1, v[156:159], s[40:41] offset:3072 nt
	v_mul_f32_e32 v160, v160, v15
	v_mul_f32_e32 v161, v161, v15
	v_mul_f32_e32 v162, v162, v15
	v_mul_f32_e32 v163, v163, v15
	v_mul_f32_e32 v164, v164, v15
	v_mul_f32_e32 v165, v165, v15
	v_mul_f32_e32 v166, v166, v15
	v_mul_f32_e32 v167, v167, v15
	v_mul_f32_e32 v168, v168, v15
	v_mul_f32_e32 v169, v169, v15
	v_mul_f32_e32 v170, v170, v15
	v_mul_f32_e32 v171, v171, v15
	v_mul_f32_e32 v172, v172, v15
	v_mul_f32_e32 v173, v173, v15
	v_mul_f32_e32 v174, v174, v15
	v_mul_f32_e32 v175, v175, v15
	v_fmac_f32_e32 v176, v160, v20
	v_fmac_f32_e32 v177, v161, v21
	v_fmac_f32_e32 v178, v162, v22
	v_fmac_f32_e32 v179, v163, v23
	v_fmac_f32_e32 v180, v164, v24
	v_fmac_f32_e32 v181, v165, v25
	v_fmac_f32_e32 v182, v166, v26
	v_fmac_f32_e32 v183, v167, v27
	v_fmac_f32_e32 v184, v168, v28
	v_fmac_f32_e32 v185, v169, v29
	v_fmac_f32_e32 v186, v170, v30
	v_fmac_f32_e32 v187, v171, v31
	v_fmac_f32_e32 v188, v172, v32
	v_fmac_f32_e32 v189, v173, v33
	v_fmac_f32_e32 v190, v174, v34
	v_fmac_f32_e32 v191, v175, v35
	global_store_dwordx4 v1, v[176:179], s[48:49] offset:0 nt
	global_store_dwordx4 v1, v[180:183], s[48:49] offset:1024 nt
	global_store_dwordx4 v1, v[184:187], s[48:49] offset:2048 nt
	global_store_dwordx4 v1, v[188:191], s[48:49] offset:3072 nt
	v_mul_f32_e32 v10, v144, v144
	v_fmac_f32_e32 v10, v145, v145
	v_fmac_f32_e32 v10, v146, v146
	v_fmac_f32_e32 v10, v147, v147
	v_fmac_f32_e32 v10, v148, v148
	v_fmac_f32_e32 v10, v149, v149
	v_fmac_f32_e32 v10, v150, v150
	v_fmac_f32_e32 v10, v151, v151
	v_fmac_f32_e32 v10, v152, v152
	v_fmac_f32_e32 v10, v153, v153
	v_fmac_f32_e32 v10, v154, v154
	v_fmac_f32_e32 v10, v155, v155
	v_fmac_f32_e32 v10, v156, v156
	v_fmac_f32_e32 v10, v157, v157
	v_fmac_f32_e32 v10, v158, v158
	v_fmac_f32_e32 v10, v159, v159
	v_mul_f32_e32 v11, v176, v176
	v_fmac_f32_e32 v11, v177, v177
	v_fmac_f32_e32 v11, v178, v178
	v_fmac_f32_e32 v11, v179, v179
	v_fmac_f32_e32 v11, v180, v180
	v_fmac_f32_e32 v11, v181, v181
	v_fmac_f32_e32 v11, v182, v182
	v_fmac_f32_e32 v11, v183, v183
	v_fmac_f32_e32 v11, v184, v184
	v_fmac_f32_e32 v11, v185, v185
	v_fmac_f32_e32 v11, v186, v186
	v_fmac_f32_e32 v11, v187, v187
	v_fmac_f32_e32 v11, v188, v188
	v_fmac_f32_e32 v11, v189, v189
	v_fmac_f32_e32 v11, v190, v190
	v_fmac_f32_e32 v11, v191, v191
	ds_bpermute_b32 v12, v4, v10
	ds_bpermute_b32 v13, v4, v11
	s_waitcnt lgkmcnt(0)
	v_add_f32_e32 v10, v10, v12
	v_add_f32_e32 v11, v11, v13
	ds_bpermute_b32 v12, v5, v10
	ds_bpermute_b32 v13, v5, v11
	s_waitcnt lgkmcnt(0)
	v_add_f32_e32 v10, v10, v12
	v_add_f32_e32 v11, v11, v13
	ds_bpermute_b32 v12, v6, v10
	ds_bpermute_b32 v13, v6, v11
	s_waitcnt lgkmcnt(0)
	v_add_f32_e32 v10, v10, v12
	v_add_f32_e32 v11, v11, v13
	ds_bpermute_b32 v12, v7, v10
	ds_bpermute_b32 v13, v7, v11
	s_waitcnt lgkmcnt(0)
	v_add_f32_e32 v10, v10, v12
	v_add_f32_e32 v11, v11, v13
	ds_bpermute_b32 v12, v8, v10
	ds_bpermute_b32 v13, v8, v11
	s_waitcnt lgkmcnt(0)
	v_add_f32_e32 v10, v10, v12
	v_add_f32_e32 v11, v11, v13
	ds_bpermute_b32 v12, v9, v10
	ds_bpermute_b32 v13, v9, v11
	s_waitcnt lgkmcnt(0)
	v_add_f32_e32 v10, v10, v12
	v_add_f32_e32 v11, v11, v13
	v_fma_f32 v14, v10, s17, v3
	v_fma_f32 v15, v11, s17, v3
	v_rsq_f32_e32 v14, v14
	v_rsq_f32_e32 v15, v15
	s_nop 0
	v_mul_f32_e32 v128, v144, v14
	v_mul_f32_e32 v129, v145, v14
	v_mul_f32_e32 v130, v146, v14
	v_mul_f32_e32 v131, v147, v14
	v_mul_f32_e32 v132, v148, v14
	v_mul_f32_e32 v133, v149, v14
	v_mul_f32_e32 v134, v150, v14
	v_mul_f32_e32 v135, v151, v14
	v_mul_f32_e32 v136, v152, v14
	v_mul_f32_e32 v137, v153, v14
	v_mul_f32_e32 v138, v154, v14
	v_mul_f32_e32 v139, v155, v14
	v_mul_f32_e32 v140, v156, v14
	v_mul_f32_e32 v141, v157, v14
	v_mul_f32_e32 v142, v158, v14
	v_mul_f32_e32 v143, v159, v14
	v_mul_f32_e32 v128, v128, v36
	v_mul_f32_e32 v129, v129, v37
	v_mul_f32_e32 v130, v130, v38
	v_mul_f32_e32 v131, v131, v39
	v_mul_f32_e32 v132, v132, v40
	v_mul_f32_e32 v133, v133, v41
	v_mul_f32_e32 v134, v134, v42
	v_mul_f32_e32 v135, v135, v43
	v_mul_f32_e32 v136, v136, v44
	v_mul_f32_e32 v137, v137, v45
	v_mul_f32_e32 v138, v138, v46
	v_mul_f32_e32 v139, v139, v47
	v_mul_f32_e32 v140, v140, v48
	v_mul_f32_e32 v141, v141, v49
	v_mul_f32_e32 v142, v142, v50
	v_mul_f32_e32 v143, v143, v51
	v_cvt_pk_bf16_f32 v128, v128, v129
	v_cvt_pk_bf16_f32 v129, v130, v131
	v_cvt_pk_bf16_f32 v132, v132, v133
	v_cvt_pk_bf16_f32 v133, v134, v135
	v_cvt_pk_bf16_f32 v136, v136, v137
	v_cvt_pk_bf16_f32 v137, v138, v139
	v_cvt_pk_bf16_f32 v140, v140, v141
	v_cvt_pk_bf16_f32 v141, v142, v143
	global_store_dwordx2 v2, v[128:129], s[42:43] offset:0
	global_store_dwordx2 v2, v[132:133], s[42:43] offset:512
	global_store_dwordx2 v2, v[136:137], s[42:43] offset:1024
	global_store_dwordx2 v2, v[140:141], s[42:43] offset:1536
	v_mul_f32_e32 v160, v176, v15
	v_mul_f32_e32 v161, v177, v15
	v_mul_f32_e32 v162, v178, v15
	v_mul_f32_e32 v163, v179, v15
	v_mul_f32_e32 v164, v180, v15
	v_mul_f32_e32 v165, v181, v15
	v_mul_f32_e32 v166, v182, v15
	v_mul_f32_e32 v167, v183, v15
	v_mul_f32_e32 v168, v184, v15
	v_mul_f32_e32 v169, v185, v15
	v_mul_f32_e32 v170, v186, v15
	v_mul_f32_e32 v171, v187, v15
	v_mul_f32_e32 v172, v188, v15
	v_mul_f32_e32 v173, v189, v15
	v_mul_f32_e32 v174, v190, v15
	v_mul_f32_e32 v175, v191, v15
	v_mul_f32_e32 v160, v160, v36
	v_mul_f32_e32 v161, v161, v37
	v_mul_f32_e32 v162, v162, v38
	v_mul_f32_e32 v163, v163, v39
	v_mul_f32_e32 v164, v164, v40
	v_mul_f32_e32 v165, v165, v41
	v_mul_f32_e32 v166, v166, v42
	v_mul_f32_e32 v167, v167, v43
	v_mul_f32_e32 v168, v168, v44
	v_mul_f32_e32 v169, v169, v45
	v_mul_f32_e32 v170, v170, v46
	v_mul_f32_e32 v171, v171, v47
	v_mul_f32_e32 v172, v172, v48
	v_mul_f32_e32 v173, v173, v49
	v_mul_f32_e32 v174, v174, v50
	v_mul_f32_e32 v175, v175, v51
	v_cvt_pk_bf16_f32 v160, v160, v161
	v_cvt_pk_bf16_f32 v161, v162, v163
	v_cvt_pk_bf16_f32 v164, v164, v165
	v_cvt_pk_bf16_f32 v165, v166, v167
	v_cvt_pk_bf16_f32 v168, v168, v169
	v_cvt_pk_bf16_f32 v169, v170, v171
	v_cvt_pk_bf16_f32 v172, v172, v173
	v_cvt_pk_bf16_f32 v173, v174, v175
	global_store_dwordx2 v2, v[160:161], s[50:51] offset:0
	global_store_dwordx2 v2, v[164:165], s[50:51] offset:512
	global_store_dwordx2 v2, v[168:169], s[50:51] offset:1024
	global_store_dwordx2 v2, v[172:173], s[50:51] offset:1536
	v_add_f32_e32 v208, v208, v212
	v_add_f32_e32 v209, v209, v213
	v_add_f32_e32 v210, v210, v214
	v_add_f32_e32 v211, v211, v215
	v_readfirstlane_b32 s18, v0
	s_lshr_b32 s18, s18, 6
	s_lshl_b32 s19, s18, 2
	s_and_b32 s52, s18, 4
	s_lshl_b32 s52, s52, 2
	v_mov_b32_e32 v16, s19
	v_mov_b32_e32 v17, s52
	v_mul_f32_e32 v10, v208, v208
	v_fmac_f32_e32 v10, v209, v209
	v_fmac_f32_e32 v10, v210, v210
	v_fmac_f32_e32 v10, v211, v211
	ds_bpermute_b32 v11, v4, v10
	s_waitcnt lgkmcnt(0)
	v_add_f32_e32 v10, v10, v11
	ds_bpermute_b32 v11, v5, v10
	s_waitcnt lgkmcnt(0)
	v_add_f32_e32 v10, v10, v11
	ds_bpermute_b32 v11, v6, v10
	s_waitcnt lgkmcnt(0)
	v_add_f32_e32 v10, v10, v11
	ds_bpermute_b32 v11, v7, v10
	s_waitcnt lgkmcnt(0)
	v_add_f32_e32 v10, v10, v11
	ds_bpermute_b32 v11, v8, v10
	s_waitcnt lgkmcnt(0)
	v_add_f32_e32 v10, v10, v11
	ds_bpermute_b32 v11, v9, v10
	s_waitcnt lgkmcnt(0)
	v_add_f32_e32 v10, v10, v11
	ds_write_b32 v16, v10 offset:0
	s_waitcnt lgkmcnt(0)
	s_barrier
	ds_read_b128 v[12:15], v17 offset:0
	s_waitcnt lgkmcnt(0)
	v_add_f32_e32 v12, v12, v13
	v_add_f32_e32 v14, v14, v15
	v_add_f32_e32 v10, v12, v14
	v_fma_f32 v11, v10, s17, v3
	v_rsq_f32_e32 v11, v11
	s_nop 0
	v_mul_f32_e32 v208, v208, v11
	v_mul_f32_e32 v209, v209, v11
	v_mul_f32_e32 v210, v210, v11
	v_mul_f32_e32 v211, v211, v11
	v_fmac_f32_e32 v240, v208, v244
	v_fmac_f32_e32 v241, v209, v245
	v_fmac_f32_e32 v242, v210, v246
	v_fmac_f32_e32 v243, v211, v247
	s_lshl_b32 s18, s54, 12
	s_add_u32 s18, s18, s55
	s_add_u32 s56, s4, s18
	s_addc_u32 s57, s5, 0
	s_add_u32 s56, s56, 0x4000000
	s_addc_u32 s57, s57, 0
	global_store_dwordx4 v1, v[240:243], s[56:57]
	v_mul_f32_e32 v10, v240, v240
	v_fmac_f32_e32 v10, v241, v241
	v_fmac_f32_e32 v10, v242, v242
	v_fmac_f32_e32 v10, v243, v243
	ds_bpermute_b32 v11, v4, v10
	s_waitcnt lgkmcnt(0)
	v_add_f32_e32 v10, v10, v11
	ds_bpermute_b32 v11, v5, v10
	s_waitcnt lgkmcnt(0)
	v_add_f32_e32 v10, v10, v11
	ds_bpermute_b32 v11, v6, v10
	s_waitcnt lgkmcnt(0)
	v_add_f32_e32 v10, v10, v11
	ds_bpermute_b32 v11, v7, v10
	s_waitcnt lgkmcnt(0)
	v_add_f32_e32 v10, v10, v11
	ds_bpermute_b32 v11, v8, v10
	s_waitcnt lgkmcnt(0)
	v_add_f32_e32 v10, v10, v11
	ds_bpermute_b32 v11, v9, v10
	s_waitcnt lgkmcnt(0)
	v_add_f32_e32 v10, v10, v11
	ds_write_b32 v16, v10 offset:64
	s_waitcnt lgkmcnt(0)
	s_barrier
	ds_read_b128 v[12:15], v17 offset:64
	s_waitcnt lgkmcnt(0)
	v_add_f32_e32 v12, v12, v13
	v_add_f32_e32 v14, v14, v15
	v_add_f32_e32 v10, v12, v14
	v_fma_f32 v11, v10, s17, v3
	v_rsq_f32_e32 v11, v11
	s_nop 0
	v_mul_f32_e32 v208, v240, v11
	v_mul_f32_e32 v209, v241, v11
	v_mul_f32_e32 v210, v242, v11
	v_mul_f32_e32 v211, v243, v11
	v_mul_f32_e32 v208, v208, v248
	v_mul_f32_e32 v209, v209, v249
	v_mul_f32_e32 v210, v210, v250
	v_mul_f32_e32 v211, v211, v251
	v_cvt_pk_bf16_f32 v208, v208, v209
	v_cvt_pk_bf16_f32 v209, v210, v211
	s_lshl_b32 s18, s54, 11
	s_lshr_b32 s19, s55, 1
	s_add_u32 s18, s18, s19
	s_add_u32 s56, s6, s18
	s_addc_u32 s57, s7, 0
	s_add_u32 s56, s56, 0x5100000
	s_addc_u32 s57, s57, 0
	global_store_dwordx2 v2, v[208:209], s[56:57]

_Z10fwd_kernelILi7ELi8EEv4Args:
	s_load_dword s3, s[0:1], 0xe8
	s_load_dwordx4 s[4:7], s[0:1], 0xd0
	s_load_dwordx2 s[8:9], s[0:1], 0xb8
	s_load_dwordx2 s[10:11], s[0:1], 0xa0
	s_waitcnt lgkmcnt(0)
	s_cmp_lg_u32 s3, 0x100
	s_cbranch_scc1 .Lrows7_orig
	s_add_u32 s10, s10, 0x1000
	s_addc_u32 s11, s11, 0
	v_readfirstlane_b32 s16, v0
	s_lshr_b32 s16, s16, 6
	s_lshl_b32 s18, s2, 3
	s_add_u32 s16, s16, s18
	s_mov_b32 s17, 0x3a800000
	v_mov_b32_e32 v3, 0x358637bd
	v_and_b32_e32 v10, 63, v0
	v_lshlrev_b32_e32 v1, 4, v10
	v_lshlrev_b32_e32 v2, 3, v10
	v_xor_b32_e32 v4, 1, v10
	v_xor_b32_e32 v5, 2, v10
	v_xor_b32_e32 v6, 4, v10
	v_xor_b32_e32 v7, 8, v10
	v_xor_b32_e32 v8, 16, v10
	v_xor_b32_e32 v9, 32, v10
	v_lshlrev_b32_e32 v4, 2, v4
	v_lshlrev_b32_e32 v5, 2, v5
	v_lshlrev_b32_e32 v6, 2, v6
	v_lshlrev_b32_e32 v7, 2, v7
	v_lshlrev_b32_e32 v8, 2, v8
	v_lshlrev_b32_e32 v9, 2, v9
	global_load_dwordx4 v[20:23], v1, s[8:9] offset:0
	global_load_dwordx4 v[24:27], v1, s[8:9] offset:1024
	global_load_dwordx4 v[28:31], v1, s[8:9] offset:2048
	global_load_dwordx4 v[32:35], v1, s[8:9] offset:3072
	global_load_dwordx4 v[36:39], v1, s[10:11] offset:0
	global_load_dwordx4 v[40:43], v1, s[10:11] offset:1024
	global_load_dwordx4 v[44:47], v1, s[10:11] offset:2048
	global_load_dwordx4 v[48:51], v1, s[10:11] offset:3072
	s_lshr_b32 s54, s16, 2
	s_and_b32 s55, s16, 3
	s_lshl_b32 s55, s55, 10
	s_lshl_b32 s18, s54, 12
	s_add_u32 s18, s18, s55
	s_add_u32 s56, s6, s18
	s_addc_u32 s57, s7, 0
	s_add_u32 s56, s56, 0x100000
	s_addc_u32 s57, s57, 0
	global_load_dwordx4 v[208:211], v1, s[56:57]
	s_add_u32 s56, s56, 0x200000
	s_addc_u32 s57, s57, 0
	global_load_dwordx4 v[212:215], v1, s[56:57]
	s_add_u32 s56, s56, 0x200000
	s_addc_u32 s57, s57, 0
	global_load_dwordx4 v[216:219], v1, s[56:57]
	s_add_u32 s56, s56, 0x200000
	s_addc_u32 s57, s57, 0
	global_load_dwordx4 v[220:223], v1, s[56:57]
	s_add_u32 s56, s56, 0x200000
	s_addc_u32 s57, s57, 0
	global_load_dwordx4 v[224:227], v1, s[56:57]
	s_add_u32 s56, s56, 0x200000
	s_addc_u32 s57, s57, 0
	global_load_dwordx4 v[228:231], v1, s[56:57]
	s_add_u32 s56, s56, 0x200000
	s_addc_u32 s57, s57, 0
	global_load_dwordx4 v[232:235], v1, s[56:57]
	s_add_u32 s56, s56, 0x200000
	s_addc_u32 s57, s57, 0
	global_load_dwordx4 v[236:239], v1, s[56:57]
	s_add_u32 s56, s4, s18
	s_addc_u32 s57, s5, 0
	s_add_u32 s56, s56, 0x4000000
	s_addc_u32 s57, s57, 0
	global_load_dwordx4 v[240:243], v1, s[56:57]
	s_add_u32 s56, s8, s55
	s_addc_u32 s57, s9, 0
	global_load_dwordx4 v[244:247], v1, s[56:57]
	s_add_u32 s56, s10, s55
	s_addc_u32 s57, s11, 0
	global_load_dwordx4 v[248:251], v1, s[56:57]
	s_add_u32 s53, s16, 0x0
	s_lshl_b32 s18, s53, 12
	s_lshl_b32 s19, s53, 11
	s_add_u32 s20, s4, s18
	s_addc_u32 s21, s5, 0
	s_add_u32 s22, s6, s19
	s_addc_u32 s23, s7, 0
	s_add_u32 s22, s22, 0x5200000
	s_addc_u32 s23, s23, 0
	s_add_u32 s24, s4, s18
	s_addc_u32 s25, s5, 0
	s_add_u32 s26, s6, s19
	s_addc_u32 s27, s7, 0
	s_add_u32 s26, s26, 0x3100000
	s_addc_u32 s27, s27, 0
	global_load_dwordx2 v[66:67], v2, s[22:23] offset:0
	global_load_dwordx2 v[70:71], v2, s[22:23] offset:512
	global_load_dwordx2 v[74:75], v2, s[22:23] offset:1024
	global_load_dwordx2 v[78:79], v2, s[22:23] offset:1536
	global_load_dwordx4 v[80:83], v1, s[20:21] offset:0 nt
	global_load_dwordx4 v[84:87], v1, s[20:21] offset:1024 nt
	global_load_dwordx4 v[88:91], v1, s[20:21] offset:2048 nt
	global_load_dwordx4 v[92:95], v1, s[20:21] offset:3072 nt
	s_add_u32 s53, s16, 0x800
	s_lshl_b32 s18, s53, 12
	s_lshl_b32 s19, s53, 11
	s_add_u32 s28, s4, s18
	s_addc_u32 s29, s5, 0
	s_add_u32 s30, s6, s19
	s_addc_u32 s31, s7, 0
	s_add_u32 s30, s30, 0x5200000
	s_addc_u32 s31, s31, 0
	s_add_u32 s32, s4, s18
	s_addc_u32 s33, s5, 0
	s_add_u32 s34, s6, s19
	s_addc_u32 s35, s7, 0
	s_add_u32 s34, s34, 0x3100000
	s_addc_u32 s35, s35, 0
	global_load_dwordx2 v[98:99], v2, s[30:31] offset:0
	global_load_dwordx2 v[102:103], v2, s[30:31] offset:512
	global_load_dwordx2 v[106:107], v2, s[30:31] offset:1024
	global_load_dwordx2 v[110:111], v2, s[30:31] offset:1536
	global_load_dwordx4 v[112:115], v1, s[28:29] offset:0 nt
	global_load_dwordx4 v[116:119], v1, s[28:29] offset:1024 nt
	global_load_dwordx4 v[120:123], v1, s[28:29] offset:2048 nt
	global_load_dwordx4 v[124:127], v1, s[28:29] offset:3072 nt
	s_add_u32 s53, s16, 0x1000
	s_lshl_b32 s18, s53, 12
	s_lshl_b32 s19, s53, 11
	s_add_u32 s36, s4, s18
	s_addc_u32 s37, s5, 0
	s_add_u32 s38, s6, s19
	s_addc_u32 s39, s7, 0
	s_add_u32 s38, s38, 0x5200000
	s_addc_u32 s39, s39, 0
	s_add_u32 s40, s4, s18
	s_addc_u32 s41, s5, 0
	s_add_u32 s42, s6, s19
	s_addc_u32 s43, s7, 0
	s_add_u32 s42, s42, 0x3100000
	s_addc_u32 s43, s43, 0
	global_load_dwordx2 v[130:131], v2, s[38:39] offset:0
	global_load_dwordx2 v[134:135], v2, s[38:39] offset:512
	global_load_dwordx2 v[138:139], v2, s[38:39] offset:1024
	global_load_dwordx2 v[142:143], v2, s[38:39] offset:1536
	global_load_dwordx4 v[144:147], v1, s[36:37] offset:0 nt
	global_load_dwordx4 v[148:151], v1, s[36:37] offset:1024 nt
	global_load_dwordx4 v[152:155], v1, s[36:37] offset:2048 nt
	global_load_dwordx4 v[156:159], v1, s[36:37] offset:3072 nt
	s_add_u32 s53, s16, 0x1800
	s_lshl_b32 s18, s53, 12
	s_lshl_b32 s19, s53, 11
	s_add_u32 s44, s4, s18
	s_addc_u32 s45, s5, 0
	s_add_u32 s46, s6, s19
	s_addc_u32 s47, s7, 0
	s_add_u32 s46, s46, 0x5200000
	s_addc_u32 s47, s47, 0
	s_add_u32 s48, s4, s18
	s_addc_u32 s49, s5, 0
	s_add_u32 s50, s6, s19
	s_addc_u32 s51, s7, 0
	s_add_u32 s50, s50, 0x3100000
	s_addc_u32 s51, s51, 0
	global_load_dwordx2 v[162:163], v2, s[46:47] offset:0
	global_load_dwordx2 v[166:167], v2, s[46:47] offset:512
	global_load_dwordx2 v[170:171], v2, s[46:47] offset:1024
	global_load_dwordx2 v[174:175], v2, s[46:47] offset:1536
	global_load_dwordx4 v[176:179], v1, s[44:45] offset:0 nt
	global_load_dwordx4 v[180:183], v1, s[44:45] offset:1024 nt
	global_load_dwordx4 v[184:187], v1, s[44:45] offset:2048 nt
	global_load_dwordx4 v[188:191], v1, s[44:45] offset:3072 nt
	s_waitcnt vmcnt(16)
	v_lshlrev_b32_e32 v64, 16, v66
	v_and_b32_e32 v65, 0xffff0000, v66
	v_lshlrev_b32_e32 v66, 16, v67
	v_and_b32_e32 v67, 0xffff0000, v67
	v_lshlrev_b32_e32 v68, 16, v70
	v_and_b32_e32 v69, 0xffff0000, v70
	v_lshlrev_b32_e32 v70, 16, v71
	v_and_b32_e32 v71, 0xffff0000, v71
	v_lshlrev_b32_e32 v72, 16, v74
	v_and_b32_e32 v73, 0xffff0000, v74
	v_lshlrev_b32_e32 v74, 16, v75
	v_and_b32_e32 v75, 0xffff0000, v75
	v_lshlrev_b32_e32 v76, 16, v78
	v_and_b32_e32 v77, 0xffff0000, v78
	v_lshlrev_b32_e32 v78, 16, v79
	v_and_b32_e32 v79, 0xffff0000, v79
	v_lshlrev_b32_e32 v96, 16, v98
	v_and_b32_e32 v97, 0xffff0000, v98
	v_lshlrev_b32_e32 v98, 16, v99
	v_and_b32_e32 v99, 0xffff0000, v99
	v_lshlrev_b32_e32 v100, 16, v102
	v_and_b32_e32 v101, 0xffff0000, v102
	v_lshlrev_b32_e32 v102, 16, v103
	v_and_b32_e32 v103, 0xffff0000, v103
	v_lshlrev_b32_e32 v104, 16, v106
	v_and_b32_e32 v105, 0xffff0000, v106
	v_lshlrev_b32_e32 v106, 16, v107
	v_and_b32_e32 v107, 0xffff0000, v107
	v_lshlrev_b32_e32 v108, 16, v110
	v_and_b32_e32 v109, 0xffff0000, v110
	v_lshlrev_b32_e32 v110, 16, v111
	v_and_b32_e32 v111, 0xffff0000, v111
	v_mul_f32_e32 v10, v64, v64
	v_fmac_f32_e32 v10, v65, v65
	v_fmac_f32_e32 v10, v66, v66
	v_fmac_f32_e32 v10, v67, v67
	v_fmac_f32_e32 v10, v68, v68
	v_fmac_f32_e32 v10, v69, v69
	v_fmac_f32_e32 v10, v70, v70
	v_fmac_f32_e32 v10, v71, v71
	v_fmac_f32_e32 v10, v72, v72
	v_fmac_f32_e32 v10, v73, v73
	v_fmac_f32_e32 v10, v74, v74
	v_fmac_f32_e32 v10, v75, v75
	v_fmac_f32_e32 v10, v76, v76
	v_fmac_f32_e32 v10, v77, v77
	v_fmac_f32_e32 v10, v78, v78
	v_fmac_f32_e32 v10, v79, v79
	v_mul_f32_e32 v11, v96, v96
	v_fmac_f32_e32 v11, v97, v97
	v_fmac_f32_e32 v11, v98, v98
	v_fmac_f32_e32 v11, v99, v99
	v_fmac_f32_e32 v11, v100, v100
	v_fmac_f32_e32 v11, v101, v101
	v_fmac_f32_e32 v11, v102, v102
	v_fmac_f32_e32 v11, v103, v103
	v_fmac_f32_e32 v11, v104, v104
	v_fmac_f32_e32 v11, v105, v105
	v_fmac_f32_e32 v11, v106, v106
	v_fmac_f32_e32 v11, v107, v107
	v_fmac_f32_e32 v11, v108, v108
	v_fmac_f32_e32 v11, v109, v109
	v_fmac_f32_e32 v11, v110, v110
	v_fmac_f32_e32 v11, v111, v111
	ds_bpermute_b32 v12, v4, v10
	ds_bpermute_b32 v13, v4, v11
	s_waitcnt lgkmcnt(0)
	v_add_f32_e32 v10, v10, v12
	v_add_f32_e32 v11, v11, v13
	ds_bpermute_b32 v12, v5, v10
	ds_bpermute_b32 v13, v5, v11
	s_waitcnt lgkmcnt(0)
	v_add_f32_e32 v10, v10, v12
	v_add_f32_e32 v11, v11, v13
	ds_bpermute_b32 v12, v6, v10
	ds_bpermute_b32 v13, v6, v11
	s_waitcnt lgkmcnt(0)
	v_add_f32_e32 v10, v10, v12
	v_add_f32_e32 v11, v11, v13
	ds_bpermute_b32 v12, v7, v10
	ds_bpermute_b32 v13, v7, v11
	s_waitcnt lgkmcnt(0)
	v_add_f32_e32 v10, v10, v12
	v_add_f32_e32 v11, v11, v13
	ds_bpermute_b32 v12, v8, v10
	ds_bpermute_b32 v13, v8, v11
	s_waitcnt lgkmcnt(0)
	v_add_f32_e32 v10, v10, v12
	v_add_f32_e32 v11, v11, v13
	ds_bpermute_b32 v12, v9, v10
	ds_bpermute_b32 v13, v9, v11
	s_waitcnt lgkmcnt(0)
	v_add_f32_e32 v10, v10, v12
	v_add_f32_e32 v11, v11, v13
	v_fma_f32 v14, v10, s17, v3
	v_fma_f32 v15, v11, s17, v3
	v_rsq_f32_e32 v14, v14
	v_rsq_f32_e32 v15, v15
	s_nop 0
	v_mul_f32_e32 v64, v64, v14
	v_mul_f32_e32 v65, v65, v14
	v_mul_f32_e32 v66, v66, v14
	v_mul_f32_e32 v67, v67, v14
	v_mul_f32_e32 v68, v68, v14
	v_mul_f32_e32 v69, v69, v14
	v_mul_f32_e32 v70, v70, v14
	v_mul_f32_e32 v71, v71, v14
	v_mul_f32_e32 v72, v72, v14
	v_mul_f32_e32 v73, v73, v14
	v_mul_f32_e32 v74, v74, v14
	v_mul_f32_e32 v75, v75, v14
	v_mul_f32_e32 v76, v76, v14
	v_mul_f32_e32 v77, v77, v14
	v_mul_f32_e32 v78, v78, v14
	v_mul_f32_e32 v79, v79, v14
	v_fmac_f32_e32 v80, v64, v20
	v_fmac_f32_e32 v81, v65, v21
	v_fmac_f32_e32 v82, v66, v22
	v_fmac_f32_e32 v83, v67, v23
	v_fmac_f32_e32 v84, v68, v24
	v_fmac_f32_e32 v85, v69, v25
	v_fmac_f32_e32 v86, v70, v26
	v_fmac_f32_e32 v87, v71, v27
	v_fmac_f32_e32 v88, v72, v28
	v_fmac_f32_e32 v89, v73, v29
	v_fmac_f32_e32 v90, v74, v30
	v_fmac_f32_e32 v91, v75, v31
	v_fmac_f32_e32 v92, v76, v32
	v_fmac_f32_e32 v93, v77, v33
	v_fmac_f32_e32 v94, v78, v34
	v_fmac_f32_e32 v95, v79, v35
	global_store_dwordx4 v1, v[80:83], s[24:25] offset:0 nt
	global_store_dwordx4 v1, v[84:87], s[24:25] offset:1024 nt
	global_store_dwordx4 v1, v[88:91], s[24:25] offset:2048 nt
	global_store_dwordx4 v1, v[92:95], s[24:25] offset:3072 nt
	v_mul_f32_e32 v96, v96, v15
	v_mul_f32_e32 v97, v97, v15
	v_mul_f32_e32 v98, v98, v15
	v_mul_f32_e32 v99, v99, v15
	v_mul_f32_e32 v100, v100, v15
	v_mul_f32_e32 v101, v101, v15
	v_mul_f32_e32 v102, v102, v15
	v_mul_f32_e32 v103, v103, v15
	v_mul_f32_e32 v104, v104, v15
	v_mul_f32_e32 v105, v105, v15
	v_mul_f32_e32 v106, v106, v15
	v_mul_f32_e32 v107, v107, v15
	v_mul_f32_e32 v108, v108, v15
	v_mul_f32_e32 v109, v109, v15
	v_mul_f32_e32 v110, v110, v15
	v_mul_f32_e32 v111, v111, v15
	v_fmac_f32_e32 v112, v96, v20
	v_fmac_f32_e32 v113, v97, v21
	v_fmac_f32_e32 v114, v98, v22
	v_fmac_f32_e32 v115, v99, v23
	v_fmac_f32_e32 v116, v100, v24
	v_fmac_f32_e32 v117, v101, v25
	v_fmac_f32_e32 v118, v102, v26
	v_fmac_f32_e32 v119, v103, v27
	v_fmac_f32_e32 v120, v104, v28
	v_fmac_f32_e32 v121, v105, v29
	v_fmac_f32_e32 v122, v106, v30
	v_fmac_f32_e32 v123, v107, v31
	v_fmac_f32_e32 v124, v108, v32
	v_fmac_f32_e32 v125, v109, v33
	v_fmac_f32_e32 v126, v110, v34
	v_fmac_f32_e32 v127, v111, v35
	global_store_dwordx4 v1, v[112:115], s[32:33] offset:0 nt
	global_store_dwordx4 v1, v[116:119], s[32:33] offset:1024 nt
	global_store_dwordx4 v1, v[120:123], s[32:33] offset:2048 nt
	global_store_dwordx4 v1, v[124:127], s[32:33] offset:3072 nt
	v_mul_f32_e32 v10, v80, v80
	v_fmac_f32_e32 v10, v81, v81
	v_fmac_f32_e32 v10, v82, v82
	v_fmac_f32_e32 v10, v83, v83
	v_fmac_f32_e32 v10, v84, v84
	v_fmac_f32_e32 v10, v85, v85
	v_fmac_f32_e32 v10, v86, v86
	v_fmac_f32_e32 v10, v87, v87
	v_fmac_f32_e32 v10, v88, v88
	v_fmac_f32_e32 v10, v89, v89
	v_fmac_f32_e32 v10, v90, v90
	v_fmac_f32_e32 v10, v91, v91
	v_fmac_f32_e32 v10, v92, v92
	v_fmac_f32_e32 v10, v93, v93
	v_fmac_f32_e32 v10, v94, v94
	v_fmac_f32_e32 v10, v95, v95
	v_mul_f32_e32 v11, v112, v112
	v_fmac_f32_e32 v11, v113, v113
	v_fmac_f32_e32 v11, v114, v114
	v_fmac_f32_e32 v11, v115, v115
	v_fmac_f32_e32 v11, v116, v116
	v_fmac_f32_e32 v11, v117, v117
	v_fmac_f32_e32 v11, v118, v118
	v_fmac_f32_e32 v11, v119, v119
	v_fmac_f32_e32 v11, v120, v120
	v_fmac_f32_e32 v11, v121, v121
	v_fmac_f32_e32 v11, v122, v122
	v_fmac_f32_e32 v11, v123, v123
	v_fmac_f32_e32 v11, v124, v124
	v_fmac_f32_e32 v11, v125, v125
	v_fmac_f32_e32 v11, v126, v126
	v_fmac_f32_e32 v11, v127, v127
	ds_bpermute_b32 v12, v4, v10
	ds_bpermute_b32 v13, v4, v11
	s_waitcnt lgkmcnt(0)
	v_add_f32_e32 v10, v10, v12
	v_add_f32_e32 v11, v11, v13
	ds_bpermute_b32 v12, v5, v10
	ds_bpermute_b32 v13, v5, v11
	s_waitcnt lgkmcnt(0)
	v_add_f32_e32 v10, v10, v12
	v_add_f32_e32 v11, v11, v13
	ds_bpermute_b32 v12, v6, v10
	ds_bpermute_b32 v13, v6, v11
	s_waitcnt lgkmcnt(0)
	v_add_f32_e32 v10, v10, v12
	v_add_f32_e32 v11, v11, v13
	ds_bpermute_b32 v12, v7, v10
	ds_bpermute_b32 v13, v7, v11
	s_waitcnt lgkmcnt(0)
	v_add_f32_e32 v10, v10, v12
	v_add_f32_e32 v11, v11, v13
	ds_bpermute_b32 v12, v8, v10
	ds_bpermute_b32 v13, v8, v11
	s_waitcnt lgkmcnt(0)
	v_add_f32_e32 v10, v10, v12
	v_add_f32_e32 v11, v11, v13
	ds_bpermute_b32 v12, v9, v10
	ds_bpermute_b32 v13, v9, v11
	s_waitcnt lgkmcnt(0)
	v_add_f32_e32 v10, v10, v12
	v_add_f32_e32 v11, v11, v13
	v_fma_f32 v14, v10, s17, v3
	v_fma_f32 v15, v11, s17, v3
	v_rsq_f32_e32 v14, v14
	v_rsq_f32_e32 v15, v15
	s_nop 0
	v_mul_f32_e32 v64, v80, v14
	v_mul_f32_e32 v65, v81, v14
	v_mul_f32_e32 v66, v82, v14
	v_mul_f32_e32 v67, v83, v14
	v_mul_f32_e32 v68, v84, v14
	v_mul_f32_e32 v69, v85, v14
	v_mul_f32_e32 v70, v86, v14
	v_mul_f32_e32 v71, v87, v14
	v_mul_f32_e32 v72, v88, v14
	v_mul_f32_e32 v73, v89, v14
	v_mul_f32_e32 v74, v90, v14
	v_mul_f32_e32 v75, v91, v14
	v_mul_f32_e32 v76, v92, v14
	v_mul_f32_e32 v77, v93, v14
	v_mul_f32_e32 v78, v94, v14
	v_mul_f32_e32 v79, v95, v14
	v_mul_f32_e32 v64, v64, v36
	v_mul_f32_e32 v65, v65, v37
	v_mul_f32_e32 v66, v66, v38
	v_mul_f32_e32 v67, v67, v39
	v_mul_f32_e32 v68, v68, v40
	v_mul_f32_e32 v69, v69, v41
	v_mul_f32_e32 v70, v70, v42
	v_mul_f32_e32 v71, v71, v43
	v_mul_f32_e32 v72, v72, v44
	v_mul_f32_e32 v73, v73, v45
	v_mul_f32_e32 v74, v74, v46
	v_mul_f32_e32 v75, v75, v47
	v_mul_f32_e32 v76, v76, v48
	v_mul_f32_e32 v77, v77, v49
	v_mul_f32_e32 v78, v78, v50
	v_mul_f32_e32 v79, v79, v51
	v_cvt_pk_bf16_f32 v64, v64, v65
	v_cvt_pk_bf16_f32 v65, v66, v67
	v_cvt_pk_bf16_f32 v68, v68, v69
	v_cvt_pk_bf16_f32 v69, v70, v71
	v_cvt_pk_bf16_f32 v72, v72, v73
	v_cvt_pk_bf16_f32 v73, v74, v75
	v_cvt_pk_bf16_f32 v76, v76, v77
	v_cvt_pk_bf16_f32 v77, v78, v79
	global_store_dwordx2 v2, v[64:65], s[26:27] offset:0
	global_store_dwordx2 v2, v[68:69], s[26:27] offset:512
	global_store_dwordx2 v2, v[72:73], s[26:27] offset:1024
	global_store_dwordx2 v2, v[76:77], s[26:27] offset:1536
	v_mul_f32_e32 v96, v112, v15
	v_mul_f32_e32 v97, v113, v15
	v_mul_f32_e32 v98, v114, v15
	v_mul_f32_e32 v99, v115, v15
	v_mul_f32_e32 v100, v116, v15
	v_mul_f32_e32 v101, v117, v15
	v_mul_f32_e32 v102, v118, v15
	v_mul_f32_e32 v103, v119, v15
	v_mul_f32_e32 v104, v120, v15
	v_mul_f32_e32 v105, v121, v15
	v_mul_f32_e32 v106, v122, v15
	v_mul_f32_e32 v107, v123, v15
	v_mul_f32_e32 v108, v124, v15
	v_mul_f32_e32 v109, v125, v15
	v_mul_f32_e32 v110, v126, v15
	v_mul_f32_e32 v111, v127, v15
	v_mul_f32_e32 v96, v96, v36
	v_mul_f32_e32 v97, v97, v37
	v_mul_f32_e32 v98, v98, v38
	v_mul_f32_e32 v99, v99, v39
	v_mul_f32_e32 v100, v100, v40
	v_mul_f32_e32 v101, v101, v41
	v_mul_f32_e32 v102, v102, v42
	v_mul_f32_e32 v103, v103, v43
	v_mul_f32_e32 v104, v104, v44
	v_mul_f32_e32 v105, v105, v45
	v_mul_f32_e32 v106, v106, v46
	v_mul_f32_e32 v107, v107, v47
	v_mul_f32_e32 v108, v108, v48
	v_mul_f32_e32 v109, v109, v49
	v_mul_f32_e32 v110, v110, v50
	v_mul_f32_e32 v111, v111, v51
	v_cvt_pk_bf16_f32 v96, v96, v97
	v_cvt_pk_bf16_f32 v97, v98, v99
	v_cvt_pk_bf16_f32 v100, v100, v101
	v_cvt_pk_bf16_f32 v101, v102, v103
	v_cvt_pk_bf16_f32 v104, v104, v105
	v_cvt_pk_bf16_f32 v105, v106, v107
	v_cvt_pk_bf16_f32 v108, v108, v109
	v_cvt_pk_bf16_f32 v109, v110, v111
	global_store_dwordx2 v2, v[96:97], s[34:35] offset:0
	global_store_dwordx2 v2, v[100:101], s[34:35] offset:512
	global_store_dwordx2 v2, v[104:105], s[34:35] offset:1024
	global_store_dwordx2 v2, v[108:109], s[34:35] offset:1536
	s_add_u32 s53, s16, 0x2000
	s_lshl_b32 s18, s53, 12
	s_lshl_b32 s19, s53, 11
	s_add_u32 s20, s4, s18
	s_addc_u32 s21, s5, 0
	s_add_u32 s22, s6, s19
	s_addc_u32 s23, s7, 0
	s_add_u32 s22, s22, 0x5200000
	s_addc_u32 s23, s23, 0
	s_add_u32 s24, s4, s18
	s_addc_u32 s25, s5, 0
	s_add_u32 s26, s6, s19
	s_addc_u32 s27, s7, 0
	s_add_u32 s26, s26, 0x3100000
	s_addc_u32 s27, s27, 0
	global_load_dwordx2 v[66:67], v2, s[22:23] offset:0
	global_load_dwordx2 v[70:71], v2, s[22:23] offset:512
	global_load_dwordx2 v[74:75], v2, s[22:23] offset:1024
	global_load_dwordx2 v[78:79], v2, s[22:23] offset:1536
	global_load_dwordx4 v[80:83], v1, s[20:21] offset:0 nt
	global_load_dwordx4 v[84:87], v1, s[20:21] offset:1024 nt
	global_load_dwordx4 v[88:91], v1, s[20:21] offset:2048 nt
	global_load_dwordx4 v[92:95], v1, s[20:21] offset:3072 nt
	s_add_u32 s53, s16, 0x2800
	s_lshl_b32 s18, s53, 12
	s_lshl_b32 s19, s53, 11
	s_add_u32 s28, s4, s18
	s_addc_u32 s29, s5, 0
	s_add_u32 s30, s6, s19
	s_addc_u32 s31, s7, 0
	s_add_u32 s30, s30, 0x5200000
	s_addc_u32 s31, s31, 0
	s_add_u32 s32, s4, s18
	s_addc_u32 s33, s5, 0
	s_add_u32 s34, s6, s19
	s_addc_u32 s35, s7, 0
	s_add_u32 s34, s34, 0x3100000
	s_addc_u32 s35, s35, 0
	global_load_dwordx2 v[98:99], v2, s[30:31] offset:0
	global_load_dwordx2 v[102:103], v2, s[30:31] offset:512
	global_load_dwordx2 v[106:107], v2, s[30:31] offset:1024
	global_load_dwordx2 v[110:111], v2, s[30:31] offset:1536
	global_load_dwordx4 v[112:115], v1, s[28:29] offset:0 nt
	global_load_dwordx4 v[116:119], v1, s[28:29] offset:1024 nt
	global_load_dwordx4 v[120:123], v1, s[28:29] offset:2048 nt
	global_load_dwordx4 v[124:127], v1, s[28:29] offset:3072 nt
	s_waitcnt vmcnt(32)
	v_lshlrev_b32_e32 v128, 16, v130
	v_and_b32_e32 v129, 0xffff0000, v130
	v_lshlrev_b32_e32 v130, 16, v131
	v_and_b32_e32 v131, 0xffff0000, v131
	v_lshlrev_b32_e32 v132, 16, v134
	v_and_b32_e32 v133, 0xffff0000, v134
	v_lshlrev_b32_e32 v134, 16, v135
	v_and_b32_e32 v135, 0xffff0000, v135
	v_lshlrev_b32_e32 v136, 16, v138
	v_and_b32_e32 v137, 0xffff0000, v138
	v_lshlrev_b32_e32 v138, 16, v139
	v_and_b32_e32 v139, 0xffff0000, v139
	v_lshlrev_b32_e32 v140, 16, v142
	v_and_b32_e32 v141, 0xffff0000, v142
	v_lshlrev_b32_e32 v142, 16, v143
	v_and_b32_e32 v143, 0xffff0000, v143
	v_lshlrev_b32_e32 v160, 16, v162
	v_and_b32_e32 v161, 0xffff0000, v162
	v_lshlrev_b32_e32 v162, 16, v163
	v_and_b32_e32 v163, 0xffff0000, v163
	v_lshlrev_b32_e32 v164, 16, v166
	v_and_b32_e32 v165, 0xffff0000, v166
	v_lshlrev_b32_e32 v166, 16, v167
	v_and_b32_e32 v167, 0xffff0000, v167
	v_lshlrev_b32_e32 v168, 16, v170
	v_and_b32_e32 v169, 0xffff0000, v170
	v_lshlrev_b32_e32 v170, 16, v171
	v_and_b32_e32 v171, 0xffff0000, v171
	v_lshlrev_b32_e32 v172, 16, v174
	v_and_b32_e32 v173, 0xffff0000, v174
	v_lshlrev_b32_e32 v174, 16, v175
	v_and_b32_e32 v175, 0xffff0000, v175
	v_mul_f32_e32 v10, v128, v128
	v_fmac_f32_e32 v10, v129, v129
	v_fmac_f32_e32 v10, v130, v130
	v_fmac_f32_e32 v10, v131, v131
	v_fmac_f32_e32 v10, v132, v132
	v_fmac_f32_e32 v10, v133, v133
	v_fmac_f32_e32 v10, v134, v134
	v_fmac_f32_e32 v10, v135, v135
	v_fmac_f32_e32 v10, v136, v136
	v_fmac_f32_e32 v10, v137, v137
	v_fmac_f32_e32 v10, v138, v138
	v_fmac_f32_e32 v10, v139, v139
	v_fmac_f32_e32 v10, v140, v140
	v_fmac_f32_e32 v10, v141, v141
	v_fmac_f32_e32 v10, v142, v142
	v_fmac_f32_e32 v10, v143, v143
	v_mul_f32_e32 v11, v160, v160
	v_fmac_f32_e32 v11, v161, v161
	v_fmac_f32_e32 v11, v162, v162
	v_fmac_f32_e32 v11, v163, v163
	v_fmac_f32_e32 v11, v164, v164
	v_fmac_f32_e32 v11, v165, v165
	v_fmac_f32_e32 v11, v166, v166
	v_fmac_f32_e32 v11, v167, v167
	v_fmac_f32_e32 v11, v168, v168
	v_fmac_f32_e32 v11, v169, v169
	v_fmac_f32_e32 v11, v170, v170
	v_fmac_f32_e32 v11, v171, v171
	v_fmac_f32_e32 v11, v172, v172
	v_fmac_f32_e32 v11, v173, v173
	v_fmac_f32_e32 v11, v174, v174
	v_fmac_f32_e32 v11, v175, v175
	ds_bpermute_b32 v12, v4, v10
	ds_bpermute_b32 v13, v4, v11
	s_waitcnt lgkmcnt(0)
	v_add_f32_e32 v10, v10, v12
	v_add_f32_e32 v11, v11, v13
	ds_bpermute_b32 v12, v5, v10
	ds_bpermute_b32 v13, v5, v11
	s_waitcnt lgkmcnt(0)
	v_add_f32_e32 v10, v10, v12
	v_add_f32_e32 v11, v11, v13
	ds_bpermute_b32 v12, v6, v10
	ds_bpermute_b32 v13, v6, v11
	s_waitcnt lgkmcnt(0)
	v_add_f32_e32 v10, v10, v12
	v_add_f32_e32 v11, v11, v13
	ds_bpermute_b32 v12, v7, v10
	ds_bpermute_b32 v13, v7, v11
	s_waitcnt lgkmcnt(0)
	v_add_f32_e32 v10, v10, v12
	v_add_f32_e32 v11, v11, v13
	ds_bpermute_b32 v12, v8, v10
	ds_bpermute_b32 v13, v8, v11
	s_waitcnt lgkmcnt(0)
	v_add_f32_e32 v10, v10, v12
	v_add_f32_e32 v11, v11, v13
	ds_bpermute_b32 v12, v9, v10
	ds_bpermute_b32 v13, v9, v11
	s_waitcnt lgkmcnt(0)
	v_add_f32_e32 v10, v10, v12
	v_add_f32_e32 v11, v11, v13
	v_fma_f32 v14, v10, s17, v3
	v_fma_f32 v15, v11, s17, v3
	v_rsq_f32_e32 v14, v14
	v_rsq_f32_e32 v15, v15
	s_nop 0
	v_mul_f32_e32 v128, v128, v14
	v_mul_f32_e32 v129, v129, v14
	v_mul_f32_e32 v130, v130, v14
	v_mul_f32_e32 v131, v131, v14
	v_mul_f32_e32 v132, v132, v14
	v_mul_f32_e32 v133, v133, v14
	v_mul_f32_e32 v134, v134, v14
	v_mul_f32_e32 v135, v135, v14
	v_mul_f32_e32 v136, v136, v14
	v_mul_f32_e32 v137, v137, v14
	v_mul_f32_e32 v138, v138, v14
	v_mul_f32_e32 v139, v139, v14
	v_mul_f32_e32 v140, v140, v14
	v_mul_f32_e32 v141, v141, v14
	v_mul_f32_e32 v142, v142, v14
	v_mul_f32_e32 v143, v143, v14
	v_fmac_f32_e32 v144, v128, v20
	v_fmac_f32_e32 v145, v129, v21
	v_fmac_f32_e32 v146, v130, v22
	v_fmac_f32_e32 v147, v131, v23
	v_fmac_f32_e32 v148, v132, v24
	v_fmac_f32_e32 v149, v133, v25
	v_fmac_f32_e32 v150, v134, v26
	v_fmac_f32_e32 v151, v135, v27
	v_fmac_f32_e32 v152, v136, v28
	v_fmac_f32_e32 v153, v137, v29
	v_fmac_f32_e32 v154, v138, v30
	v_fmac_f32_e32 v155, v139, v31
	v_fmac_f32_e32 v156, v140, v32
	v_fmac_f32_e32 v157, v141, v33
	v_fmac_f32_e32 v158, v142, v34
	v_fmac_f32_e32 v159, v143, v35
	global_store_dwordx4 v1, v[144:147], s[40:41] offset:0 nt
	global_store_dwordx4 v1, v[148:151], s[40:41] offset:1024 nt
	global_store_dwordx4 v1, v[152:155], s[40:41] offset:2048 nt
	global_store_dwordx4 v1, v[156:159], s[40:41] offset:3072 nt
	v_mul_f32_e32 v160, v160, v15
	v_mul_f32_e32 v161, v161, v15
	v_mul_f32_e32 v162, v162, v15
	v_mul_f32_e32 v163, v163, v15
	v_mul_f32_e32 v164, v164, v15
	v_mul_f32_e32 v165, v165, v15
	v_mul_f32_e32 v166, v166, v15
	v_mul_f32_e32 v167, v167, v15
	v_mul_f32_e32 v168, v168, v15
	v_mul_f32_e32 v169, v169, v15
	v_mul_f32_e32 v170, v170, v15
	v_mul_f32_e32 v171, v171, v15
	v_mul_f32_e32 v172, v172, v15
	v_mul_f32_e32 v173, v173, v15
	v_mul_f32_e32 v174, v174, v15
	v_mul_f32_e32 v175, v175, v15
	v_fmac_f32_e32 v176, v160, v20
	v_fmac_f32_e32 v177, v161, v21
	v_fmac_f32_e32 v178, v162, v22
	v_fmac_f32_e32 v179, v163, v23
	v_fmac_f32_e32 v180, v164, v24
	v_fmac_f32_e32 v181, v165, v25
	v_fmac_f32_e32 v182, v166, v26
	v_fmac_f32_e32 v183, v167, v27
	v_fmac_f32_e32 v184, v168, v28
	v_fmac_f32_e32 v185, v169, v29
	v_fmac_f32_e32 v186, v170, v30
	v_fmac_f32_e32 v187, v171, v31
	v_fmac_f32_e32 v188, v172, v32
	v_fmac_f32_e32 v189, v173, v33
	v_fmac_f32_e32 v190, v174, v34
	v_fmac_f32_e32 v191, v175, v35
	global_store_dwordx4 v1, v[176:179], s[48:49] offset:0 nt
	global_store_dwordx4 v1, v[180:183], s[48:49] offset:1024 nt
	global_store_dwordx4 v1, v[184:187], s[48:49] offset:2048 nt
	global_store_dwordx4 v1, v[188:191], s[48:49] offset:3072 nt
	v_mul_f32_e32 v10, v144, v144
	v_fmac_f32_e32 v10, v145, v145
	v_fmac_f32_e32 v10, v146, v146
	v_fmac_f32_e32 v10, v147, v147
	v_fmac_f32_e32 v10, v148, v148
	v_fmac_f32_e32 v10, v149, v149
	v_fmac_f32_e32 v10, v150, v150
	v_fmac_f32_e32 v10, v151, v151
	v_fmac_f32_e32 v10, v152, v152
	v_fmac_f32_e32 v10, v153, v153
	v_fmac_f32_e32 v10, v154, v154
	v_fmac_f32_e32 v10, v155, v155
	v_fmac_f32_e32 v10, v156, v156
	v_fmac_f32_e32 v10, v157, v157
	v_fmac_f32_e32 v10, v158, v158
	v_fmac_f32_e32 v10, v159, v159
	v_mul_f32_e32 v11, v176, v176
	v_fmac_f32_e32 v11, v177, v177
	v_fmac_f32_e32 v11, v178, v178
	v_fmac_f32_e32 v11, v179, v179
	v_fmac_f32_e32 v11, v180, v180
	v_fmac_f32_e32 v11, v181, v181
	v_fmac_f32_e32 v11, v182, v182
	v_fmac_f32_e32 v11, v183, v183
	v_fmac_f32_e32 v11, v184, v184
	v_fmac_f32_e32 v11, v185, v185
	v_fmac_f32_e32 v11, v186, v186
	v_fmac_f32_e32 v11, v187, v187
	v_fmac_f32_e32 v11, v188, v188
	v_fmac_f32_e32 v11, v189, v189
	v_fmac_f32_e32 v11, v190, v190
	v_fmac_f32_e32 v11, v191, v191
	ds_bpermute_b32 v12, v4, v10
	ds_bpermute_b32 v13, v4, v11
	s_waitcnt lgkmcnt(0)
	v_add_f32_e32 v10, v10, v12
	v_add_f32_e32 v11, v11, v13
	ds_bpermute_b32 v12, v5, v10
	ds_bpermute_b32 v13, v5, v11
	s_waitcnt lgkmcnt(0)
	v_add_f32_e32 v10, v10, v12
	v_add_f32_e32 v11, v11, v13
	ds_bpermute_b32 v12, v6, v10
	ds_bpermute_b32 v13, v6, v11
	s_waitcnt lgkmcnt(0)
	v_add_f32_e32 v10, v10, v12
	v_add_f32_e32 v11, v11, v13
	ds_bpermute_b32 v12, v7, v10
	ds_bpermute_b32 v13, v7, v11
	s_waitcnt lgkmcnt(0)
	v_add_f32_e32 v10, v10, v12
	v_add_f32_e32 v11, v11, v13
	ds_bpermute_b32 v12, v8, v10
	ds_bpermute_b32 v13, v8, v11
	s_waitcnt lgkmcnt(0)
	v_add_f32_e32 v10, v10, v12
	v_add_f32_e32 v11, v11, v13
	ds_bpermute_b32 v12, v9, v10
	ds_bpermute_b32 v13, v9, v11
	s_waitcnt lgkmcnt(0)
	v_add_f32_e32 v10, v10, v12
	v_add_f32_e32 v11, v11, v13
	v_fma_f32 v14, v10, s17, v3
	v_fma_f32 v15, v11, s17, v3
	v_rsq_f32_e32 v14, v14
	v_rsq_f32_e32 v15, v15
	s_nop 0
	v_mul_f32_e32 v128, v144, v14
	v_mul_f32_e32 v129, v145, v14
	v_mul_f32_e32 v130, v146, v14
	v_mul_f32_e32 v131, v147, v14
	v_mul_f32_e32 v132, v148, v14
	v_mul_f32_e32 v133, v149, v14
	v_mul_f32_e32 v134, v150, v14
	v_mul_f32_e32 v135, v151, v14
	v_mul_f32_e32 v136, v152, v14
	v_mul_f32_e32 v137, v153, v14
	v_mul_f32_e32 v138, v154, v14
	v_mul_f32_e32 v139, v155, v14
	v_mul_f32_e32 v140, v156, v14
	v_mul_f32_e32 v141, v157, v14
	v_mul_f32_e32 v142, v158, v14
	v_mul_f32_e32 v143, v159, v14
	v_mul_f32_e32 v128, v128, v36
	v_mul_f32_e32 v129, v129, v37
	v_mul_f32_e32 v130, v130, v38
	v_mul_f32_e32 v131, v131, v39
	v_mul_f32_e32 v132, v132, v40
	v_mul_f32_e32 v133, v133, v41
	v_mul_f32_e32 v134, v134, v42
	v_mul_f32_e32 v135, v135, v43
	v_mul_f32_e32 v136, v136, v44
	v_mul_f32_e32 v137, v137, v45
	v_mul_f32_e32 v138, v138, v46
	v_mul_f32_e32 v139, v139, v47
	v_mul_f32_e32 v140, v140, v48
	v_mul_f32_e32 v141, v141, v49
	v_mul_f32_e32 v142, v142, v50
	v_mul_f32_e32 v143, v143, v51
	v_cvt_pk_bf16_f32 v128, v128, v129
	v_cvt_pk_bf16_f32 v129, v130, v131
	v_cvt_pk_bf16_f32 v132, v132, v133
	v_cvt_pk_bf16_f32 v133, v134, v135
	v_cvt_pk_bf16_f32 v136, v136, v137
	v_cvt_pk_bf16_f32 v137, v138, v139
	v_cvt_pk_bf16_f32 v140, v140, v141
	v_cvt_pk_bf16_f32 v141, v142, v143
	global_store_dwordx2 v2, v[128:129], s[42:43] offset:0
	global_store_dwordx2 v2, v[132:133], s[42:43] offset:512
	global_store_dwordx2 v2, v[136:137], s[42:43] offset:1024
	global_store_dwordx2 v2, v[140:141], s[42:43] offset:1536
	v_mul_f32_e32 v160, v176, v15
	v_mul_f32_e32 v161, v177, v15
	v_mul_f32_e32 v162, v178, v15
	v_mul_f32_e32 v163, v179, v15
	v_mul_f32_e32 v164, v180, v15
	v_mul_f32_e32 v165, v181, v15
	v_mul_f32_e32 v166, v182, v15
	v_mul_f32_e32 v167, v183, v15
	v_mul_f32_e32 v168, v184, v15
	v_mul_f32_e32 v169, v185, v15
	v_mul_f32_e32 v170, v186, v15
	v_mul_f32_e32 v171, v187, v15
	v_mul_f32_e32 v172, v188, v15
	v_mul_f32_e32 v173, v189, v15
	v_mul_f32_e32 v174, v190, v15
	v_mul_f32_e32 v175, v191, v15
	v_mul_f32_e32 v160, v160, v36
	v_mul_f32_e32 v161, v161, v37
	v_mul_f32_e32 v162, v162, v38
	v_mul_f32_e32 v163, v163, v39
	v_mul_f32_e32 v164, v164, v40
	v_mul_f32_e32 v165, v165, v41
	v_mul_f32_e32 v166, v166, v42
	v_mul_f32_e32 v167, v167, v43
	v_mul_f32_e32 v168, v168, v44
	v_mul_f32_e32 v169, v169, v45
	v_mul_f32_e32 v170, v170, v46
	v_mul_f32_e32 v171, v171, v47
	v_mul_f32_e32 v172, v172, v48
	v_mul_f32_e32 v173, v173, v49
	v_mul_f32_e32 v174, v174, v50
	v_mul_f32_e32 v175, v175, v51
	v_cvt_pk_bf16_f32 v160, v160, v161
	v_cvt_pk_bf16_f32 v161, v162, v163
	v_cvt_pk_bf16_f32 v164, v164, v165
	v_cvt_pk_bf16_f32 v165, v166, v167
	v_cvt_pk_bf16_f32 v168, v168, v169
	v_cvt_pk_bf16_f32 v169, v170, v171
	v_cvt_pk_bf16_f32 v172, v172, v173
	v_cvt_pk_bf16_f32 v173, v174, v175
	global_store_dwordx2 v2, v[160:161], s[50:51] offset:0
	global_store_dwordx2 v2, v[164:165], s[50:51] offset:512
	global_store_dwordx2 v2, v[168:169], s[50:51] offset:1024
	global_store_dwordx2 v2, v[172:173], s[50:51] offset:1536
	s_add_u32 s53, s16, 0x3000
	s_lshl_b32 s18, s53, 12
	s_lshl_b32 s19, s53, 11
	s_add_u32 s36, s4, s18
	s_addc_u32 s37, s5, 0
	s_add_u32 s38, s6, s19
	s_addc_u32 s39, s7, 0
	s_add_u32 s38, s38, 0x5200000
	s_addc_u32 s39, s39, 0
	s_add_u32 s40, s4, s18
	s_addc_u32 s41, s5, 0
	s_add_u32 s42, s6, s19
	s_addc_u32 s43, s7, 0
	s_add_u32 s42, s42, 0x3100000
	s_addc_u32 s43, s43, 0
	global_load_dwordx2 v[130:131], v2, s[38:39] offset:0
	global_load_dwordx2 v[134:135], v2, s[38:39] offset:512
	global_load_dwordx2 v[138:139], v2, s[38:39] offset:1024
	global_load_dwordx2 v[142:143], v2, s[38:39] offset:1536
	global_load_dwordx4 v[144:147], v1, s[36:37] offset:0 nt
	global_load_dwordx4 v[148:151], v1, s[36:37] offset:1024 nt
	global_load_dwordx4 v[152:155], v1, s[36:37] offset:2048 nt
	global_load_dwordx4 v[156:159], v1, s[36:37] offset:3072 nt
	s_add_u32 s53, s16, 0x3800
	s_lshl_b32 s18, s53, 12
	s_lshl_b32 s19, s53, 11
	s_add_u32 s44, s4, s18
	s_addc_u32 s45, s5, 0
	s_add_u32 s46, s6, s19
	s_addc_u32 s47, s7, 0
	s_add_u32 s46, s46, 0x5200000
	s_addc_u32 s47, s47, 0
	s_add_u32 s48, s4, s18
	s_addc_u32 s49, s5, 0
	s_add_u32 s50, s6, s19
	s_addc_u32 s51, s7, 0
	s_add_u32 s50, s50, 0x3100000
	s_addc_u32 s51, s51, 0
	global_load_dwordx2 v[162:163], v2, s[46:47] offset:0
	global_load_dwordx2 v[166:167], v2, s[46:47] offset:512
	global_load_dwordx2 v[170:171], v2, s[46:47] offset:1024
	global_load_dwordx2 v[174:175], v2, s[46:47] offset:1536
	global_load_dwordx4 v[176:179], v1, s[44:45] offset:0 nt
	global_load_dwordx4 v[180:183], v1, s[44:45] offset:1024 nt
	global_load_dwordx4 v[184:187], v1, s[44:45] offset:2048 nt
	global_load_dwordx4 v[188:191], v1, s[44:45] offset:3072 nt
	s_waitcnt vmcnt(32)
	v_lshlrev_b32_e32 v64, 16, v66
	v_and_b32_e32 v65, 0xffff0000, v66
	v_lshlrev_b32_e32 v66, 16, v67
	v_and_b32_e32 v67, 0xffff0000, v67
	v_lshlrev_b32_e32 v68, 16, v70
	v_and_b32_e32 v69, 0xffff0000, v70
	v_lshlrev_b32_e32 v70, 16, v71
	v_and_b32_e32 v71, 0xffff0000, v71
	v_lshlrev_b32_e32 v72, 16, v74
	v_and_b32_e32 v73, 0xffff0000, v74
	v_lshlrev_b32_e32 v74, 16, v75
	v_and_b32_e32 v75, 0xffff0000, v75
	v_lshlrev_b32_e32 v76, 16, v78
	v_and_b32_e32 v77, 0xffff0000, v78
	v_lshlrev_b32_e32 v78, 16, v79
	v_and_b32_e32 v79, 0xffff0000, v79
	v_lshlrev_b32_e32 v96, 16, v98
	v_and_b32_e32 v97, 0xffff0000, v98
	v_lshlrev_b32_e32 v98, 16, v99
	v_and_b32_e32 v99, 0xffff0000, v99
	v_lshlrev_b32_e32 v100, 16, v102
	v_and_b32_e32 v101, 0xffff0000, v102
	v_lshlrev_b32_e32 v102, 16, v103
	v_and_b32_e32 v103, 0xffff0000, v103
	v_lshlrev_b32_e32 v104, 16, v106
	v_and_b32_e32 v105, 0xffff0000, v106
	v_lshlrev_b32_e32 v106, 16, v107
	v_and_b32_e32 v107, 0xffff0000, v107
	v_lshlrev_b32_e32 v108, 16, v110
	v_and_b32_e32 v109, 0xffff0000, v110
	v_lshlrev_b32_e32 v110, 16, v111
	v_and_b32_e32 v111, 0xffff0000, v111
	v_mul_f32_e32 v10, v64, v64
	v_fmac_f32_e32 v10, v65, v65
	v_fmac_f32_e32 v10, v66, v66
	v_fmac_f32_e32 v10, v67, v67
	v_fmac_f32_e32 v10, v68, v68
	v_fmac_f32_e32 v10, v69, v69
	v_fmac_f32_e32 v10, v70, v70
	v_fmac_f32_e32 v10, v71, v71
	v_fmac_f32_e32 v10, v72, v72
	v_fmac_f32_e32 v10, v73, v73
	v_fmac_f32_e32 v10, v74, v74
	v_fmac_f32_e32 v10, v75, v75
	v_fmac_f32_e32 v10, v76, v76
	v_fmac_f32_e32 v10, v77, v77
	v_fmac_f32_e32 v10, v78, v78
	v_fmac_f32_e32 v10, v79, v79
	v_mul_f32_e32 v11, v96, v96
	v_fmac_f32_e32 v11, v97, v97
	v_fmac_f32_e32 v11, v98, v98
	v_fmac_f32_e32 v11, v99, v99
	v_fmac_f32_e32 v11, v100, v100
	v_fmac_f32_e32 v11, v101, v101
	v_fmac_f32_e32 v11, v102, v102
	v_fmac_f32_e32 v11, v103, v103
	v_fmac_f32_e32 v11, v104, v104
	v_fmac_f32_e32 v11, v105, v105
	v_fmac_f32_e32 v11, v106, v106
	v_fmac_f32_e32 v11, v107, v107
	v_fmac_f32_e32 v11, v108, v108
	v_fmac_f32_e32 v11, v109, v109
	v_fmac_f32_e32 v11, v110, v110
	v_fmac_f32_e32 v11, v111, v111
	ds_bpermute_b32 v12, v4, v10
	ds_bpermute_b32 v13, v4, v11
	s_waitcnt lgkmcnt(0)
	v_add_f32_e32 v10, v10, v12
	v_add_f32_e32 v11, v11, v13
	ds_bpermute_b32 v12, v5, v10
	ds_bpermute_b32 v13, v5, v11
	s_waitcnt lgkmcnt(0)
	v_add_f32_e32 v10, v10, v12
	v_add_f32_e32 v11, v11, v13
	ds_bpermute_b32 v12, v6, v10
	ds_bpermute_b32 v13, v6, v11
	s_waitcnt lgkmcnt(0)
	v_add_f32_e32 v10, v10, v12
	v_add_f32_e32 v11, v11, v13
	ds_bpermute_b32 v12, v7, v10
	ds_bpermute_b32 v13, v7, v11
	s_waitcnt lgkmcnt(0)
	v_add_f32_e32 v10, v10, v12
	v_add_f32_e32 v11, v11, v13
	ds_bpermute_b32 v12, v8, v10
	ds_bpermute_b32 v13, v8, v11
	s_waitcnt lgkmcnt(0)
	v_add_f32_e32 v10, v10, v12
	v_add_f32_e32 v11, v11, v13
	ds_bpermute_b32 v12, v9, v10
	ds_bpermute_b32 v13, v9, v11
	s_waitcnt lgkmcnt(0)
	v_add_f32_e32 v10, v10, v12
	v_add_f32_e32 v11, v11, v13
	v_fma_f32 v14, v10, s17, v3
	v_fma_f32 v15, v11, s17, v3
	v_rsq_f32_e32 v14, v14
	v_rsq_f32_e32 v15, v15
	s_nop 0
	v_mul_f32_e32 v64, v64, v14
	v_mul_f32_e32 v65, v65, v14
	v_mul_f32_e32 v66, v66, v14
	v_mul_f32_e32 v67, v67, v14
	v_mul_f32_e32 v68, v68, v14
	v_mul_f32_e32 v69, v69, v14
	v_mul_f32_e32 v70, v70, v14
	v_mul_f32_e32 v71, v71, v14
	v_mul_f32_e32 v72, v72, v14
	v_mul_f32_e32 v73, v73, v14
	v_mul_f32_e32 v74, v74, v14
	v_mul_f32_e32 v75, v75, v14
	v_mul_f32_e32 v76, v76, v14
	v_mul_f32_e32 v77, v77, v14
	v_mul_f32_e32 v78, v78, v14
	v_mul_f32_e32 v79, v79, v14
	v_fmac_f32_e32 v80, v64, v20
	v_fmac_f32_e32 v81, v65, v21
	v_fmac_f32_e32 v82, v66, v22
	v_fmac_f32_e32 v83, v67, v23
	v_fmac_f32_e32 v84, v68, v24
	v_fmac_f32_e32 v85, v69, v25
	v_fmac_f32_e32 v86, v70, v26
	v_fmac_f32_e32 v87, v71, v27
	v_fmac_f32_e32 v88, v72, v28
	v_fmac_f32_e32 v89, v73, v29
	v_fmac_f32_e32 v90, v74, v30
	v_fmac_f32_e32 v91, v75, v31
	v_fmac_f32_e32 v92, v76, v32
	v_fmac_f32_e32 v93, v77, v33
	v_fmac_f32_e32 v94, v78, v34
	v_fmac_f32_e32 v95, v79, v35
	global_store_dwordx4 v1, v[80:83], s[24:25] offset:0 nt
	global_store_dwordx4 v1, v[84:87], s[24:25] offset:1024 nt
	global_store_dwordx4 v1, v[88:91], s[24:25] offset:2048 nt
	global_store_dwordx4 v1, v[92:95], s[24:25] offset:3072 nt
	v_mul_f32_e32 v96, v96, v15
	v_mul_f32_e32 v97, v97, v15
	v_mul_f32_e32 v98, v98, v15
	v_mul_f32_e32 v99, v99, v15
	v_mul_f32_e32 v100, v100, v15
	v_mul_f32_e32 v101, v101, v15
	v_mul_f32_e32 v102, v102, v15
	v_mul_f32_e32 v103, v103, v15
	v_mul_f32_e32 v104, v104, v15
	v_mul_f32_e32 v105, v105, v15
	v_mul_f32_e32 v106, v106, v15
	v_mul_f32_e32 v107, v107, v15
	v_mul_f32_e32 v108, v108, v15
	v_mul_f32_e32 v109, v109, v15
	v_mul_f32_e32 v110, v110, v15
	v_mul_f32_e32 v111, v111, v15
	v_fmac_f32_e32 v112, v96, v20
	v_fmac_f32_e32 v113, v97, v21
	v_fmac_f32_e32 v114, v98, v22
	v_fmac_f32_e32 v115, v99, v23
	v_fmac_f32_e32 v116, v100, v24
	v_fmac_f32_e32 v117, v101, v25
	v_fmac_f32_e32 v118, v102, v26
	v_fmac_f32_e32 v119, v103, v27
	v_fmac_f32_e32 v120, v104, v28
	v_fmac_f32_e32 v121, v105, v29
	v_fmac_f32_e32 v122, v106, v30
	v_fmac_f32_e32 v123, v107, v31
	v_fmac_f32_e32 v124, v108, v32
	v_fmac_f32_e32 v125, v109, v33
	v_fmac_f32_e32 v126, v110, v34
	v_fmac_f32_e32 v127, v111, v35
	global_store_dwordx4 v1, v[112:115], s[32:33] offset:0 nt
	global_store_dwordx4 v1, v[116:119], s[32:33] offset:1024 nt
	global_store_dwordx4 v1, v[120:123], s[32:33] offset:2048 nt
	global_store_dwordx4 v1, v[124:127], s[32:33] offset:3072 nt
	v_mul_f32_e32 v10, v80, v80
	v_fmac_f32_e32 v10, v81, v81
	v_fmac_f32_e32 v10, v82, v82
	v_fmac_f32_e32 v10, v83, v83
	v_fmac_f32_e32 v10, v84, v84
	v_fmac_f32_e32 v10, v85, v85
	v_fmac_f32_e32 v10, v86, v86
	v_fmac_f32_e32 v10, v87, v87
	v_fmac_f32_e32 v10, v88, v88
	v_fmac_f32_e32 v10, v89, v89
	v_fmac_f32_e32 v10, v90, v90
	v_fmac_f32_e32 v10, v91, v91
	v_fmac_f32_e32 v10, v92, v92
	v_fmac_f32_e32 v10, v93, v93
	v_fmac_f32_e32 v10, v94, v94
	v_fmac_f32_e32 v10, v95, v95
	v_mul_f32_e32 v11, v112, v112
	v_fmac_f32_e32 v11, v113, v113
	v_fmac_f32_e32 v11, v114, v114
	v_fmac_f32_e32 v11, v115, v115
	v_fmac_f32_e32 v11, v116, v116
	v_fmac_f32_e32 v11, v117, v117
	v_fmac_f32_e32 v11, v118, v118
	v_fmac_f32_e32 v11, v119, v119
	v_fmac_f32_e32 v11, v120, v120
	v_fmac_f32_e32 v11, v121, v121
	v_fmac_f32_e32 v11, v122, v122
	v_fmac_f32_e32 v11, v123, v123
	v_fmac_f32_e32 v11, v124, v124
	v_fmac_f32_e32 v11, v125, v125
	v_fmac_f32_e32 v11, v126, v126
	v_fmac_f32_e32 v11, v127, v127
	ds_bpermute_b32 v12, v4, v10
	ds_bpermute_b32 v13, v4, v11
	s_waitcnt lgkmcnt(0)
	v_add_f32_e32 v10, v10, v12
	v_add_f32_e32 v11, v11, v13
	ds_bpermute_b32 v12, v5, v10
	ds_bpermute_b32 v13, v5, v11
	s_waitcnt lgkmcnt(0)
	v_add_f32_e32 v10, v10, v12
	v_add_f32_e32 v11, v11, v13
	ds_bpermute_b32 v12, v6, v10
	ds_bpermute_b32 v13, v6, v11
	s_waitcnt lgkmcnt(0)
	v_add_f32_e32 v10, v10, v12
	v_add_f32_e32 v11, v11, v13
	ds_bpermute_b32 v12, v7, v10
	ds_bpermute_b32 v13, v7, v11
	s_waitcnt lgkmcnt(0)
	v_add_f32_e32 v10, v10, v12
	v_add_f32_e32 v11, v11, v13
	ds_bpermute_b32 v12, v8, v10
	ds_bpermute_b32 v13, v8, v11
	s_waitcnt lgkmcnt(0)
	v_add_f32_e32 v10, v10, v12
	v_add_f32_e32 v11, v11, v13
	ds_bpermute_b32 v12, v9, v10
	ds_bpermute_b32 v13, v9, v11
	s_waitcnt lgkmcnt(0)
	v_add_f32_e32 v10, v10, v12
	v_add_f32_e32 v11, v11, v13
	v_fma_f32 v14, v10, s17, v3
	v_fma_f32 v15, v11, s17, v3
	v_rsq_f32_e32 v14, v14
	v_rsq_f32_e32 v15, v15
	s_nop 0
	v_mul_f32_e32 v64, v80, v14
	v_mul_f32_e32 v65, v81, v14
	v_mul_f32_e32 v66, v82, v14
	v_mul_f32_e32 v67, v83, v14
	v_mul_f32_e32 v68, v84, v14
	v_mul_f32_e32 v69, v85, v14
	v_mul_f32_e32 v70, v86, v14
	v_mul_f32_e32 v71, v87, v14
	v_mul_f32_e32 v72, v88, v14
	v_mul_f32_e32 v73, v89, v14
	v_mul_f32_e32 v74, v90, v14
	v_mul_f32_e32 v75, v91, v14
	v_mul_f32_e32 v76, v92, v14
	v_mul_f32_e32 v77, v93, v14
	v_mul_f32_e32 v78, v94, v14
	v_mul_f32_e32 v79, v95, v14
	v_mul_f32_e32 v64, v64, v36
	v_mul_f32_e32 v65, v65, v37
	v_mul_f32_e32 v66, v66, v38
	v_mul_f32_e32 v67, v67, v39
	v_mul_f32_e32 v68, v68, v40
	v_mul_f32_e32 v69, v69, v41
	v_mul_f32_e32 v70, v70, v42
	v_mul_f32_e32 v71, v71, v43
	v_mul_f32_e32 v72, v72, v44
	v_mul_f32_e32 v73, v73, v45
	v_mul_f32_e32 v74, v74, v46
	v_mul_f32_e32 v75, v75, v47
	v_mul_f32_e32 v76, v76, v48
	v_mul_f32_e32 v77, v77, v49
	v_mul_f32_e32 v78, v78, v50
	v_mul_f32_e32 v79, v79, v51
	v_cvt_pk_bf16_f32 v64, v64, v65
	v_cvt_pk_bf16_f32 v65, v66, v67
	v_cvt_pk_bf16_f32 v68, v68, v69
	v_cvt_pk_bf16_f32 v69, v70, v71
	v_cvt_pk_bf16_f32 v72, v72, v73
	v_cvt_pk_bf16_f32 v73, v74, v75
	v_cvt_pk_bf16_f32 v76, v76, v77
	v_cvt_pk_bf16_f32 v77, v78, v79
	global_store_dwordx2 v2, v[64:65], s[26:27] offset:0
	global_store_dwordx2 v2, v[68:69], s[26:27] offset:512
	global_store_dwordx2 v2, v[72:73], s[26:27] offset:1024
	global_store_dwordx2 v2, v[76:77], s[26:27] offset:1536
	v_mul_f32_e32 v96, v112, v15
	v_mul_f32_e32 v97, v113, v15
	v_mul_f32_e32 v98, v114, v15
	v_mul_f32_e32 v99, v115, v15
	v_mul_f32_e32 v100, v116, v15
	v_mul_f32_e32 v101, v117, v15
	v_mul_f32_e32 v102, v118, v15
	v_mul_f32_e32 v103, v119, v15
	v_mul_f32_e32 v104, v120, v15
	v_mul_f32_e32 v105, v121, v15
	v_mul_f32_e32 v106, v122, v15
	v_mul_f32_e32 v107, v123, v15
	v_mul_f32_e32 v108, v124, v15
	v_mul_f32_e32 v109, v125, v15
	v_mul_f32_e32 v110, v126, v15
	v_mul_f32_e32 v111, v127, v15
	v_mul_f32_e32 v96, v96, v36
	v_mul_f32_e32 v97, v97, v37
	v_mul_f32_e32 v98, v98, v38
	v_mul_f32_e32 v99, v99, v39
	v_mul_f32_e32 v100, v100, v40
	v_mul_f32_e32 v101, v101, v41
	v_mul_f32_e32 v102, v102, v42
	v_mul_f32_e32 v103, v103, v43
	v_mul_f32_e32 v104, v104, v44
	v_mul_f32_e32 v105, v105, v45
	v_mul_f32_e32 v106, v106, v46
	v_mul_f32_e32 v107, v107, v47
	v_mul_f32_e32 v108, v108, v48
	v_mul_f32_e32 v109, v109, v49
	v_mul_f32_e32 v110, v110, v50
	v_mul_f32_e32 v111, v111, v51
	v_cvt_pk_bf16_f32 v96, v96, v97
	v_cvt_pk_bf16_f32 v97, v98, v99
	v_cvt_pk_bf16_f32 v100, v100, v101
	v_cvt_pk_bf16_f32 v101, v102, v103
	v_cvt_pk_bf16_f32 v104, v104, v105
	v_cvt_pk_bf16_f32 v105, v106, v107
	v_cvt_pk_bf16_f32 v108, v108, v109
	v_cvt_pk_bf16_f32 v109, v110, v111
	global_store_dwordx2 v2, v[96:97], s[34:35] offset:0
	global_store_dwordx2 v2, v[100:101], s[34:35] offset:512
	global_store_dwordx2 v2, v[104:105], s[34:35] offset:1024
	global_store_dwordx2 v2, v[108:109], s[34:35] offset:1536
	s_waitcnt vmcnt(16)
	v_lshlrev_b32_e32 v128, 16, v130
	v_and_b32_e32 v129, 0xffff0000, v130
	v_lshlrev_b32_e32 v130, 16, v131
	v_and_b32_e32 v131, 0xffff0000, v131
	v_lshlrev_b32_e32 v132, 16, v134
	v_and_b32_e32 v133, 0xffff0000, v134
	v_lshlrev_b32_e32 v134, 16, v135
	v_and_b32_e32 v135, 0xffff0000, v135
	v_lshlrev_b32_e32 v136, 16, v138
	v_and_b32_e32 v137, 0xffff0000, v138
	v_lshlrev_b32_e32 v138, 16, v139
	v_and_b32_e32 v139, 0xffff0000, v139
	v_lshlrev_b32_e32 v140, 16, v142
	v_and_b32_e32 v141, 0xffff0000, v142
	v_lshlrev_b32_e32 v142, 16, v143
	v_and_b32_e32 v143, 0xffff0000, v143
	v_lshlrev_b32_e32 v160, 16, v162
	v_and_b32_e32 v161, 0xffff0000, v162
	v_lshlrev_b32_e32 v162, 16, v163
	v_and_b32_e32 v163, 0xffff0000, v163
	v_lshlrev_b32_e32 v164, 16, v166
	v_and_b32_e32 v165, 0xffff0000, v166
	v_lshlrev_b32_e32 v166, 16, v167
	v_and_b32_e32 v167, 0xffff0000, v167
	v_lshlrev_b32_e32 v168, 16, v170
	v_and_b32_e32 v169, 0xffff0000, v170
	v_lshlrev_b32_e32 v170, 16, v171
	v_and_b32_e32 v171, 0xffff0000, v171
	v_lshlrev_b32_e32 v172, 16, v174
	v_and_b32_e32 v173, 0xffff0000, v174
	v_lshlrev_b32_e32 v174, 16, v175
	v_and_b32_e32 v175, 0xffff0000, v175
	v_mul_f32_e32 v10, v128, v128
	v_fmac_f32_e32 v10, v129, v129
	v_fmac_f32_e32 v10, v130, v130
	v_fmac_f32_e32 v10, v131, v131
	v_fmac_f32_e32 v10, v132, v132
	v_fmac_f32_e32 v10, v133, v133
	v_fmac_f32_e32 v10, v134, v134
	v_fmac_f32_e32 v10, v135, v135
	v_fmac_f32_e32 v10, v136, v136
	v_fmac_f32_e32 v10, v137, v137
	v_fmac_f32_e32 v10, v138, v138
	v_fmac_f32_e32 v10, v139, v139
	v_fmac_f32_e32 v10, v140, v140
	v_fmac_f32_e32 v10, v141, v141
	v_fmac_f32_e32 v10, v142, v142
	v_fmac_f32_e32 v10, v143, v143
	v_mul_f32_e32 v11, v160, v160
	v_fmac_f32_e32 v11, v161, v161
	v_fmac_f32_e32 v11, v162, v162
	v_fmac_f32_e32 v11, v163, v163
	v_fmac_f32_e32 v11, v164, v164
	v_fmac_f32_e32 v11, v165, v165
	v_fmac_f32_e32 v11, v166, v166
	v_fmac_f32_e32 v11, v167, v167
	v_fmac_f32_e32 v11, v168, v168
	v_fmac_f32_e32 v11, v169, v169
	v_fmac_f32_e32 v11, v170, v170
	v_fmac_f32_e32 v11, v171, v171
	v_fmac_f32_e32 v11, v172, v172
	v_fmac_f32_e32 v11, v173, v173
	v_fmac_f32_e32 v11, v174, v174
	v_fmac_f32_e32 v11, v175, v175
	ds_bpermute_b32 v12, v4, v10
	ds_bpermute_b32 v13, v4, v11
	s_waitcnt lgkmcnt(0)
	v_add_f32_e32 v10, v10, v12
	v_add_f32_e32 v11, v11, v13
	ds_bpermute_b32 v12, v5, v10
	ds_bpermute_b32 v13, v5, v11
	s_waitcnt lgkmcnt(0)
	v_add_f32_e32 v10, v10, v12
	v_add_f32_e32 v11, v11, v13
	ds_bpermute_b32 v12, v6, v10
	ds_bpermute_b32 v13, v6, v11
	s_waitcnt lgkmcnt(0)
	v_add_f32_e32 v10, v10, v12
	v_add_f32_e32 v11, v11, v13
	ds_bpermute_b32 v12, v7, v10
	ds_bpermute_b32 v13, v7, v11
	s_waitcnt lgkmcnt(0)
	v_add_f32_e32 v10, v10, v12
	v_add_f32_e32 v11, v11, v13
	ds_bpermute_b32 v12, v8, v10
	ds_bpermute_b32 v13, v8, v11
	s_waitcnt lgkmcnt(0)
	v_add_f32_e32 v10, v10, v12
	v_add_f32_e32 v11, v11, v13
	ds_bpermute_b32 v12, v9, v10
	ds_bpermute_b32 v13, v9, v11
	s_waitcnt lgkmcnt(0)
	v_add_f32_e32 v10, v10, v12
	v_add_f32_e32 v11, v11, v13
	v_fma_f32 v14, v10, s17, v3
	v_fma_f32 v15, v11, s17, v3
	v_rsq_f32_e32 v14, v14
	v_rsq_f32_e32 v15, v15
	s_nop 0
	v_mul_f32_e32 v128, v128, v14
	v_mul_f32_e32 v129, v129, v14
	v_mul_f32_e32 v130, v130, v14
	v_mul_f32_e32 v131, v131, v14
	v_mul_f32_e32 v132, v132, v14
	v_mul_f32_e32 v133, v133, v14
	v_mul_f32_e32 v134, v134, v14
	v_mul_f32_e32 v135, v135, v14
	v_mul_f32_e32 v136, v136, v14
	v_mul_f32_e32 v137, v137, v14
	v_mul_f32_e32 v138, v138, v14
	v_mul_f32_e32 v139, v139, v14
	v_mul_f32_e32 v140, v140, v14
	v_mul_f32_e32 v141, v141, v14
	v_mul_f32_e32 v142, v142, v14
	v_mul_f32_e32 v143, v143, v14
	v_fmac_f32_e32 v144, v128, v20
	v_fmac_f32_e32 v145, v129, v21
	v_fmac_f32_e32 v146, v130, v22
	v_fmac_f32_e32 v147, v131, v23
	v_fmac_f32_e32 v148, v132, v24
	v_fmac_f32_e32 v149, v133, v25
	v_fmac_f32_e32 v150, v134, v26
	v_fmac_f32_e32 v151, v135, v27
	v_fmac_f32_e32 v152, v136, v28
	v_fmac_f32_e32 v153, v137, v29
	v_fmac_f32_e32 v154, v138, v30
	v_fmac_f32_e32 v155, v139, v31
	v_fmac_f32_e32 v156, v140, v32
	v_fmac_f32_e32 v157, v141, v33
	v_fmac_f32_e32 v158, v142, v34
	v_fmac_f32_e32 v159, v143, v35
	global_store_dwordx4 v1, v[144:147], s[40:41] offset:0 nt
	global_store_dwordx4 v1, v[148:151], s[40:41] offset:1024 nt
	global_store_dwordx4 v1, v[152:155], s[40:41] offset:2048 nt
	global_store_dwordx4 v1, v[156:159], s[40:41] offset:3072 nt
	v_mul_f32_e32 v160, v160, v15
	v_mul_f32_e32 v161, v161, v15
	v_mul_f32_e32 v162, v162, v15
	v_mul_f32_e32 v163, v163, v15
	v_mul_f32_e32 v164, v164, v15
	v_mul_f32_e32 v165, v165, v15
	v_mul_f32_e32 v166, v166, v15
	v_mul_f32_e32 v167, v167, v15
	v_mul_f32_e32 v168, v168, v15
	v_mul_f32_e32 v169, v169, v15
	v_mul_f32_e32 v170, v170, v15
	v_mul_f32_e32 v171, v171, v15
	v_mul_f32_e32 v172, v172, v15
	v_mul_f32_e32 v173, v173, v15
	v_mul_f32_e32 v174, v174, v15
	v_mul_f32_e32 v175, v175, v15
	v_fmac_f32_e32 v176, v160, v20
	v_fmac_f32_e32 v177, v161, v21
	v_fmac_f32_e32 v178, v162, v22
	v_fmac_f32_e32 v179, v163, v23
	v_fmac_f32_e32 v180, v164, v24
	v_fmac_f32_e32 v181, v165, v25
	v_fmac_f32_e32 v182, v166, v26
	v_fmac_f32_e32 v183, v167, v27
	v_fmac_f32_e32 v184, v168, v28
	v_fmac_f32_e32 v185, v169, v29
	v_fmac_f32_e32 v186, v170, v30
	v_fmac_f32_e32 v187, v171, v31
	v_fmac_f32_e32 v188, v172, v32
	v_fmac_f32_e32 v189, v173, v33
	v_fmac_f32_e32 v190, v174, v34
	v_fmac_f32_e32 v191, v175, v35
	global_store_dwordx4 v1, v[176:179], s[48:49] offset:0 nt
	global_store_dwordx4 v1, v[180:183], s[48:49] offset:1024 nt
	global_store_dwordx4 v1, v[184:187], s[48:49] offset:2048 nt
	global_store_dwordx4 v1, v[188:191], s[48:49] offset:3072 nt
	v_mul_f32_e32 v10, v144, v144
	v_fmac_f32_e32 v10, v145, v145
	v_fmac_f32_e32 v10, v146, v146
	v_fmac_f32_e32 v10, v147, v147
	v_fmac_f32_e32 v10, v148, v148
	v_fmac_f32_e32 v10, v149, v149
	v_fmac_f32_e32 v10, v150, v150
	v_fmac_f32_e32 v10, v151, v151
	v_fmac_f32_e32 v10, v152, v152
	v_fmac_f32_e32 v10, v153, v153
	v_fmac_f32_e32 v10, v154, v154
	v_fmac_f32_e32 v10, v155, v155
	v_fmac_f32_e32 v10, v156, v156
	v_fmac_f32_e32 v10, v157, v157
	v_fmac_f32_e32 v10, v158, v158
	v_fmac_f32_e32 v10, v159, v159
	v_mul_f32_e32 v11, v176, v176
	v_fmac_f32_e32 v11, v177, v177
	v_fmac_f32_e32 v11, v178, v178
	v_fmac_f32_e32 v11, v179, v179
	v_fmac_f32_e32 v11, v180, v180
	v_fmac_f32_e32 v11, v181, v181
	v_fmac_f32_e32 v11, v182, v182
	v_fmac_f32_e32 v11, v183, v183
	v_fmac_f32_e32 v11, v184, v184
	v_fmac_f32_e32 v11, v185, v185
	v_fmac_f32_e32 v11, v186, v186
	v_fmac_f32_e32 v11, v187, v187
	v_fmac_f32_e32 v11, v188, v188
	v_fmac_f32_e32 v11, v189, v189
	v_fmac_f32_e32 v11, v190, v190
	v_fmac_f32_e32 v11, v191, v191
	ds_bpermute_b32 v12, v4, v10
	ds_bpermute_b32 v13, v4, v11
	s_waitcnt lgkmcnt(0)
	v_add_f32_e32 v10, v10, v12
	v_add_f32_e32 v11, v11, v13
	ds_bpermute_b32 v12, v5, v10
	ds_bpermute_b32 v13, v5, v11
	s_waitcnt lgkmcnt(0)
	v_add_f32_e32 v10, v10, v12
	v_add_f32_e32 v11, v11, v13
	ds_bpermute_b32 v12, v6, v10
	ds_bpermute_b32 v13, v6, v11
	s_waitcnt lgkmcnt(0)
	v_add_f32_e32 v10, v10, v12
	v_add_f32_e32 v11, v11, v13
	ds_bpermute_b32 v12, v7, v10
	ds_bpermute_b32 v13, v7, v11
	s_waitcnt lgkmcnt(0)
	v_add_f32_e32 v10, v10, v12
	v_add_f32_e32 v11, v11, v13
	ds_bpermute_b32 v12, v8, v10
	ds_bpermute_b32 v13, v8, v11
	s_waitcnt lgkmcnt(0)
	v_add_f32_e32 v10, v10, v12
	v_add_f32_e32 v11, v11, v13
	ds_bpermute_b32 v12, v9, v10
	ds_bpermute_b32 v13, v9, v11
	s_waitcnt lgkmcnt(0)
	v_add_f32_e32 v10, v10, v12
	v_add_f32_e32 v11, v11, v13
	v_fma_f32 v14, v10, s17, v3
	v_fma_f32 v15, v11, s17, v3
	v_rsq_f32_e32 v14, v14
	v_rsq_f32_e32 v15, v15
	s_nop 0
	v_mul_f32_e32 v128, v144, v14
	v_mul_f32_e32 v129, v145, v14
	v_mul_f32_e32 v130, v146, v14
	v_mul_f32_e32 v131, v147, v14
	v_mul_f32_e32 v132, v148, v14
	v_mul_f32_e32 v133, v149, v14
	v_mul_f32_e32 v134, v150, v14
	v_mul_f32_e32 v135, v151, v14
	v_mul_f32_e32 v136, v152, v14
	v_mul_f32_e32 v137, v153, v14
	v_mul_f32_e32 v138, v154, v14
	v_mul_f32_e32 v139, v155, v14
	v_mul_f32_e32 v140, v156, v14
	v_mul_f32_e32 v141, v157, v14
	v_mul_f32_e32 v142, v158, v14
	v_mul_f32_e32 v143, v159, v14
	v_mul_f32_e32 v128, v128, v36
	v_mul_f32_e32 v129, v129, v37
	v_mul_f32_e32 v130, v130, v38
	v_mul_f32_e32 v131, v131, v39
	v_mul_f32_e32 v132, v132, v40
	v_mul_f32_e32 v133, v133, v41
	v_mul_f32_e32 v134, v134, v42
	v_mul_f32_e32 v135, v135, v43
	v_mul_f32_e32 v136, v136, v44
	v_mul_f32_e32 v137, v137, v45
	v_mul_f32_e32 v138, v138, v46
	v_mul_f32_e32 v139, v139, v47
	v_mul_f32_e32 v140, v140, v48
	v_mul_f32_e32 v141, v141, v49
	v_mul_f32_e32 v142, v142, v50
	v_mul_f32_e32 v143, v143, v51
	v_cvt_pk_bf16_f32 v128, v128, v129
	v_cvt_pk_bf16_f32 v129, v130, v131
	v_cvt_pk_bf16_f32 v132, v132, v133
	v_cvt_pk_bf16_f32 v133, v134, v135
	v_cvt_pk_bf16_f32 v136, v136, v137
	v_cvt_pk_bf16_f32 v137, v138, v139
	v_cvt_pk_bf16_f32 v140, v140, v141
	v_cvt_pk_bf16_f32 v141, v142, v143
	global_store_dwordx2 v2, v[128:129], s[42:43] offset:0
	global_store_dwordx2 v2, v[132:133], s[42:43] offset:512
	global_store_dwordx2 v2, v[136:137], s[42:43] offset:1024
	global_store_dwordx2 v2, v[140:141], s[42:43] offset:1536
	v_mul_f32_e32 v160, v176, v15
	v_mul_f32_e32 v161, v177, v15
	v_mul_f32_e32 v162, v178, v15
	v_mul_f32_e32 v163, v179, v15
	v_mul_f32_e32 v164, v180, v15
	v_mul_f32_e32 v165, v181, v15
	v_mul_f32_e32 v166, v182, v15
	v_mul_f32_e32 v167, v183, v15
	v_mul_f32_e32 v168, v184, v15
	v_mul_f32_e32 v169, v185, v15
	v_mul_f32_e32 v170, v186, v15
	v_mul_f32_e32 v171, v187, v15
	v_mul_f32_e32 v172, v188, v15
	v_mul_f32_e32 v173, v189, v15
	v_mul_f32_e32 v174, v190, v15
	v_mul_f32_e32 v175, v191, v15
	v_mul_f32_e32 v160, v160, v36
	v_mul_f32_e32 v161, v161, v37
	v_mul_f32_e32 v162, v162, v38
	v_mul_f32_e32 v163, v163, v39
	v_mul_f32_e32 v164, v164, v40
	v_mul_f32_e32 v165, v165, v41
	v_mul_f32_e32 v166, v166, v42
	v_mul_f32_e32 v167, v167, v43
	v_mul_f32_e32 v168, v168, v44
	v_mul_f32_e32 v169, v169, v45
	v_mul_f32_e32 v170, v170, v46
	v_mul_f32_e32 v171, v171, v47
	v_mul_f32_e32 v172, v172, v48
	v_mul_f32_e32 v173, v173, v49
	v_mul_f32_e32 v174, v174, v50
	v_mul_f32_e32 v175, v175, v51
	v_cvt_pk_bf16_f32 v160, v160, v161
	v_cvt_pk_bf16_f32 v161, v162, v163
	v_cvt_pk_bf16_f32 v164, v164, v165
	v_cvt_pk_bf16_f32 v165, v166, v167
	v_cvt_pk_bf16_f32 v168, v168, v169
	v_cvt_pk_bf16_f32 v169, v170, v171
	v_cvt_pk_bf16_f32 v172, v172, v173
	v_cvt_pk_bf16_f32 v173, v174, v175
	global_store_dwordx2 v2, v[160:161], s[50:51] offset:0
	global_store_dwordx2 v2, v[164:165], s[50:51] offset:512
	global_store_dwordx2 v2, v[168:169], s[50:51] offset:1024
	global_store_dwordx2 v2, v[172:173], s[50:51] offset:1536
	v_add_f32_e32 v208, v208, v212
	v_add_f32_e32 v209, v209, v213
	v_add_f32_e32 v210, v210, v214
	v_add_f32_e32 v211, v211, v215
	v_add_f32_e32 v216, v216, v220
	v_add_f32_e32 v217, v217, v221
	v_add_f32_e32 v218, v218, v222
	v_add_f32_e32 v219, v219, v223
	v_add_f32_e32 v224, v224, v228
	v_add_f32_e32 v225, v225, v229
	v_add_f32_e32 v226, v226, v230
	v_add_f32_e32 v227, v227, v231
	v_add_f32_e32 v232, v232, v236
	v_add_f32_e32 v233, v233, v237
	v_add_f32_e32 v234, v234, v238
	v_add_f32_e32 v235, v235, v239
	v_add_f32_e32 v208, v208, v216
	v_add_f32_e32 v209, v209, v217
	v_add_f32_e32 v210, v210, v218
	v_add_f32_e32 v211, v211, v219
	v_add_f32_e32 v224, v224, v232
	v_add_f32_e32 v225, v225, v233
	v_add_f32_e32 v226, v226, v234
	v_add_f32_e32 v227, v227, v235
	v_add_f32_e32 v208, v208, v224
	v_add_f32_e32 v209, v209, v225
	v_add_f32_e32 v210, v210, v226
	v_add_f32_e32 v211, v211, v227
	v_readfirstlane_b32 s18, v0
	s_lshr_b32 s18, s18, 6
	s_lshl_b32 s19, s18, 2
	s_and_b32 s52, s18, 4
	s_lshl_b32 s52, s52, 2
	v_mov_b32_e32 v16, s19
	v_mov_b32_e32 v17, s52
	v_mul_f32_e32 v10, v208, v208
	v_fmac_f32_e32 v10, v209, v209
	v_fmac_f32_e32 v10, v210, v210
	v_fmac_f32_e32 v10, v211, v211
	ds_bpermute_b32 v11, v4, v10
	s_waitcnt lgkmcnt(0)
	v_add_f32_e32 v10, v10, v11
	ds_bpermute_b32 v11, v5, v10
	s_waitcnt lgkmcnt(0)
	v_add_f32_e32 v10, v10, v11
	ds_bpermute_b32 v11, v6, v10
	s_waitcnt lgkmcnt(0)
	v_add_f32_e32 v10, v10, v11
	ds_bpermute_b32 v11, v7, v10
	s_waitcnt lgkmcnt(0)
	v_add_f32_e32 v10, v10, v11
	ds_bpermute_b32 v11, v8, v10
	s_waitcnt lgkmcnt(0)
	v_add_f32_e32 v10, v10, v11
	ds_bpermute_b32 v11, v9, v10
	s_waitcnt lgkmcnt(0)
	v_add_f32_e32 v10, v10, v11
	ds_write_b32 v16, v10 offset:0
	s_waitcnt lgkmcnt(0)
	s_barrier
	ds_read_b128 v[12:15], v17 offset:0
	s_waitcnt lgkmcnt(0)
	v_add_f32_e32 v12, v12, v13
	v_add_f32_e32 v14, v14, v15
	v_add_f32_e32 v10, v12, v14
	v_fma_f32 v11, v10, s17, v3
	v_rsq_f32_e32 v11, v11
	s_nop 0
	v_mul_f32_e32 v208, v208, v11
	v_mul_f32_e32 v209, v209, v11
	v_mul_f32_e32 v210, v210, v11
	v_mul_f32_e32 v211, v211, v11
	v_fmac_f32_e32 v240, v208, v244
	v_fmac_f32_e32 v241, v209, v245
	v_fmac_f32_e32 v242, v210, v246
	v_fmac_f32_e32 v243, v211, v247
	s_lshl_b32 s18, s54, 12
	s_add_u32 s18, s18, s55
	s_add_u32 s56, s4, s18
	s_addc_u32 s57, s5, 0
	s_add_u32 s56, s56, 0x4000000
	s_addc_u32 s57, s57, 0
	global_store_dwordx4 v1, v[240:243], s[56:57]
	v_mul_f32_e32 v10, v240, v240
	v_fmac_f32_e32 v10, v241, v241
	v_fmac_f32_e32 v10, v242, v242
	v_fmac_f32_e32 v10, v243, v243
	ds_bpermute_b32 v11, v4, v10
	s_waitcnt lgkmcnt(0)
	v_add_f32_e32 v10, v10, v11
	ds_bpermute_b32 v11, v5, v10
	s_waitcnt lgkmcnt(0)
	v_add_f32_e32 v10, v10, v11
	ds_bpermute_b32 v11, v6, v10
	s_waitcnt lgkmcnt(0)
	v_add_f32_e32 v10, v10, v11
	ds_bpermute_b32 v11, v7, v10
	s_waitcnt lgkmcnt(0)
	v_add_f32_e32 v10, v10, v11
	ds_bpermute_b32 v11, v8, v10
	s_waitcnt lgkmcnt(0)
	v_add_f32_e32 v10, v10, v11
	ds_bpermute_b32 v11, v9, v10
	s_waitcnt lgkmcnt(0)
	v_add_f32_e32 v10, v10, v11
	ds_write_b32 v16, v10 offset:64
	s_waitcnt lgkmcnt(0)
	s_barrier
	ds_read_b128 v[12:15], v17 offset:64
	s_waitcnt lgkmcnt(0)
	v_add_f32_e32 v12, v12, v13
	v_add_f32_e32 v14, v14, v15
	v_add_f32_e32 v10, v12, v14
	v_fma_f32 v11, v10, s17, v3
	v_rsq_f32_e32 v11, v11
	s_nop 0
	v_mul_f32_e32 v208, v240, v11
	v_mul_f32_e32 v209, v241, v11
	v_mul_f32_e32 v210, v242, v11
	v_mul_f32_e32 v211, v243, v11
	v_mul_f32_e32 v208, v208, v248
	v_mul_f32_e32 v209, v209, v249
	v_mul_f32_e32 v210, v210, v250
	v_mul_f32_e32 v211, v211, v251
	v_cvt_pk_bf16_f32 v208, v208, v209
	v_cvt_pk_bf16_f32 v209, v210, v211
	s_lshl_b32 s18, s54, 11
	s_lshr_b32 s19, s55, 1
	s_add_u32 s18, s18, s19
	s_add_u32 s56, s6, s18
	s_addc_u32 s57, s7, 0
	s_add_u32 s56, s56, 0x5100000
	s_addc_u32 s57, s57, 0
	global_store_dwordx2 v2, v[208:209], s[56:57]

_Z10fwd_kernelILi11ELi12EEv4Args:
	s_load_dword s3, s[0:1], 0xe8
	s_load_dwordx4 s[4:7], s[0:1], 0xd0
	s_load_dwordx2 s[8:9], s[0:1], 0xa8
	s_load_dwordx2 s[10:11], s[0:1], 0xb0
	s_waitcnt lgkmcnt(0)
	s_cmp_lg_u32 s3, 0x100
	s_cbranch_scc1 .Lrows11_orig
	s_add_u32 s8, s8, 0x1000
	s_addc_u32 s9, s9, 0
	s_add_u32 s10, s10, 0x1000
	s_addc_u32 s11, s11, 0
	v_readfirstlane_b32 s16, v0
	s_lshr_b32 s16, s16, 6
	s_lshl_b32 s18, s2, 3
	s_add_u32 s16, s16, s18
	s_mov_b32 s17, 0x3a800000
	v_mov_b32_e32 v3, 0x358637bd
	v_and_b32_e32 v10, 63, v0
	v_lshlrev_b32_e32 v1, 4, v10
	v_lshlrev_b32_e32 v2, 3, v10
	v_xor_b32_e32 v4, 1, v10
	v_xor_b32_e32 v5, 2, v10
	v_xor_b32_e32 v6, 4, v10
	v_xor_b32_e32 v7, 8, v10
	v_xor_b32_e32 v8, 16, v10
	v_xor_b32_e32 v9, 32, v10
	v_lshlrev_b32_e32 v4, 2, v4
	v_lshlrev_b32_e32 v5, 2, v5
	v_lshlrev_b32_e32 v6, 2, v6
	v_lshlrev_b32_e32 v7, 2, v7
	v_lshlrev_b32_e32 v8, 2, v8
	v_lshlrev_b32_e32 v9, 2, v9
	global_load_dwordx4 v[20:23], v1, s[8:9] offset:0
	global_load_dwordx4 v[24:27], v1, s[8:9] offset:1024
	global_load_dwordx4 v[28:31], v1, s[8:9] offset:2048
	global_load_dwordx4 v[32:35], v1, s[8:9] offset:3072
	global_load_dwordx4 v[36:39], v1, s[10:11] offset:0
	global_load_dwordx4 v[40:43], v1, s[10:11] offset:1024
	global_load_dwordx4 v[44:47], v1, s[10:11] offset:2048
	global_load_dwordx4 v[48:51], v1, s[10:11] offset:3072
	s_lshr_b32 s54, s16, 2
	s_and_b32 s55, s16, 3
	s_lshl_b32 s55, s55, 10
	s_lshl_b32 s18, s54, 12
	s_add_u32 s18, s18, s55
	s_add_u32 s56, s6, s18
	s_addc_u32 s57, s7, 0
	s_add_u32 s56, s56, 0x7400000
	s_addc_u32 s57, s57, 0
	global_load_dwordx4 v[208:211], v1, s[56:57]
	s_add_u32 s56, s56, 0x200000
	s_addc_u32 s57, s57, 0
	global_load_dwordx4 v[212:215], v1, s[56:57]
	s_add_u32 s56, s4, s18
	s_addc_u32 s57, s5, 0
	s_add_u32 s56, s56, 0x4000000
	s_addc_u32 s57, s57, 0
	global_load_dwordx4 v[240:243], v1, s[56:57]
	s_add_u32 s56, s8, s55
	s_addc_u32 s57, s9, 0
	global_load_dwordx4 v[244:247], v1, s[56:57]
	s_add_u32 s56, s10, s55
	s_addc_u32 s57, s11, 0
	global_load_dwordx4 v[248:251], v1, s[56:57]
	s_add_u32 s53, s16, 0x0
	s_lshl_b32 s18, s53, 12
	s_lshl_b32 s19, s53, 11
	s_add_u32 s20, s4, s18
	s_addc_u32 s21, s5, 0
	s_add_u32 s22, s6, s19
	s_addc_u32 s23, s7, 0
	s_add_u32 s22, s22, 0x5200000
	s_addc_u32 s23, s23, 0
	s_add_u32 s24, s4, s18
	s_addc_u32 s25, s5, 0
	s_add_u32 s26, s6, s19
	s_addc_u32 s27, s7, 0
	s_add_u32 s26, s26, 0x3100000
	s_addc_u32 s27, s27, 0
	global_load_dwordx2 v[66:67], v2, s[22:23] offset:0
	global_load_dwordx2 v[70:71], v2, s[22:23] offset:512
	global_load_dwordx2 v[74:75], v2, s[22:23] offset:1024
	global_load_dwordx2 v[78:79], v2, s[22:23] offset:1536
	global_load_dwordx4 v[80:83], v1, s[20:21] offset:0 nt
	global_load_dwordx4 v[84:87], v1, s[20:21] offset:1024 nt
	global_load_dwordx4 v[88:91], v1, s[20:21] offset:2048 nt
	global_load_dwordx4 v[92:95], v1, s[20:21] offset:3072 nt
	s_add_u32 s53, s16, 0x800
	s_lshl_b32 s18, s53, 12
	s_lshl_b32 s19, s53, 11
	s_add_u32 s28, s4, s18
	s_addc_u32 s29, s5, 0
	s_add_u32 s30, s6, s19
	s_addc_u32 s31, s7, 0
	s_add_u32 s30, s30, 0x5200000
	s_addc_u32 s31, s31, 0
	s_add_u32 s32, s4, s18
	s_addc_u32 s33, s5, 0
	s_add_u32 s34, s6, s19
	s_addc_u32 s35, s7, 0
	s_add_u32 s34, s34, 0x3100000
	s_addc_u32 s35, s35, 0
	global_load_dwordx2 v[98:99], v2, s[30:31] offset:0
	global_load_dwordx2 v[102:103], v2, s[30:31] offset:512
	global_load_dwordx2 v[106:107], v2, s[30:31] offset:1024
	global_load_dwordx2 v[110:111], v2, s[30:31] offset:1536
	global_load_dwordx4 v[112:115], v1, s[28:29] offset:0 nt
	global_load_dwordx4 v[116:119], v1, s[28:29] offset:1024 nt
	global_load_dwordx4 v[120:123], v1, s[28:29] offset:2048 nt
	global_load_dwordx4 v[124:127], v1, s[28:29] offset:3072 nt
	s_add_u32 s53, s16, 0x1000
	s_lshl_b32 s18, s53, 12
	s_lshl_b32 s19, s53, 11
	s_add_u32 s36, s4, s18
	s_addc_u32 s37, s5, 0
	s_add_u32 s38, s6, s19
	s_addc_u32 s39, s7, 0
	s_add_u32 s38, s38, 0x5200000
	s_addc_u32 s39, s39, 0
	s_add_u32 s40, s4, s18
	s_addc_u32 s41, s5, 0
	s_add_u32 s42, s6, s19
	s_addc_u32 s43, s7, 0
	s_add_u32 s42, s42, 0x3100000
	s_addc_u32 s43, s43, 0
	global_load_dwordx2 v[130:131], v2, s[38:39] offset:0
	global_load_dwordx2 v[134:135], v2, s[38:39] offset:512
	global_load_dwordx2 v[138:139], v2, s[38:39] offset:1024
	global_load_dwordx2 v[142:143], v2, s[38:39] offset:1536
	global_load_dwordx4 v[144:147], v1, s[36:37] offset:0 nt
	global_load_dwordx4 v[148:151], v1, s[36:37] offset:1024 nt
	global_load_dwordx4 v[152:155], v1, s[36:37] offset:2048 nt
	global_load_dwordx4 v[156:159], v1, s[36:37] offset:3072 nt
	s_add_u32 s53, s16, 0x1800
	s_lshl_b32 s18, s53, 12
	s_lshl_b32 s19, s53, 11
	s_add_u32 s44, s4, s18
	s_addc_u32 s45, s5, 0
	s_add_u32 s46, s6, s19
	s_addc_u32 s47, s7, 0
	s_add_u32 s46, s46, 0x5200000
	s_addc_u32 s47, s47, 0
	s_add_u32 s48, s4, s18
	s_addc_u32 s49, s5, 0
	s_add_u32 s50, s6, s19
	s_addc_u32 s51, s7, 0
	s_add_u32 s50, s50, 0x3100000
	s_addc_u32 s51, s51, 0
	global_load_dwordx2 v[162:163], v2, s[46:47] offset:0
	global_load_dwordx2 v[166:167], v2, s[46:47] offset:512
	global_load_dwordx2 v[170:171], v2, s[46:47] offset:1024
	global_load_dwordx2 v[174:175], v2, s[46:47] offset:1536
	global_load_dwordx4 v[176:179], v1, s[44:45] offset:0 nt
	global_load_dwordx4 v[180:183], v1, s[44:45] offset:1024 nt
	global_load_dwordx4 v[184:187], v1, s[44:45] offset:2048 nt
	global_load_dwordx4 v[188:191], v1, s[44:45] offset:3072 nt
	s_waitcnt vmcnt(16)
	v_lshlrev_b32_e32 v64, 16, v66
	v_and_b32_e32 v65, 0xffff0000, v66
	v_lshlrev_b32_e32 v66, 16, v67
	v_and_b32_e32 v67, 0xffff0000, v67
	v_lshlrev_b32_e32 v68, 16, v70
	v_and_b32_e32 v69, 0xffff0000, v70
	v_lshlrev_b32_e32 v70, 16, v71
	v_and_b32_e32 v71, 0xffff0000, v71
	v_lshlrev_b32_e32 v72, 16, v74
	v_and_b32_e32 v73, 0xffff0000, v74
	v_lshlrev_b32_e32 v74, 16, v75
	v_and_b32_e32 v75, 0xffff0000, v75
	v_lshlrev_b32_e32 v76, 16, v78
	v_and_b32_e32 v77, 0xffff0000, v78
	v_lshlrev_b32_e32 v78, 16, v79
	v_and_b32_e32 v79, 0xffff0000, v79
	v_lshlrev_b32_e32 v96, 16, v98
	v_and_b32_e32 v97, 0xffff0000, v98
	v_lshlrev_b32_e32 v98, 16, v99
	v_and_b32_e32 v99, 0xffff0000, v99
	v_lshlrev_b32_e32 v100, 16, v102
	v_and_b32_e32 v101, 0xffff0000, v102
	v_lshlrev_b32_e32 v102, 16, v103
	v_and_b32_e32 v103, 0xffff0000, v103
	v_lshlrev_b32_e32 v104, 16, v106
	v_and_b32_e32 v105, 0xffff0000, v106
	v_lshlrev_b32_e32 v106, 16, v107
	v_and_b32_e32 v107, 0xffff0000, v107
	v_lshlrev_b32_e32 v108, 16, v110
	v_and_b32_e32 v109, 0xffff0000, v110
	v_lshlrev_b32_e32 v110, 16, v111
	v_and_b32_e32 v111, 0xffff0000, v111
	v_mul_f32_e32 v10, v64, v64
	v_fmac_f32_e32 v10, v65, v65
	v_fmac_f32_e32 v10, v66, v66
	v_fmac_f32_e32 v10, v67, v67
	v_fmac_f32_e32 v10, v68, v68
	v_fmac_f32_e32 v10, v69, v69
	v_fmac_f32_e32 v10, v70, v70
	v_fmac_f32_e32 v10, v71, v71
	v_fmac_f32_e32 v10, v72, v72
	v_fmac_f32_e32 v10, v73, v73
	v_fmac_f32_e32 v10, v74, v74
	v_fmac_f32_e32 v10, v75, v75
	v_fmac_f32_e32 v10, v76, v76
	v_fmac_f32_e32 v10, v77, v77
	v_fmac_f32_e32 v10, v78, v78
	v_fmac_f32_e32 v10, v79, v79
	v_mul_f32_e32 v11, v96, v96
	v_fmac_f32_e32 v11, v97, v97
	v_fmac_f32_e32 v11, v98, v98
	v_fmac_f32_e32 v11, v99, v99
	v_fmac_f32_e32 v11, v100, v100
	v_fmac_f32_e32 v11, v101, v101
	v_fmac_f32_e32 v11, v102, v102
	v_fmac_f32_e32 v11, v103, v103
	v_fmac_f32_e32 v11, v104, v104
	v_fmac_f32_e32 v11, v105, v105
	v_fmac_f32_e32 v11, v106, v106
	v_fmac_f32_e32 v11, v107, v107
	v_fmac_f32_e32 v11, v108, v108
	v_fmac_f32_e32 v11, v109, v109
	v_fmac_f32_e32 v11, v110, v110
	v_fmac_f32_e32 v11, v111, v111
	ds_bpermute_b32 v12, v4, v10
	ds_bpermute_b32 v13, v4, v11
	s_waitcnt lgkmcnt(0)
	v_add_f32_e32 v10, v10, v12
	v_add_f32_e32 v11, v11, v13
	ds_bpermute_b32 v12, v5, v10
	ds_bpermute_b32 v13, v5, v11
	s_waitcnt lgkmcnt(0)
	v_add_f32_e32 v10, v10, v12
	v_add_f32_e32 v11, v11, v13
	ds_bpermute_b32 v12, v6, v10
	ds_bpermute_b32 v13, v6, v11
	s_waitcnt lgkmcnt(0)
	v_add_f32_e32 v10, v10, v12
	v_add_f32_e32 v11, v11, v13
	ds_bpermute_b32 v12, v7, v10
	ds_bpermute_b32 v13, v7, v11
	s_waitcnt lgkmcnt(0)
	v_add_f32_e32 v10, v10, v12
	v_add_f32_e32 v11, v11, v13
	ds_bpermute_b32 v12, v8, v10
	ds_bpermute_b32 v13, v8, v11
	s_waitcnt lgkmcnt(0)
	v_add_f32_e32 v10, v10, v12
	v_add_f32_e32 v11, v11, v13
	ds_bpermute_b32 v12, v9, v10
	ds_bpermute_b32 v13, v9, v11
	s_waitcnt lgkmcnt(0)
	v_add_f32_e32 v10, v10, v12
	v_add_f32_e32 v11, v11, v13
	v_fma_f32 v14, v10, s17, v3
	v_fma_f32 v15, v11, s17, v3
	v_rsq_f32_e32 v14, v14
	v_rsq_f32_e32 v15, v15
	s_nop 0
	v_mul_f32_e32 v64, v64, v14
	v_mul_f32_e32 v65, v65, v14
	v_mul_f32_e32 v66, v66, v14
	v_mul_f32_e32 v67, v67, v14
	v_mul_f32_e32 v68, v68, v14
	v_mul_f32_e32 v69, v69, v14
	v_mul_f32_e32 v70, v70, v14
	v_mul_f32_e32 v71, v71, v14
	v_mul_f32_e32 v72, v72, v14
	v_mul_f32_e32 v73, v73, v14
	v_mul_f32_e32 v74, v74, v14
	v_mul_f32_e32 v75, v75, v14
	v_mul_f32_e32 v76, v76, v14
	v_mul_f32_e32 v77, v77, v14
	v_mul_f32_e32 v78, v78, v14
	v_mul_f32_e32 v79, v79, v14
	v_fmac_f32_e32 v80, v64, v20
	v_fmac_f32_e32 v81, v65, v21
	v_fmac_f32_e32 v82, v66, v22
	v_fmac_f32_e32 v83, v67, v23
	v_fmac_f32_e32 v84, v68, v24
	v_fmac_f32_e32 v85, v69, v25
	v_fmac_f32_e32 v86, v70, v26
	v_fmac_f32_e32 v87, v71, v27
	v_fmac_f32_e32 v88, v72, v28
	v_fmac_f32_e32 v89, v73, v29
	v_fmac_f32_e32 v90, v74, v30
	v_fmac_f32_e32 v91, v75, v31
	v_fmac_f32_e32 v92, v76, v32
	v_fmac_f32_e32 v93, v77, v33
	v_fmac_f32_e32 v94, v78, v34
	v_fmac_f32_e32 v95, v79, v35
	global_store_dwordx4 v1, v[80:83], s[24:25] offset:0 nt
	global_store_dwordx4 v1, v[84:87], s[24:25] offset:1024 nt
	global_store_dwordx4 v1, v[88:91], s[24:25] offset:2048 nt
	global_store_dwordx4 v1, v[92:95], s[24:25] offset:3072 nt
	v_mul_f32_e32 v96, v96, v15
	v_mul_f32_e32 v97, v97, v15
	v_mul_f32_e32 v98, v98, v15
	v_mul_f32_e32 v99, v99, v15
	v_mul_f32_e32 v100, v100, v15
	v_mul_f32_e32 v101, v101, v15
	v_mul_f32_e32 v102, v102, v15
	v_mul_f32_e32 v103, v103, v15
	v_mul_f32_e32 v104, v104, v15
	v_mul_f32_e32 v105, v105, v15
	v_mul_f32_e32 v106, v106, v15
	v_mul_f32_e32 v107, v107, v15
	v_mul_f32_e32 v108, v108, v15
	v_mul_f32_e32 v109, v109, v15
	v_mul_f32_e32 v110, v110, v15
	v_mul_f32_e32 v111, v111, v15
	v_fmac_f32_e32 v112, v96, v20
	v_fmac_f32_e32 v113, v97, v21
	v_fmac_f32_e32 v114, v98, v22
	v_fmac_f32_e32 v115, v99, v23
	v_fmac_f32_e32 v116, v100, v24
	v_fmac_f32_e32 v117, v101, v25
	v_fmac_f32_e32 v118, v102, v26
	v_fmac_f32_e32 v119, v103, v27
	v_fmac_f32_e32 v120, v104, v28
	v_fmac_f32_e32 v121, v105, v29
	v_fmac_f32_e32 v122, v106, v30
	v_fmac_f32_e32 v123, v107, v31
	v_fmac_f32_e32 v124, v108, v32
	v_fmac_f32_e32 v125, v109, v33
	v_fmac_f32_e32 v126, v110, v34
	v_fmac_f32_e32 v127, v111, v35
	global_store_dwordx4 v1, v[112:115], s[32:33] offset:0 nt
	global_store_dwordx4 v1, v[116:119], s[32:33] offset:1024 nt
	global_store_dwordx4 v1, v[120:123], s[32:33] offset:2048 nt
	global_store_dwordx4 v1, v[124:127], s[32:33] offset:3072 nt
	v_mul_f32_e32 v10, v80, v80
	v_fmac_f32_e32 v10, v81, v81
	v_fmac_f32_e32 v10, v82, v82
	v_fmac_f32_e32 v10, v83, v83
	v_fmac_f32_e32 v10, v84, v84
	v_fmac_f32_e32 v10, v85, v85
	v_fmac_f32_e32 v10, v86, v86
	v_fmac_f32_e32 v10, v87, v87
	v_fmac_f32_e32 v10, v88, v88
	v_fmac_f32_e32 v10, v89, v89
	v_fmac_f32_e32 v10, v90, v90
	v_fmac_f32_e32 v10, v91, v91
	v_fmac_f32_e32 v10, v92, v92
	v_fmac_f32_e32 v10, v93, v93
	v_fmac_f32_e32 v10, v94, v94
	v_fmac_f32_e32 v10, v95, v95
	v_mul_f32_e32 v11, v112, v112
	v_fmac_f32_e32 v11, v113, v113
	v_fmac_f32_e32 v11, v114, v114
	v_fmac_f32_e32 v11, v115, v115
	v_fmac_f32_e32 v11, v116, v116
	v_fmac_f32_e32 v11, v117, v117
	v_fmac_f32_e32 v11, v118, v118
	v_fmac_f32_e32 v11, v119, v119
	v_fmac_f32_e32 v11, v120, v120
	v_fmac_f32_e32 v11, v121, v121
	v_fmac_f32_e32 v11, v122, v122
	v_fmac_f32_e32 v11, v123, v123
	v_fmac_f32_e32 v11, v124, v124
	v_fmac_f32_e32 v11, v125, v125
	v_fmac_f32_e32 v11, v126, v126
	v_fmac_f32_e32 v11, v127, v127
	ds_bpermute_b32 v12, v4, v10
	ds_bpermute_b32 v13, v4, v11
	s_waitcnt lgkmcnt(0)
	v_add_f32_e32 v10, v10, v12
	v_add_f32_e32 v11, v11, v13
	ds_bpermute_b32 v12, v5, v10
	ds_bpermute_b32 v13, v5, v11
	s_waitcnt lgkmcnt(0)
	v_add_f32_e32 v10, v10, v12
	v_add_f32_e32 v11, v11, v13
	ds_bpermute_b32 v12, v6, v10
	ds_bpermute_b32 v13, v6, v11
	s_waitcnt lgkmcnt(0)
	v_add_f32_e32 v10, v10, v12
	v_add_f32_e32 v11, v11, v13
	ds_bpermute_b32 v12, v7, v10
	ds_bpermute_b32 v13, v7, v11
	s_waitcnt lgkmcnt(0)
	v_add_f32_e32 v10, v10, v12
	v_add_f32_e32 v11, v11, v13
	ds_bpermute_b32 v12, v8, v10
	ds_bpermute_b32 v13, v8, v11
	s_waitcnt lgkmcnt(0)
	v_add_f32_e32 v10, v10, v12
	v_add_f32_e32 v11, v11, v13
	ds_bpermute_b32 v12, v9, v10
	ds_bpermute_b32 v13, v9, v11
	s_waitcnt lgkmcnt(0)
	v_add_f32_e32 v10, v10, v12
	v_add_f32_e32 v11, v11, v13
	v_fma_f32 v14, v10, s17, v3
	v_fma_f32 v15, v11, s17, v3
	v_rsq_f32_e32 v14, v14
	v_rsq_f32_e32 v15, v15
	s_nop 0
	v_mul_f32_e32 v64, v80, v14
	v_mul_f32_e32 v65, v81, v14
	v_mul_f32_e32 v66, v82, v14
	v_mul_f32_e32 v67, v83, v14
	v_mul_f32_e32 v68, v84, v14
	v_mul_f32_e32 v69, v85, v14
	v_mul_f32_e32 v70, v86, v14
	v_mul_f32_e32 v71, v87, v14
	v_mul_f32_e32 v72, v88, v14
	v_mul_f32_e32 v73, v89, v14
	v_mul_f32_e32 v74, v90, v14
	v_mul_f32_e32 v75, v91, v14
	v_mul_f32_e32 v76, v92, v14
	v_mul_f32_e32 v77, v93, v14
	v_mul_f32_e32 v78, v94, v14
	v_mul_f32_e32 v79, v95, v14
	v_mul_f32_e32 v64, v64, v36
	v_mul_f32_e32 v65, v65, v37
	v_mul_f32_e32 v66, v66, v38
	v_mul_f32_e32 v67, v67, v39
	v_mul_f32_e32 v68, v68, v40
	v_mul_f32_e32 v69, v69, v41
	v_mul_f32_e32 v70, v70, v42
	v_mul_f32_e32 v71, v71, v43
	v_mul_f32_e32 v72, v72, v44
	v_mul_f32_e32 v73, v73, v45
	v_mul_f32_e32 v74, v74, v46
	v_mul_f32_e32 v75, v75, v47
	v_mul_f32_e32 v76, v76, v48
	v_mul_f32_e32 v77, v77, v49
	v_mul_f32_e32 v78, v78, v50
	v_mul_f32_e32 v79, v79, v51
	v_cvt_pk_bf16_f32 v64, v64, v65
	v_cvt_pk_bf16_f32 v65, v66, v67
	v_cvt_pk_bf16_f32 v68, v68, v69
	v_cvt_pk_bf16_f32 v69, v70, v71
	v_cvt_pk_bf16_f32 v72, v72, v73
	v_cvt_pk_bf16_f32 v73, v74, v75
	v_cvt_pk_bf16_f32 v76, v76, v77
	v_cvt_pk_bf16_f32 v77, v78, v79
	global_store_dwordx2 v2, v[64:65], s[26:27] offset:0
	global_store_dwordx2 v2, v[68:69], s[26:27] offset:512
	global_store_dwordx2 v2, v[72:73], s[26:27] offset:1024
	global_store_dwordx2 v2, v[76:77], s[26:27] offset:1536
	v_mul_f32_e32 v96, v112, v15
	v_mul_f32_e32 v97, v113, v15
	v_mul_f32_e32 v98, v114, v15
	v_mul_f32_e32 v99, v115, v15
	v_mul_f32_e32 v100, v116, v15
	v_mul_f32_e32 v101, v117, v15
	v_mul_f32_e32 v102, v118, v15
	v_mul_f32_e32 v103, v119, v15
	v_mul_f32_e32 v104, v120, v15
	v_mul_f32_e32 v105, v121, v15
	v_mul_f32_e32 v106, v122, v15
	v_mul_f32_e32 v107, v123, v15
	v_mul_f32_e32 v108, v124, v15
	v_mul_f32_e32 v109, v125, v15
	v_mul_f32_e32 v110, v126, v15
	v_mul_f32_e32 v111, v127, v15
	v_mul_f32_e32 v96, v96, v36
	v_mul_f32_e32 v97, v97, v37
	v_mul_f32_e32 v98, v98, v38
	v_mul_f32_e32 v99, v99, v39
	v_mul_f32_e32 v100, v100, v40
	v_mul_f32_e32 v101, v101, v41
	v_mul_f32_e32 v102, v102, v42
	v_mul_f32_e32 v103, v103, v43
	v_mul_f32_e32 v104, v104, v44
	v_mul_f32_e32 v105, v105, v45
	v_mul_f32_e32 v106, v106, v46
	v_mul_f32_e32 v107, v107, v47
	v_mul_f32_e32 v108, v108, v48
	v_mul_f32_e32 v109, v109, v49
	v_mul_f32_e32 v110, v110, v50
	v_mul_f32_e32 v111, v111, v51
	v_cvt_pk_bf16_f32 v96, v96, v97
	v_cvt_pk_bf16_f32 v97, v98, v99
	v_cvt_pk_bf16_f32 v100, v100, v101
	v_cvt_pk_bf16_f32 v101, v102, v103
	v_cvt_pk_bf16_f32 v104, v104, v105
	v_cvt_pk_bf16_f32 v105, v106, v107
	v_cvt_pk_bf16_f32 v108, v108, v109
	v_cvt_pk_bf16_f32 v109, v110, v111
	global_store_dwordx2 v2, v[96:97], s[34:35] offset:0
	global_store_dwordx2 v2, v[100:101], s[34:35] offset:512
	global_store_dwordx2 v2, v[104:105], s[34:35] offset:1024
	global_store_dwordx2 v2, v[108:109], s[34:35] offset:1536
	s_add_u32 s53, s16, 0x2000
	s_lshl_b32 s18, s53, 12
	s_lshl_b32 s19, s53, 11
	s_add_u32 s20, s4, s18
	s_addc_u32 s21, s5, 0
	s_add_u32 s22, s6, s19
	s_addc_u32 s23, s7, 0
	s_add_u32 s22, s22, 0x5200000
	s_addc_u32 s23, s23, 0
	s_add_u32 s24, s4, s18
	s_addc_u32 s25, s5, 0
	s_add_u32 s26, s6, s19
	s_addc_u32 s27, s7, 0
	s_add_u32 s26, s26, 0x3100000
	s_addc_u32 s27, s27, 0
	global_load_dwordx2 v[66:67], v2, s[22:23] offset:0
	global_load_dwordx2 v[70:71], v2, s[22:23] offset:512
	global_load_dwordx2 v[74:75], v2, s[22:23] offset:1024
	global_load_dwordx2 v[78:79], v2, s[22:23] offset:1536
	global_load_dwordx4 v[80:83], v1, s[20:21] offset:0 nt
	global_load_dwordx4 v[84:87], v1, s[20:21] offset:1024 nt
	global_load_dwordx4 v[88:91], v1, s[20:21] offset:2048 nt
	global_load_dwordx4 v[92:95], v1, s[20:21] offset:3072 nt
	s_add_u32 s53, s16, 0x2800
	s_lshl_b32 s18, s53, 12
	s_lshl_b32 s19, s53, 11
	s_add_u32 s28, s4, s18
	s_addc_u32 s29, s5, 0
	s_add_u32 s30, s6, s19
	s_addc_u32 s31, s7, 0
	s_add_u32 s30, s30, 0x5200000
	s_addc_u32 s31, s31, 0
	s_add_u32 s32, s4, s18
	s_addc_u32 s33, s5, 0
	s_add_u32 s34, s6, s19
	s_addc_u32 s35, s7, 0
	s_add_u32 s34, s34, 0x3100000
	s_addc_u32 s35, s35, 0
	global_load_dwordx2 v[98:99], v2, s[30:31] offset:0
	global_load_dwordx2 v[102:103], v2, s[30:31] offset:512
	global_load_dwordx2 v[106:107], v2, s[30:31] offset:1024
	global_load_dwordx2 v[110:111], v2, s[30:31] offset:1536
	global_load_dwordx4 v[112:115], v1, s[28:29] offset:0 nt
	global_load_dwordx4 v[116:119], v1, s[28:29] offset:1024 nt
	global_load_dwordx4 v[120:123], v1, s[28:29] offset:2048 nt
	global_load_dwordx4 v[124:127], v1, s[28:29] offset:3072 nt
	s_waitcnt vmcnt(32)
	v_lshlrev_b32_e32 v128, 16, v130
	v_and_b32_e32 v129, 0xffff0000, v130
	v_lshlrev_b32_e32 v130, 16, v131
	v_and_b32_e32 v131, 0xffff0000, v131
	v_lshlrev_b32_e32 v132, 16, v134
	v_and_b32_e32 v133, 0xffff0000, v134
	v_lshlrev_b32_e32 v134, 16, v135
	v_and_b32_e32 v135, 0xffff0000, v135
	v_lshlrev_b32_e32 v136, 16, v138
	v_and_b32_e32 v137, 0xffff0000, v138
	v_lshlrev_b32_e32 v138, 16, v139
	v_and_b32_e32 v139, 0xffff0000, v139
	v_lshlrev_b32_e32 v140, 16, v142
	v_and_b32_e32 v141, 0xffff0000, v142
	v_lshlrev_b32_e32 v142, 16, v143
	v_and_b32_e32 v143, 0xffff0000, v143
	v_lshlrev_b32_e32 v160, 16, v162
	v_and_b32_e32 v161, 0xffff0000, v162
	v_lshlrev_b32_e32 v162, 16, v163
	v_and_b32_e32 v163, 0xffff0000, v163
	v_lshlrev_b32_e32 v164, 16, v166
	v_and_b32_e32 v165, 0xffff0000, v166
	v_lshlrev_b32_e32 v166, 16, v167
	v_and_b32_e32 v167, 0xffff0000, v167
	v_lshlrev_b32_e32 v168, 16, v170
	v_and_b32_e32 v169, 0xffff0000, v170
	v_lshlrev_b32_e32 v170, 16, v171
	v_and_b32_e32 v171, 0xffff0000, v171
	v_lshlrev_b32_e32 v172, 16, v174
	v_and_b32_e32 v173, 0xffff0000, v174
	v_lshlrev_b32_e32 v174, 16, v175
	v_and_b32_e32 v175, 0xffff0000, v175
	v_mul_f32_e32 v10, v128, v128
	v_fmac_f32_e32 v10, v129, v129
	v_fmac_f32_e32 v10, v130, v130
	v_fmac_f32_e32 v10, v131, v131
	v_fmac_f32_e32 v10, v132, v132
	v_fmac_f32_e32 v10, v133, v133
	v_fmac_f32_e32 v10, v134, v134
	v_fmac_f32_e32 v10, v135, v135
	v_fmac_f32_e32 v10, v136, v136
	v_fmac_f32_e32 v10, v137, v137
	v_fmac_f32_e32 v10, v138, v138
	v_fmac_f32_e32 v10, v139, v139
	v_fmac_f32_e32 v10, v140, v140
	v_fmac_f32_e32 v10, v141, v141
	v_fmac_f32_e32 v10, v142, v142
	v_fmac_f32_e32 v10, v143, v143
	v_mul_f32_e32 v11, v160, v160
	v_fmac_f32_e32 v11, v161, v161
	v_fmac_f32_e32 v11, v162, v162
	v_fmac_f32_e32 v11, v163, v163
	v_fmac_f32_e32 v11, v164, v164
	v_fmac_f32_e32 v11, v165, v165
	v_fmac_f32_e32 v11, v166, v166
	v_fmac_f32_e32 v11, v167, v167
	v_fmac_f32_e32 v11, v168, v168
	v_fmac_f32_e32 v11, v169, v169
	v_fmac_f32_e32 v11, v170, v170
	v_fmac_f32_e32 v11, v171, v171
	v_fmac_f32_e32 v11, v172, v172
	v_fmac_f32_e32 v11, v173, v173
	v_fmac_f32_e32 v11, v174, v174
	v_fmac_f32_e32 v11, v175, v175
	ds_bpermute_b32 v12, v4, v10
	ds_bpermute_b32 v13, v4, v11
	s_waitcnt lgkmcnt(0)
	v_add_f32_e32 v10, v10, v12
	v_add_f32_e32 v11, v11, v13
	ds_bpermute_b32 v12, v5, v10
	ds_bpermute_b32 v13, v5, v11
	s_waitcnt lgkmcnt(0)
	v_add_f32_e32 v10, v10, v12
	v_add_f32_e32 v11, v11, v13
	ds_bpermute_b32 v12, v6, v10
	ds_bpermute_b32 v13, v6, v11
	s_waitcnt lgkmcnt(0)
	v_add_f32_e32 v10, v10, v12
	v_add_f32_e32 v11, v11, v13
	ds_bpermute_b32 v12, v7, v10
	ds_bpermute_b32 v13, v7, v11
	s_waitcnt lgkmcnt(0)
	v_add_f32_e32 v10, v10, v12
	v_add_f32_e32 v11, v11, v13
	ds_bpermute_b32 v12, v8, v10
	ds_bpermute_b32 v13, v8, v11
	s_waitcnt lgkmcnt(0)
	v_add_f32_e32 v10, v10, v12
	v_add_f32_e32 v11, v11, v13
	ds_bpermute_b32 v12, v9, v10
	ds_bpermute_b32 v13, v9, v11
	s_waitcnt lgkmcnt(0)
	v_add_f32_e32 v10, v10, v12
	v_add_f32_e32 v11, v11, v13
	v_fma_f32 v14, v10, s17, v3
	v_fma_f32 v15, v11, s17, v3
	v_rsq_f32_e32 v14, v14
	v_rsq_f32_e32 v15, v15
	s_nop 0
	v_mul_f32_e32 v128, v128, v14
	v_mul_f32_e32 v129, v129, v14
	v_mul_f32_e32 v130, v130, v14
	v_mul_f32_e32 v131, v131, v14
	v_mul_f32_e32 v132, v132, v14
	v_mul_f32_e32 v133, v133, v14
	v_mul_f32_e32 v134, v134, v14
	v_mul_f32_e32 v135, v135, v14
	v_mul_f32_e32 v136, v136, v14
	v_mul_f32_e32 v137, v137, v14
	v_mul_f32_e32 v138, v138, v14
	v_mul_f32_e32 v139, v139, v14
	v_mul_f32_e32 v140, v140, v14
	v_mul_f32_e32 v141, v141, v14
	v_mul_f32_e32 v142, v142, v14
	v_mul_f32_e32 v143, v143, v14
	v_fmac_f32_e32 v144, v128, v20
	v_fmac_f32_e32 v145, v129, v21
	v_fmac_f32_e32 v146, v130, v22
	v_fmac_f32_e32 v147, v131, v23
	v_fmac_f32_e32 v148, v132, v24
	v_fmac_f32_e32 v149, v133, v25
	v_fmac_f32_e32 v150, v134, v26
	v_fmac_f32_e32 v151, v135, v27
	v_fmac_f32_e32 v152, v136, v28
	v_fmac_f32_e32 v153, v137, v29
	v_fmac_f32_e32 v154, v138, v30
	v_fmac_f32_e32 v155, v139, v31
	v_fmac_f32_e32 v156, v140, v32
	v_fmac_f32_e32 v157, v141, v33
	v_fmac_f32_e32 v158, v142, v34
	v_fmac_f32_e32 v159, v143, v35
	global_store_dwordx4 v1, v[144:147], s[40:41] offset:0 nt
	global_store_dwordx4 v1, v[148:151], s[40:41] offset:1024 nt
	global_store_dwordx4 v1, v[152:155], s[40:41] offset:2048 nt
	global_store_dwordx4 v1, v[156:159], s[40:41] offset:3072 nt
	v_mul_f32_e32 v160, v160, v15
	v_mul_f32_e32 v161, v161, v15
	v_mul_f32_e32 v162, v162, v15
	v_mul_f32_e32 v163, v163, v15
	v_mul_f32_e32 v164, v164, v15
	v_mul_f32_e32 v165, v165, v15
	v_mul_f32_e32 v166, v166, v15
	v_mul_f32_e32 v167, v167, v15
	v_mul_f32_e32 v168, v168, v15
	v_mul_f32_e32 v169, v169, v15
	v_mul_f32_e32 v170, v170, v15
	v_mul_f32_e32 v171, v171, v15
	v_mul_f32_e32 v172, v172, v15
	v_mul_f32_e32 v173, v173, v15
	v_mul_f32_e32 v174, v174, v15
	v_mul_f32_e32 v175, v175, v15
	v_fmac_f32_e32 v176, v160, v20
	v_fmac_f32_e32 v177, v161, v21
	v_fmac_f32_e32 v178, v162, v22
	v_fmac_f32_e32 v179, v163, v23
	v_fmac_f32_e32 v180, v164, v24
	v_fmac_f32_e32 v181, v165, v25
	v_fmac_f32_e32 v182, v166, v26
	v_fmac_f32_e32 v183, v167, v27
	v_fmac_f32_e32 v184, v168, v28
	v_fmac_f32_e32 v185, v169, v29
	v_fmac_f32_e32 v186, v170, v30
	v_fmac_f32_e32 v187, v171, v31
	v_fmac_f32_e32 v188, v172, v32
	v_fmac_f32_e32 v189, v173, v33
	v_fmac_f32_e32 v190, v174, v34
	v_fmac_f32_e32 v191, v175, v35
	global_store_dwordx4 v1, v[176:179], s[48:49] offset:0 nt
	global_store_dwordx4 v1, v[180:183], s[48:49] offset:1024 nt
	global_store_dwordx4 v1, v[184:187], s[48:49] offset:2048 nt
	global_store_dwordx4 v1, v[188:191], s[48:49] offset:3072 nt
	v_mul_f32_e32 v10, v144, v144
	v_fmac_f32_e32 v10, v145, v145
	v_fmac_f32_e32 v10, v146, v146
	v_fmac_f32_e32 v10, v147, v147
	v_fmac_f32_e32 v10, v148, v148
	v_fmac_f32_e32 v10, v149, v149
	v_fmac_f32_e32 v10, v150, v150
	v_fmac_f32_e32 v10, v151, v151
	v_fmac_f32_e32 v10, v152, v152
	v_fmac_f32_e32 v10, v153, v153
	v_fmac_f32_e32 v10, v154, v154
	v_fmac_f32_e32 v10, v155, v155
	v_fmac_f32_e32 v10, v156, v156
	v_fmac_f32_e32 v10, v157, v157
	v_fmac_f32_e32 v10, v158, v158
	v_fmac_f32_e32 v10, v159, v159
	v_mul_f32_e32 v11, v176, v176
	v_fmac_f32_e32 v11, v177, v177
	v_fmac_f32_e32 v11, v178, v178
	v_fmac_f32_e32 v11, v179, v179
	v_fmac_f32_e32 v11, v180, v180
	v_fmac_f32_e32 v11, v181, v181
	v_fmac_f32_e32 v11, v182, v182
	v_fmac_f32_e32 v11, v183, v183
	v_fmac_f32_e32 v11, v184, v184
	v_fmac_f32_e32 v11, v185, v185
	v_fmac_f32_e32 v11, v186, v186
	v_fmac_f32_e32 v11, v187, v187
	v_fmac_f32_e32 v11, v188, v188
	v_fmac_f32_e32 v11, v189, v189
	v_fmac_f32_e32 v11, v190, v190
	v_fmac_f32_e32 v11, v191, v191
	ds_bpermute_b32 v12, v4, v10
	ds_bpermute_b32 v13, v4, v11
	s_waitcnt lgkmcnt(0)
	v_add_f32_e32 v10, v10, v12
	v_add_f32_e32 v11, v11, v13
	ds_bpermute_b32 v12, v5, v10
	ds_bpermute_b32 v13, v5, v11
	s_waitcnt lgkmcnt(0)
	v_add_f32_e32 v10, v10, v12
	v_add_f32_e32 v11, v11, v13
	ds_bpermute_b32 v12, v6, v10
	ds_bpermute_b32 v13, v6, v11
	s_waitcnt lgkmcnt(0)
	v_add_f32_e32 v10, v10, v12
	v_add_f32_e32 v11, v11, v13
	ds_bpermute_b32 v12, v7, v10
	ds_bpermute_b32 v13, v7, v11
	s_waitcnt lgkmcnt(0)
	v_add_f32_e32 v10, v10, v12
	v_add_f32_e32 v11, v11, v13
	ds_bpermute_b32 v12, v8, v10
	ds_bpermute_b32 v13, v8, v11
	s_waitcnt lgkmcnt(0)
	v_add_f32_e32 v10, v10, v12
	v_add_f32_e32 v11, v11, v13
	ds_bpermute_b32 v12, v9, v10
	ds_bpermute_b32 v13, v9, v11
	s_waitcnt lgkmcnt(0)
	v_add_f32_e32 v10, v10, v12
	v_add_f32_e32 v11, v11, v13
	v_fma_f32 v14, v10, s17, v3
	v_fma_f32 v15, v11, s17, v3
	v_rsq_f32_e32 v14, v14
	v_rsq_f32_e32 v15, v15
	s_nop 0
	v_mul_f32_e32 v128, v144, v14
	v_mul_f32_e32 v129, v145, v14
	v_mul_f32_e32 v130, v146, v14
	v_mul_f32_e32 v131, v147, v14
	v_mul_f32_e32 v132, v148, v14
	v_mul_f32_e32 v133, v149, v14
	v_mul_f32_e32 v134, v150, v14
	v_mul_f32_e32 v135, v151, v14
	v_mul_f32_e32 v136, v152, v14
	v_mul_f32_e32 v137, v153, v14
	v_mul_f32_e32 v138, v154, v14
	v_mul_f32_e32 v139, v155, v14
	v_mul_f32_e32 v140, v156, v14
	v_mul_f32_e32 v141, v157, v14
	v_mul_f32_e32 v142, v158, v14
	v_mul_f32_e32 v143, v159, v14
	v_mul_f32_e32 v128, v128, v36
	v_mul_f32_e32 v129, v129, v37
	v_mul_f32_e32 v130, v130, v38
	v_mul_f32_e32 v131, v131, v39
	v_mul_f32_e32 v132, v132, v40
	v_mul_f32_e32 v133, v133, v41
	v_mul_f32_e32 v134, v134, v42
	v_mul_f32_e32 v135, v135, v43
	v_mul_f32_e32 v136, v136, v44
	v_mul_f32_e32 v137, v137, v45
	v_mul_f32_e32 v138, v138, v46
	v_mul_f32_e32 v139, v139, v47
	v_mul_f32_e32 v140, v140, v48
	v_mul_f32_e32 v141, v141, v49
	v_mul_f32_e32 v142, v142, v50
	v_mul_f32_e32 v143, v143, v51
	v_cvt_pk_bf16_f32 v128, v128, v129
	v_cvt_pk_bf16_f32 v129, v130, v131
	v_cvt_pk_bf16_f32 v132, v132, v133
	v_cvt_pk_bf16_f32 v133, v134, v135
	v_cvt_pk_bf16_f32 v136, v136, v137
	v_cvt_pk_bf16_f32 v137, v138, v139
	v_cvt_pk_bf16_f32 v140, v140, v141
	v_cvt_pk_bf16_f32 v141, v142, v143
	global_store_dwordx2 v2, v[128:129], s[42:43] offset:0
	global_store_dwordx2 v2, v[132:133], s[42:43] offset:512
	global_store_dwordx2 v2, v[136:137], s[42:43] offset:1024
	global_store_dwordx2 v2, v[140:141], s[42:43] offset:1536
	v_mul_f32_e32 v160, v176, v15
	v_mul_f32_e32 v161, v177, v15
	v_mul_f32_e32 v162, v178, v15
	v_mul_f32_e32 v163, v179, v15
	v_mul_f32_e32 v164, v180, v15
	v_mul_f32_e32 v165, v181, v15
	v_mul_f32_e32 v166, v182, v15
	v_mul_f32_e32 v167, v183, v15
	v_mul_f32_e32 v168, v184, v15
	v_mul_f32_e32 v169, v185, v15
	v_mul_f32_e32 v170, v186, v15
	v_mul_f32_e32 v171, v187, v15
	v_mul_f32_e32 v172, v188, v15
	v_mul_f32_e32 v173, v189, v15
	v_mul_f32_e32 v174, v190, v15
	v_mul_f32_e32 v175, v191, v15
	v_mul_f32_e32 v160, v160, v36
	v_mul_f32_e32 v161, v161, v37
	v_mul_f32_e32 v162, v162, v38
	v_mul_f32_e32 v163, v163, v39
	v_mul_f32_e32 v164, v164, v40
	v_mul_f32_e32 v165, v165, v41
	v_mul_f32_e32 v166, v166, v42
	v_mul_f32_e32 v167, v167, v43
	v_mul_f32_e32 v168, v168, v44
	v_mul_f32_e32 v169, v169, v45
	v_mul_f32_e32 v170, v170, v46
	v_mul_f32_e32 v171, v171, v47
	v_mul_f32_e32 v172, v172, v48
	v_mul_f32_e32 v173, v173, v49
	v_mul_f32_e32 v174, v174, v50
	v_mul_f32_e32 v175, v175, v51
	v_cvt_pk_bf16_f32 v160, v160, v161
	v_cvt_pk_bf16_f32 v161, v162, v163
	v_cvt_pk_bf16_f32 v164, v164, v165
	v_cvt_pk_bf16_f32 v165, v166, v167
	v_cvt_pk_bf16_f32 v168, v168, v169
	v_cvt_pk_bf16_f32 v169, v170, v171
	v_cvt_pk_bf16_f32 v172, v172, v173
	v_cvt_pk_bf16_f32 v173, v174, v175
	global_store_dwordx2 v2, v[160:161], s[50:51] offset:0
	global_store_dwordx2 v2, v[164:165], s[50:51] offset:512
	global_store_dwordx2 v2, v[168:169], s[50:51] offset:1024
	global_store_dwordx2 v2, v[172:173], s[50:51] offset:1536
	s_add_u32 s53, s16, 0x3000
	s_lshl_b32 s18, s53, 12
	s_lshl_b32 s19, s53, 11
	s_add_u32 s36, s4, s18
	s_addc_u32 s37, s5, 0
	s_add_u32 s38, s6, s19
	s_addc_u32 s39, s7, 0
	s_add_u32 s38, s38, 0x5200000
	s_addc_u32 s39, s39, 0
	s_add_u32 s40, s4, s18
	s_addc_u32 s41, s5, 0
	s_add_u32 s42, s6, s19
	s_addc_u32 s43, s7, 0
	s_add_u32 s42, s42, 0x3100000
	s_addc_u32 s43, s43, 0
	global_load_dwordx2 v[130:131], v2, s[38:39] offset:0
	global_load_dwordx2 v[134:135], v2, s[38:39] offset:512
	global_load_dwordx2 v[138:139], v2, s[38:39] offset:1024
	global_load_dwordx2 v[142:143], v2, s[38:39] offset:1536
	global_load_dwordx4 v[144:147], v1, s[36:37] offset:0 nt
	global_load_dwordx4 v[148:151], v1, s[36:37] offset:1024 nt
	global_load_dwordx4 v[152:155], v1, s[36:37] offset:2048 nt
	global_load_dwordx4 v[156:159], v1, s[36:37] offset:3072 nt
	s_add_u32 s53, s16, 0x3800
	s_lshl_b32 s18, s53, 12
	s_lshl_b32 s19, s53, 11
	s_add_u32 s44, s4, s18
	s_addc_u32 s45, s5, 0
	s_add_u32 s46, s6, s19
	s_addc_u32 s47, s7, 0
	s_add_u32 s46, s46, 0x5200000
	s_addc_u32 s47, s47, 0
	s_add_u32 s48, s4, s18
	s_addc_u32 s49, s5, 0
	s_add_u32 s50, s6, s19
	s_addc_u32 s51, s7, 0
	s_add_u32 s50, s50, 0x3100000
	s_addc_u32 s51, s51, 0
	global_load_dwordx2 v[162:163], v2, s[46:47] offset:0
	global_load_dwordx2 v[166:167], v2, s[46:47] offset:512
	global_load_dwordx2 v[170:171], v2, s[46:47] offset:1024
	global_load_dwordx2 v[174:175], v2, s[46:47] offset:1536
	global_load_dwordx4 v[176:179], v1, s[44:45] offset:0 nt
	global_load_dwordx4 v[180:183], v1, s[44:45] offset:1024 nt
	global_load_dwordx4 v[184:187], v1, s[44:45] offset:2048 nt
	global_load_dwordx4 v[188:191], v1, s[44:45] offset:3072 nt
	s_waitcnt vmcnt(32)
	v_lshlrev_b32_e32 v64, 16, v66
	v_and_b32_e32 v65, 0xffff0000, v66
	v_lshlrev_b32_e32 v66, 16, v67
	v_and_b32_e32 v67, 0xffff0000, v67
	v_lshlrev_b32_e32 v68, 16, v70
	v_and_b32_e32 v69, 0xffff0000, v70
	v_lshlrev_b32_e32 v70, 16, v71
	v_and_b32_e32 v71, 0xffff0000, v71
	v_lshlrev_b32_e32 v72, 16, v74
	v_and_b32_e32 v73, 0xffff0000, v74
	v_lshlrev_b32_e32 v74, 16, v75
	v_and_b32_e32 v75, 0xffff0000, v75
	v_lshlrev_b32_e32 v76, 16, v78
	v_and_b32_e32 v77, 0xffff0000, v78
	v_lshlrev_b32_e32 v78, 16, v79
	v_and_b32_e32 v79, 0xffff0000, v79
	v_lshlrev_b32_e32 v96, 16, v98
	v_and_b32_e32 v97, 0xffff0000, v98
	v_lshlrev_b32_e32 v98, 16, v99
	v_and_b32_e32 v99, 0xffff0000, v99
	v_lshlrev_b32_e32 v100, 16, v102
	v_and_b32_e32 v101, 0xffff0000, v102
	v_lshlrev_b32_e32 v102, 16, v103
	v_and_b32_e32 v103, 0xffff0000, v103
	v_lshlrev_b32_e32 v104, 16, v106
	v_and_b32_e32 v105, 0xffff0000, v106
	v_lshlrev_b32_e32 v106, 16, v107
	v_and_b32_e32 v107, 0xffff0000, v107
	v_lshlrev_b32_e32 v108, 16, v110
	v_and_b32_e32 v109, 0xffff0000, v110
	v_lshlrev_b32_e32 v110, 16, v111
	v_and_b32_e32 v111, 0xffff0000, v111
	v_mul_f32_e32 v10, v64, v64
	v_fmac_f32_e32 v10, v65, v65
	v_fmac_f32_e32 v10, v66, v66
	v_fmac_f32_e32 v10, v67, v67
	v_fmac_f32_e32 v10, v68, v68
	v_fmac_f32_e32 v10, v69, v69
	v_fmac_f32_e32 v10, v70, v70
	v_fmac_f32_e32 v10, v71, v71
	v_fmac_f32_e32 v10, v72, v72
	v_fmac_f32_e32 v10, v73, v73
	v_fmac_f32_e32 v10, v74, v74
	v_fmac_f32_e32 v10, v75, v75
	v_fmac_f32_e32 v10, v76, v76
	v_fmac_f32_e32 v10, v77, v77
	v_fmac_f32_e32 v10, v78, v78
	v_fmac_f32_e32 v10, v79, v79
	v_mul_f32_e32 v11, v96, v96
	v_fmac_f32_e32 v11, v97, v97
	v_fmac_f32_e32 v11, v98, v98
	v_fmac_f32_e32 v11, v99, v99
	v_fmac_f32_e32 v11, v100, v100
	v_fmac_f32_e32 v11, v101, v101
	v_fmac_f32_e32 v11, v102, v102
	v_fmac_f32_e32 v11, v103, v103
	v_fmac_f32_e32 v11, v104, v104
	v_fmac_f32_e32 v11, v105, v105
	v_fmac_f32_e32 v11, v106, v106
	v_fmac_f32_e32 v11, v107, v107
	v_fmac_f32_e32 v11, v108, v108
	v_fmac_f32_e32 v11, v109, v109
	v_fmac_f32_e32 v11, v110, v110
	v_fmac_f32_e32 v11, v111, v111
	ds_bpermute_b32 v12, v4, v10
	ds_bpermute_b32 v13, v4, v11
	s_waitcnt lgkmcnt(0)
	v_add_f32_e32 v10, v10, v12
	v_add_f32_e32 v11, v11, v13
	ds_bpermute_b32 v12, v5, v10
	ds_bpermute_b32 v13, v5, v11
	s_waitcnt lgkmcnt(0)
	v_add_f32_e32 v10, v10, v12
	v_add_f32_e32 v11, v11, v13
	ds_bpermute_b32 v12, v6, v10
	ds_bpermute_b32 v13, v6, v11
	s_waitcnt lgkmcnt(0)
	v_add_f32_e32 v10, v10, v12
	v_add_f32_e32 v11, v11, v13
	ds_bpermute_b32 v12, v7, v10
	ds_bpermute_b32 v13, v7, v11
	s_waitcnt lgkmcnt(0)
	v_add_f32_e32 v10, v10, v12
	v_add_f32_e32 v11, v11, v13
	ds_bpermute_b32 v12, v8, v10
	ds_bpermute_b32 v13, v8, v11
	s_waitcnt lgkmcnt(0)
	v_add_f32_e32 v10, v10, v12
	v_add_f32_e32 v11, v11, v13
	ds_bpermute_b32 v12, v9, v10
	ds_bpermute_b32 v13, v9, v11
	s_waitcnt lgkmcnt(0)
	v_add_f32_e32 v10, v10, v12
	v_add_f32_e32 v11, v11, v13
	v_fma_f32 v14, v10, s17, v3
	v_fma_f32 v15, v11, s17, v3
	v_rsq_f32_e32 v14, v14
	v_rsq_f32_e32 v15, v15
	s_nop 0
	v_mul_f32_e32 v64, v64, v14
	v_mul_f32_e32 v65, v65, v14
	v_mul_f32_e32 v66, v66, v14
	v_mul_f32_e32 v67, v67, v14
	v_mul_f32_e32 v68, v68, v14
	v_mul_f32_e32 v69, v69, v14
	v_mul_f32_e32 v70, v70, v14
	v_mul_f32_e32 v71, v71, v14
	v_mul_f32_e32 v72, v72, v14
	v_mul_f32_e32 v73, v73, v14
	v_mul_f32_e32 v74, v74, v14
	v_mul_f32_e32 v75, v75, v14
	v_mul_f32_e32 v76, v76, v14
	v_mul_f32_e32 v77, v77, v14
	v_mul_f32_e32 v78, v78, v14
	v_mul_f32_e32 v79, v79, v14
	v_fmac_f32_e32 v80, v64, v20
	v_fmac_f32_e32 v81, v65, v21
	v_fmac_f32_e32 v82, v66, v22
	v_fmac_f32_e32 v83, v67, v23
	v_fmac_f32_e32 v84, v68, v24
	v_fmac_f32_e32 v85, v69, v25
	v_fmac_f32_e32 v86, v70, v26
	v_fmac_f32_e32 v87, v71, v27
	v_fmac_f32_e32 v88, v72, v28
	v_fmac_f32_e32 v89, v73, v29
	v_fmac_f32_e32 v90, v74, v30
	v_fmac_f32_e32 v91, v75, v31
	v_fmac_f32_e32 v92, v76, v32
	v_fmac_f32_e32 v93, v77, v33
	v_fmac_f32_e32 v94, v78, v34
	v_fmac_f32_e32 v95, v79, v35
	global_store_dwordx4 v1, v[80:83], s[24:25] offset:0 nt
	global_store_dwordx4 v1, v[84:87], s[24:25] offset:1024 nt
	global_store_dwordx4 v1, v[88:91], s[24:25] offset:2048 nt
	global_store_dwordx4 v1, v[92:95], s[24:25] offset:3072 nt
	v_mul_f32_e32 v96, v96, v15
	v_mul_f32_e32 v97, v97, v15
	v_mul_f32_e32 v98, v98, v15
	v_mul_f32_e32 v99, v99, v15
	v_mul_f32_e32 v100, v100, v15
	v_mul_f32_e32 v101, v101, v15
	v_mul_f32_e32 v102, v102, v15
	v_mul_f32_e32 v103, v103, v15
	v_mul_f32_e32 v104, v104, v15
	v_mul_f32_e32 v105, v105, v15
	v_mul_f32_e32 v106, v106, v15
	v_mul_f32_e32 v107, v107, v15
	v_mul_f32_e32 v108, v108, v15
	v_mul_f32_e32 v109, v109, v15
	v_mul_f32_e32 v110, v110, v15
	v_mul_f32_e32 v111, v111, v15
	v_fmac_f32_e32 v112, v96, v20
	v_fmac_f32_e32 v113, v97, v21
	v_fmac_f32_e32 v114, v98, v22
	v_fmac_f32_e32 v115, v99, v23
	v_fmac_f32_e32 v116, v100, v24
	v_fmac_f32_e32 v117, v101, v25
	v_fmac_f32_e32 v118, v102, v26
	v_fmac_f32_e32 v119, v103, v27
	v_fmac_f32_e32 v120, v104, v28
	v_fmac_f32_e32 v121, v105, v29
	v_fmac_f32_e32 v122, v106, v30
	v_fmac_f32_e32 v123, v107, v31
	v_fmac_f32_e32 v124, v108, v32
	v_fmac_f32_e32 v125, v109, v33
	v_fmac_f32_e32 v126, v110, v34
	v_fmac_f32_e32 v127, v111, v35
	global_store_dwordx4 v1, v[112:115], s[32:33] offset:0 nt
	global_store_dwordx4 v1, v[116:119], s[32:33] offset:1024 nt
	global_store_dwordx4 v1, v[120:123], s[32:33] offset:2048 nt
	global_store_dwordx4 v1, v[124:127], s[32:33] offset:3072 nt
	v_mul_f32_e32 v10, v80, v80
	v_fmac_f32_e32 v10, v81, v81
	v_fmac_f32_e32 v10, v82, v82
	v_fmac_f32_e32 v10, v83, v83
	v_fmac_f32_e32 v10, v84, v84
	v_fmac_f32_e32 v10, v85, v85
	v_fmac_f32_e32 v10, v86, v86
	v_fmac_f32_e32 v10, v87, v87
	v_fmac_f32_e32 v10, v88, v88
	v_fmac_f32_e32 v10, v89, v89
	v_fmac_f32_e32 v10, v90, v90
	v_fmac_f32_e32 v10, v91, v91
	v_fmac_f32_e32 v10, v92, v92
	v_fmac_f32_e32 v10, v93, v93
	v_fmac_f32_e32 v10, v94, v94
	v_fmac_f32_e32 v10, v95, v95
	v_mul_f32_e32 v11, v112, v112
	v_fmac_f32_e32 v11, v113, v113
	v_fmac_f32_e32 v11, v114, v114
	v_fmac_f32_e32 v11, v115, v115
	v_fmac_f32_e32 v11, v116, v116
	v_fmac_f32_e32 v11, v117, v117
	v_fmac_f32_e32 v11, v118, v118
	v_fmac_f32_e32 v11, v119, v119
	v_fmac_f32_e32 v11, v120, v120
	v_fmac_f32_e32 v11, v121, v121
	v_fmac_f32_e32 v11, v122, v122
	v_fmac_f32_e32 v11, v123, v123
	v_fmac_f32_e32 v11, v124, v124
	v_fmac_f32_e32 v11, v125, v125
	v_fmac_f32_e32 v11, v126, v126
	v_fmac_f32_e32 v11, v127, v127
	ds_bpermute_b32 v12, v4, v10
	ds_bpermute_b32 v13, v4, v11
	s_waitcnt lgkmcnt(0)
	v_add_f32_e32 v10, v10, v12
	v_add_f32_e32 v11, v11, v13
	ds_bpermute_b32 v12, v5, v10
	ds_bpermute_b32 v13, v5, v11
	s_waitcnt lgkmcnt(0)
	v_add_f32_e32 v10, v10, v12
	v_add_f32_e32 v11, v11, v13
	ds_bpermute_b32 v12, v6, v10
	ds_bpermute_b32 v13, v6, v11
	s_waitcnt lgkmcnt(0)
	v_add_f32_e32 v10, v10, v12
	v_add_f32_e32 v11, v11, v13
	ds_bpermute_b32 v12, v7, v10
	ds_bpermute_b32 v13, v7, v11
	s_waitcnt lgkmcnt(0)
	v_add_f32_e32 v10, v10, v12
	v_add_f32_e32 v11, v11, v13
	ds_bpermute_b32 v12, v8, v10
	ds_bpermute_b32 v13, v8, v11
	s_waitcnt lgkmcnt(0)
	v_add_f32_e32 v10, v10, v12
	v_add_f32_e32 v11, v11, v13
	ds_bpermute_b32 v12, v9, v10
	ds_bpermute_b32 v13, v9, v11
	s_waitcnt lgkmcnt(0)
	v_add_f32_e32 v10, v10, v12
	v_add_f32_e32 v11, v11, v13
	v_fma_f32 v14, v10, s17, v3
	v_fma_f32 v15, v11, s17, v3
	v_rsq_f32_e32 v14, v14
	v_rsq_f32_e32 v15, v15
	s_nop 0
	v_mul_f32_e32 v64, v80, v14
	v_mul_f32_e32 v65, v81, v14
	v_mul_f32_e32 v66, v82, v14
	v_mul_f32_e32 v67, v83, v14
	v_mul_f32_e32 v68, v84, v14
	v_mul_f32_e32 v69, v85, v14
	v_mul_f32_e32 v70, v86, v14
	v_mul_f32_e32 v71, v87, v14
	v_mul_f32_e32 v72, v88, v14
	v_mul_f32_e32 v73, v89, v14
	v_mul_f32_e32 v74, v90, v14
	v_mul_f32_e32 v75, v91, v14
	v_mul_f32_e32 v76, v92, v14
	v_mul_f32_e32 v77, v93, v14
	v_mul_f32_e32 v78, v94, v14
	v_mul_f32_e32 v79, v95, v14
	v_mul_f32_e32 v64, v64, v36
	v_mul_f32_e32 v65, v65, v37
	v_mul_f32_e32 v66, v66, v38
	v_mul_f32_e32 v67, v67, v39
	v_mul_f32_e32 v68, v68, v40
	v_mul_f32_e32 v69, v69, v41
	v_mul_f32_e32 v70, v70, v42
	v_mul_f32_e32 v71, v71, v43
	v_mul_f32_e32 v72, v72, v44
	v_mul_f32_e32 v73, v73, v45
	v_mul_f32_e32 v74, v74, v46
	v_mul_f32_e32 v75, v75, v47
	v_mul_f32_e32 v76, v76, v48
	v_mul_f32_e32 v77, v77, v49
	v_mul_f32_e32 v78, v78, v50
	v_mul_f32_e32 v79, v79, v51
	v_cvt_pk_bf16_f32 v64, v64, v65
	v_cvt_pk_bf16_f32 v65, v66, v67
	v_cvt_pk_bf16_f32 v68, v68, v69
	v_cvt_pk_bf16_f32 v69, v70, v71
	v_cvt_pk_bf16_f32 v72, v72, v73
	v_cvt_pk_bf16_f32 v73, v74, v75
	v_cvt_pk_bf16_f32 v76, v76, v77
	v_cvt_pk_bf16_f32 v77, v78, v79
	global_store_dwordx2 v2, v[64:65], s[26:27] offset:0
	global_store_dwordx2 v2, v[68:69], s[26:27] offset:512
	global_store_dwordx2 v2, v[72:73], s[26:27] offset:1024
	global_store_dwordx2 v2, v[76:77], s[26:27] offset:1536
	v_mul_f32_e32 v96, v112, v15
	v_mul_f32_e32 v97, v113, v15
	v_mul_f32_e32 v98, v114, v15
	v_mul_f32_e32 v99, v115, v15
	v_mul_f32_e32 v100, v116, v15
	v_mul_f32_e32 v101, v117, v15
	v_mul_f32_e32 v102, v118, v15
	v_mul_f32_e32 v103, v119, v15
	v_mul_f32_e32 v104, v120, v15
	v_mul_f32_e32 v105, v121, v15
	v_mul_f32_e32 v106, v122, v15
	v_mul_f32_e32 v107, v123, v15
	v_mul_f32_e32 v108, v124, v15
	v_mul_f32_e32 v109, v125, v15
	v_mul_f32_e32 v110, v126, v15
	v_mul_f32_e32 v111, v127, v15
	v_mul_f32_e32 v96, v96, v36
	v_mul_f32_e32 v97, v97, v37
	v_mul_f32_e32 v98, v98, v38
	v_mul_f32_e32 v99, v99, v39
	v_mul_f32_e32 v100, v100, v40
	v_mul_f32_e32 v101, v101, v41
	v_mul_f32_e32 v102, v102, v42
	v_mul_f32_e32 v103, v103, v43
	v_mul_f32_e32 v104, v104, v44
	v_mul_f32_e32 v105, v105, v45
	v_mul_f32_e32 v106, v106, v46
	v_mul_f32_e32 v107, v107, v47
	v_mul_f32_e32 v108, v108, v48
	v_mul_f32_e32 v109, v109, v49
	v_mul_f32_e32 v110, v110, v50
	v_mul_f32_e32 v111, v111, v51
	v_cvt_pk_bf16_f32 v96, v96, v97
	v_cvt_pk_bf16_f32 v97, v98, v99
	v_cvt_pk_bf16_f32 v100, v100, v101
	v_cvt_pk_bf16_f32 v101, v102, v103
	v_cvt_pk_bf16_f32 v104, v104, v105
	v_cvt_pk_bf16_f32 v105, v106, v107
	v_cvt_pk_bf16_f32 v108, v108, v109
	v_cvt_pk_bf16_f32 v109, v110, v111
	global_store_dwordx2 v2, v[96:97], s[34:35] offset:0
	global_store_dwordx2 v2, v[100:101], s[34:35] offset:512
	global_store_dwordx2 v2, v[104:105], s[34:35] offset:1024
	global_store_dwordx2 v2, v[108:109], s[34:35] offset:1536
	s_waitcnt vmcnt(16)
	v_lshlrev_b32_e32 v128, 16, v130
	v_and_b32_e32 v129, 0xffff0000, v130
	v_lshlrev_b32_e32 v130, 16, v131
	v_and_b32_e32 v131, 0xffff0000, v131
	v_lshlrev_b32_e32 v132, 16, v134
	v_and_b32_e32 v133, 0xffff0000, v134
	v_lshlrev_b32_e32 v134, 16, v135
	v_and_b32_e32 v135, 0xffff0000, v135
	v_lshlrev_b32_e32 v136, 16, v138
	v_and_b32_e32 v137, 0xffff0000, v138
	v_lshlrev_b32_e32 v138, 16, v139
	v_and_b32_e32 v139, 0xffff0000, v139
	v_lshlrev_b32_e32 v140, 16, v142
	v_and_b32_e32 v141, 0xffff0000, v142
	v_lshlrev_b32_e32 v142, 16, v143
	v_and_b32_e32 v143, 0xffff0000, v143
	v_lshlrev_b32_e32 v160, 16, v162
	v_and_b32_e32 v161, 0xffff0000, v162
	v_lshlrev_b32_e32 v162, 16, v163
	v_and_b32_e32 v163, 0xffff0000, v163
	v_lshlrev_b32_e32 v164, 16, v166
	v_and_b32_e32 v165, 0xffff0000, v166
	v_lshlrev_b32_e32 v166, 16, v167
	v_and_b32_e32 v167, 0xffff0000, v167
	v_lshlrev_b32_e32 v168, 16, v170
	v_and_b32_e32 v169, 0xffff0000, v170
	v_lshlrev_b32_e32 v170, 16, v171
	v_and_b32_e32 v171, 0xffff0000, v171
	v_lshlrev_b32_e32 v172, 16, v174
	v_and_b32_e32 v173, 0xffff0000, v174
	v_lshlrev_b32_e32 v174, 16, v175
	v_and_b32_e32 v175, 0xffff0000, v175
	v_mul_f32_e32 v10, v128, v128
	v_fmac_f32_e32 v10, v129, v129
	v_fmac_f32_e32 v10, v130, v130
	v_fmac_f32_e32 v10, v131, v131
	v_fmac_f32_e32 v10, v132, v132
	v_fmac_f32_e32 v10, v133, v133
	v_fmac_f32_e32 v10, v134, v134
	v_fmac_f32_e32 v10, v135, v135
	v_fmac_f32_e32 v10, v136, v136
	v_fmac_f32_e32 v10, v137, v137
	v_fmac_f32_e32 v10, v138, v138
	v_fmac_f32_e32 v10, v139, v139
	v_fmac_f32_e32 v10, v140, v140
	v_fmac_f32_e32 v10, v141, v141
	v_fmac_f32_e32 v10, v142, v142
	v_fmac_f32_e32 v10, v143, v143
	v_mul_f32_e32 v11, v160, v160
	v_fmac_f32_e32 v11, v161, v161
	v_fmac_f32_e32 v11, v162, v162
	v_fmac_f32_e32 v11, v163, v163
	v_fmac_f32_e32 v11, v164, v164
	v_fmac_f32_e32 v11, v165, v165
	v_fmac_f32_e32 v11, v166, v166
	v_fmac_f32_e32 v11, v167, v167
	v_fmac_f32_e32 v11, v168, v168
	v_fmac_f32_e32 v11, v169, v169
	v_fmac_f32_e32 v11, v170, v170
	v_fmac_f32_e32 v11, v171, v171
	v_fmac_f32_e32 v11, v172, v172
	v_fmac_f32_e32 v11, v173, v173
	v_fmac_f32_e32 v11, v174, v174
	v_fmac_f32_e32 v11, v175, v175
	ds_bpermute_b32 v12, v4, v10
	ds_bpermute_b32 v13, v4, v11
	s_waitcnt lgkmcnt(0)
	v_add_f32_e32 v10, v10, v12
	v_add_f32_e32 v11, v11, v13
	ds_bpermute_b32 v12, v5, v10
	ds_bpermute_b32 v13, v5, v11
	s_waitcnt lgkmcnt(0)
	v_add_f32_e32 v10, v10, v12
	v_add_f32_e32 v11, v11, v13
	ds_bpermute_b32 v12, v6, v10
	ds_bpermute_b32 v13, v6, v11
	s_waitcnt lgkmcnt(0)
	v_add_f32_e32 v10, v10, v12
	v_add_f32_e32 v11, v11, v13
	ds_bpermute_b32 v12, v7, v10
	ds_bpermute_b32 v13, v7, v11
	s_waitcnt lgkmcnt(0)
	v_add_f32_e32 v10, v10, v12
	v_add_f32_e32 v11, v11, v13
	ds_bpermute_b32 v12, v8, v10
	ds_bpermute_b32 v13, v8, v11
	s_waitcnt lgkmcnt(0)
	v_add_f32_e32 v10, v10, v12
	v_add_f32_e32 v11, v11, v13
	ds_bpermute_b32 v12, v9, v10
	ds_bpermute_b32 v13, v9, v11
	s_waitcnt lgkmcnt(0)
	v_add_f32_e32 v10, v10, v12
	v_add_f32_e32 v11, v11, v13
	v_fma_f32 v14, v10, s17, v3
	v_fma_f32 v15, v11, s17, v3
	v_rsq_f32_e32 v14, v14
	v_rsq_f32_e32 v15, v15
	s_nop 0
	v_mul_f32_e32 v128, v128, v14
	v_mul_f32_e32 v129, v129, v14
	v_mul_f32_e32 v130, v130, v14
	v_mul_f32_e32 v131, v131, v14
	v_mul_f32_e32 v132, v132, v14
	v_mul_f32_e32 v133, v133, v14
	v_mul_f32_e32 v134, v134, v14
	v_mul_f32_e32 v135, v135, v14
	v_mul_f32_e32 v136, v136, v14
	v_mul_f32_e32 v137, v137, v14
	v_mul_f32_e32 v138, v138, v14
	v_mul_f32_e32 v139, v139, v14
	v_mul_f32_e32 v140, v140, v14
	v_mul_f32_e32 v141, v141, v14
	v_mul_f32_e32 v142, v142, v14
	v_mul_f32_e32 v143, v143, v14
	v_fmac_f32_e32 v144, v128, v20
	v_fmac_f32_e32 v145, v129, v21
	v_fmac_f32_e32 v146, v130, v22
	v_fmac_f32_e32 v147, v131, v23
	v_fmac_f32_e32 v148, v132, v24
	v_fmac_f32_e32 v149, v133, v25
	v_fmac_f32_e32 v150, v134, v26
	v_fmac_f32_e32 v151, v135, v27
	v_fmac_f32_e32 v152, v136, v28
	v_fmac_f32_e32 v153, v137, v29
	v_fmac_f32_e32 v154, v138, v30
	v_fmac_f32_e32 v155, v139, v31
	v_fmac_f32_e32 v156, v140, v32
	v_fmac_f32_e32 v157, v141, v33
	v_fmac_f32_e32 v158, v142, v34
	v_fmac_f32_e32 v159, v143, v35
	global_store_dwordx4 v1, v[144:147], s[40:41] offset:0 nt
	global_store_dwordx4 v1, v[148:151], s[40:41] offset:1024 nt
	global_store_dwordx4 v1, v[152:155], s[40:41] offset:2048 nt
	global_store_dwordx4 v1, v[156:159], s[40:41] offset:3072 nt
	v_mul_f32_e32 v160, v160, v15
	v_mul_f32_e32 v161, v161, v15
	v_mul_f32_e32 v162, v162, v15
	v_mul_f32_e32 v163, v163, v15
	v_mul_f32_e32 v164, v164, v15
	v_mul_f32_e32 v165, v165, v15
	v_mul_f32_e32 v166, v166, v15
	v_mul_f32_e32 v167, v167, v15
	v_mul_f32_e32 v168, v168, v15
	v_mul_f32_e32 v169, v169, v15
	v_mul_f32_e32 v170, v170, v15
	v_mul_f32_e32 v171, v171, v15
	v_mul_f32_e32 v172, v172, v15
	v_mul_f32_e32 v173, v173, v15
	v_mul_f32_e32 v174, v174, v15
	v_mul_f32_e32 v175, v175, v15
	v_fmac_f32_e32 v176, v160, v20
	v_fmac_f32_e32 v177, v161, v21
	v_fmac_f32_e32 v178, v162, v22
	v_fmac_f32_e32 v179, v163, v23
	v_fmac_f32_e32 v180, v164, v24
	v_fmac_f32_e32 v181, v165, v25
	v_fmac_f32_e32 v182, v166, v26
	v_fmac_f32_e32 v183, v167, v27
	v_fmac_f32_e32 v184, v168, v28
	v_fmac_f32_e32 v185, v169, v29
	v_fmac_f32_e32 v186, v170, v30
	v_fmac_f32_e32 v187, v171, v31
	v_fmac_f32_e32 v188, v172, v32
	v_fmac_f32_e32 v189, v173, v33
	v_fmac_f32_e32 v190, v174, v34
	v_fmac_f32_e32 v191, v175, v35
	global_store_dwordx4 v1, v[176:179], s[48:49] offset:0 nt
	global_store_dwordx4 v1, v[180:183], s[48:49] offset:1024 nt
	global_store_dwordx4 v1, v[184:187], s[48:49] offset:2048 nt
	global_store_dwordx4 v1, v[188:191], s[48:49] offset:3072 nt
	v_mul_f32_e32 v10, v144, v144
	v_fmac_f32_e32 v10, v145, v145
	v_fmac_f32_e32 v10, v146, v146
	v_fmac_f32_e32 v10, v147, v147
	v_fmac_f32_e32 v10, v148, v148
	v_fmac_f32_e32 v10, v149, v149
	v_fmac_f32_e32 v10, v150, v150
	v_fmac_f32_e32 v10, v151, v151
	v_fmac_f32_e32 v10, v152, v152
	v_fmac_f32_e32 v10, v153, v153
	v_fmac_f32_e32 v10, v154, v154
	v_fmac_f32_e32 v10, v155, v155
	v_fmac_f32_e32 v10, v156, v156
	v_fmac_f32_e32 v10, v157, v157
	v_fmac_f32_e32 v10, v158, v158
	v_fmac_f32_e32 v10, v159, v159
	v_mul_f32_e32 v11, v176, v176
	v_fmac_f32_e32 v11, v177, v177
	v_fmac_f32_e32 v11, v178, v178
	v_fmac_f32_e32 v11, v179, v179
	v_fmac_f32_e32 v11, v180, v180
	v_fmac_f32_e32 v11, v181, v181
	v_fmac_f32_e32 v11, v182, v182
	v_fmac_f32_e32 v11, v183, v183
	v_fmac_f32_e32 v11, v184, v184
	v_fmac_f32_e32 v11, v185, v185
	v_fmac_f32_e32 v11, v186, v186
	v_fmac_f32_e32 v11, v187, v187
	v_fmac_f32_e32 v11, v188, v188
	v_fmac_f32_e32 v11, v189, v189
	v_fmac_f32_e32 v11, v190, v190
	v_fmac_f32_e32 v11, v191, v191
	ds_bpermute_b32 v12, v4, v10
	ds_bpermute_b32 v13, v4, v11
	s_waitcnt lgkmcnt(0)
	v_add_f32_e32 v10, v10, v12
	v_add_f32_e32 v11, v11, v13
	ds_bpermute_b32 v12, v5, v10
	ds_bpermute_b32 v13, v5, v11
	s_waitcnt lgkmcnt(0)
	v_add_f32_e32 v10, v10, v12
	v_add_f32_e32 v11, v11, v13
	ds_bpermute_b32 v12, v6, v10
	ds_bpermute_b32 v13, v6, v11
	s_waitcnt lgkmcnt(0)
	v_add_f32_e32 v10, v10, v12
	v_add_f32_e32 v11, v11, v13
	ds_bpermute_b32 v12, v7, v10
	ds_bpermute_b32 v13, v7, v11
	s_waitcnt lgkmcnt(0)
	v_add_f32_e32 v10, v10, v12
	v_add_f32_e32 v11, v11, v13
	ds_bpermute_b32 v12, v8, v10
	ds_bpermute_b32 v13, v8, v11
	s_waitcnt lgkmcnt(0)
	v_add_f32_e32 v10, v10, v12
	v_add_f32_e32 v11, v11, v13
	ds_bpermute_b32 v12, v9, v10
	ds_bpermute_b32 v13, v9, v11
	s_waitcnt lgkmcnt(0)
	v_add_f32_e32 v10, v10, v12
	v_add_f32_e32 v11, v11, v13
	v_fma_f32 v14, v10, s17, v3
	v_fma_f32 v15, v11, s17, v3
	v_rsq_f32_e32 v14, v14
	v_rsq_f32_e32 v15, v15
	s_nop 0
	v_mul_f32_e32 v128, v144, v14
	v_mul_f32_e32 v129, v145, v14
	v_mul_f32_e32 v130, v146, v14
	v_mul_f32_e32 v131, v147, v14
	v_mul_f32_e32 v132, v148, v14
	v_mul_f32_e32 v133, v149, v14
	v_mul_f32_e32 v134, v150, v14
	v_mul_f32_e32 v135, v151, v14
	v_mul_f32_e32 v136, v152, v14
	v_mul_f32_e32 v137, v153, v14
	v_mul_f32_e32 v138, v154, v14
	v_mul_f32_e32 v139, v155, v14
	v_mul_f32_e32 v140, v156, v14
	v_mul_f32_e32 v141, v157, v14
	v_mul_f32_e32 v142, v158, v14
	v_mul_f32_e32 v143, v159, v14
	v_mul_f32_e32 v128, v128, v36
	v_mul_f32_e32 v129, v129, v37
	v_mul_f32_e32 v130, v130, v38
	v_mul_f32_e32 v131, v131, v39
	v_mul_f32_e32 v132, v132, v40
	v_mul_f32_e32 v133, v133, v41
	v_mul_f32_e32 v134, v134, v42
	v_mul_f32_e32 v135, v135, v43
	v_mul_f32_e32 v136, v136, v44
	v_mul_f32_e32 v137, v137, v45
	v_mul_f32_e32 v138, v138, v46
	v_mul_f32_e32 v139, v139, v47
	v_mul_f32_e32 v140, v140, v48
	v_mul_f32_e32 v141, v141, v49
	v_mul_f32_e32 v142, v142, v50
	v_mul_f32_e32 v143, v143, v51
	v_cvt_pk_bf16_f32 v128, v128, v129
	v_cvt_pk_bf16_f32 v129, v130, v131
	v_cvt_pk_bf16_f32 v132, v132, v133
	v_cvt_pk_bf16_f32 v133, v134, v135
	v_cvt_pk_bf16_f32 v136, v136, v137
	v_cvt_pk_bf16_f32 v137, v138, v139
	v_cvt_pk_bf16_f32 v140, v140, v141
	v_cvt_pk_bf16_f32 v141, v142, v143
	global_store_dwordx2 v2, v[128:129], s[42:43] offset:0
	global_store_dwordx2 v2, v[132:133], s[42:43] offset:512
	global_store_dwordx2 v2, v[136:137], s[42:43] offset:1024
	global_store_dwordx2 v2, v[140:141], s[42:43] offset:1536
	v_mul_f32_e32 v160, v176, v15
	v_mul_f32_e32 v161, v177, v15
	v_mul_f32_e32 v162, v178, v15
	v_mul_f32_e32 v163, v179, v15
	v_mul_f32_e32 v164, v180, v15
	v_mul_f32_e32 v165, v181, v15
	v_mul_f32_e32 v166, v182, v15
	v_mul_f32_e32 v167, v183, v15
	v_mul_f32_e32 v168, v184, v15
	v_mul_f32_e32 v169, v185, v15
	v_mul_f32_e32 v170, v186, v15
	v_mul_f32_e32 v171, v187, v15
	v_mul_f32_e32 v172, v188, v15
	v_mul_f32_e32 v173, v189, v15
	v_mul_f32_e32 v174, v190, v15
	v_mul_f32_e32 v175, v191, v15
	v_mul_f32_e32 v160, v160, v36
	v_mul_f32_e32 v161, v161, v37
	v_mul_f32_e32 v162, v162, v38
	v_mul_f32_e32 v163, v163, v39
	v_mul_f32_e32 v164, v164, v40
	v_mul_f32_e32 v165, v165, v41
	v_mul_f32_e32 v166, v166, v42
	v_mul_f32_e32 v167, v167, v43
	v_mul_f32_e32 v168, v168, v44
	v_mul_f32_e32 v169, v169, v45
	v_mul_f32_e32 v170, v170, v46
	v_mul_f32_e32 v171, v171, v47
	v_mul_f32_e32 v172, v172, v48
	v_mul_f32_e32 v173, v173, v49
	v_mul_f32_e32 v174, v174, v50
	v_mul_f32_e32 v175, v175, v51
	v_cvt_pk_bf16_f32 v160, v160, v161
	v_cvt_pk_bf16_f32 v161, v162, v163
	v_cvt_pk_bf16_f32 v164, v164, v165
	v_cvt_pk_bf16_f32 v165, v166, v167
	v_cvt_pk_bf16_f32 v168, v168, v169
	v_cvt_pk_bf16_f32 v169, v170, v171
	v_cvt_pk_bf16_f32 v172, v172, v173
	v_cvt_pk_bf16_f32 v173, v174, v175
	global_store_dwordx2 v2, v[160:161], s[50:51] offset:0
	global_store_dwordx2 v2, v[164:165], s[50:51] offset:512
	global_store_dwordx2 v2, v[168:169], s[50:51] offset:1024
	global_store_dwordx2 v2, v[172:173], s[50:51] offset:1536
	v_add_f32_e32 v208, v208, v212
	v_add_f32_e32 v209, v209, v213
	v_add_f32_e32 v210, v210, v214
	v_add_f32_e32 v211, v211, v215
	v_readfirstlane_b32 s18, v0
	s_lshr_b32 s18, s18, 6
	s_lshl_b32 s19, s18, 2
	s_and_b32 s52, s18, 4
	s_lshl_b32 s52, s52, 2
	v_mov_b32_e32 v16, s19
	v_mov_b32_e32 v17, s52
	v_mul_f32_e32 v10, v208, v208
	v_fmac_f32_e32 v10, v209, v209
	v_fmac_f32_e32 v10, v210, v210
	v_fmac_f32_e32 v10, v211, v211
	ds_bpermute_b32 v11, v4, v10
	s_waitcnt lgkmcnt(0)
	v_add_f32_e32 v10, v10, v11
	ds_bpermute_b32 v11, v5, v10
	s_waitcnt lgkmcnt(0)
	v_add_f32_e32 v10, v10, v11
	ds_bpermute_b32 v11, v6, v10
	s_waitcnt lgkmcnt(0)
	v_add_f32_e32 v10, v10, v11
	ds_bpermute_b32 v11, v7, v10
	s_waitcnt lgkmcnt(0)
	v_add_f32_e32 v10, v10, v11
	ds_bpermute_b32 v11, v8, v10
	s_waitcnt lgkmcnt(0)
	v_add_f32_e32 v10, v10, v11
	ds_bpermute_b32 v11, v9, v10
	s_waitcnt lgkmcnt(0)
	v_add_f32_e32 v10, v10, v11
	ds_write_b32 v16, v10 offset:0
	s_waitcnt lgkmcnt(0)
	s_barrier
	ds_read_b128 v[12:15], v17 offset:0
	s_waitcnt lgkmcnt(0)
	v_add_f32_e32 v12, v12, v13
	v_add_f32_e32 v14, v14, v15
	v_add_f32_e32 v10, v12, v14
	v_fma_f32 v11, v10, s17, v3
	v_rsq_f32_e32 v11, v11
	s_nop 0
	v_mul_f32_e32 v208, v208, v11
	v_mul_f32_e32 v209, v209, v11
	v_mul_f32_e32 v210, v210, v11
	v_mul_f32_e32 v211, v211, v11
	v_fmac_f32_e32 v240, v208, v244
	v_fmac_f32_e32 v241, v209, v245
	v_fmac_f32_e32 v242, v210, v246
	v_fmac_f32_e32 v243, v211, v247
	s_lshl_b32 s18, s54, 12
	s_add_u32 s18, s18, s55
	s_add_u32 s56, s4, s18
	s_addc_u32 s57, s5, 0
	s_add_u32 s56, s56, 0x4000000
	s_addc_u32 s57, s57, 0
	global_store_dwordx4 v1, v[240:243], s[56:57]
	v_mul_f32_e32 v10, v240, v240
	v_fmac_f32_e32 v10, v241, v241
	v_fmac_f32_e32 v10, v242, v242
	v_fmac_f32_e32 v10, v243, v243
	ds_bpermute_b32 v11, v4, v10
	s_waitcnt lgkmcnt(0)
	v_add_f32_e32 v10, v10, v11
	ds_bpermute_b32 v11, v5, v10
	s_waitcnt lgkmcnt(0)
	v_add_f32_e32 v10, v10, v11
	ds_bpermute_b32 v11, v6, v10
	s_waitcnt lgkmcnt(0)
	v_add_f32_e32 v10, v10, v11
	ds_bpermute_b32 v11, v7, v10
	s_waitcnt lgkmcnt(0)
	v_add_f32_e32 v10, v10, v11
	ds_bpermute_b32 v11, v8, v10
	s_waitcnt lgkmcnt(0)
	v_add_f32_e32 v10, v10, v11
	ds_bpermute_b32 v11, v9, v10
	s_waitcnt lgkmcnt(0)
	v_add_f32_e32 v10, v10, v11
	ds_write_b32 v16, v10 offset:64
	s_waitcnt lgkmcnt(0)
	s_barrier
	ds_read_b128 v[12:15], v17 offset:64
	s_waitcnt lgkmcnt(0)
	v_add_f32_e32 v12, v12, v13
	v_add_f32_e32 v14, v14, v15
	v_add_f32_e32 v10, v12, v14
	v_fma_f32 v11, v10, s17, v3
	v_rsq_f32_e32 v11, v11
	s_nop 0
	v_mul_f32_e32 v208, v240, v11
	v_mul_f32_e32 v209, v241, v11
	v_mul_f32_e32 v210, v242, v11
	v_mul_f32_e32 v211, v243, v11
	v_mul_f32_e32 v208, v208, v248
	v_mul_f32_e32 v209, v209, v249
	v_mul_f32_e32 v210, v210, v250
	v_mul_f32_e32 v211, v211, v251
	v_cvt_pk_bf16_f32 v208, v208, v209
	v_cvt_pk_bf16_f32 v209, v210, v211
	s_lshl_b32 s18, s54, 11
	s_lshr_b32 s19, s55, 1
	s_add_u32 s18, s18, s19
	s_add_u32 s56, s6, s18
	s_addc_u32 s57, s7, 0
	s_add_u32 s56, s56, 0x5100000
	s_addc_u32 s57, s57, 0
	global_store_dwordx2 v2, v[208:209], s[56:57]

_Z10fwd_kernelILi14ELi15EEv4Args:
	s_load_dword s3, s[0:1], 0xe8
	s_load_dwordx4 s[4:7], s[0:1], 0xd0
	s_load_dwordx2 s[8:9], s[0:1], 0xb8
	s_waitcnt lgkmcnt(0)
	s_cmp_lg_u32 s3, 0x100
	s_cbranch_scc1 .Lrows14_orig
	s_add_u32 s8, s8, 0x1000
	s_addc_u32 s9, s9, 0
	v_readfirstlane_b32 s16, v0
	s_lshr_b32 s16, s16, 6
	s_lshl_b32 s18, s2, 3
	s_add_u32 s16, s16, s18
	s_mov_b32 s17, 0x3a800000
	v_mov_b32_e32 v3, 0x358637bd
	v_and_b32_e32 v10, 63, v0
	v_lshlrev_b32_e32 v1, 4, v10
	v_lshlrev_b32_e32 v2, 3, v10
	v_xor_b32_e32 v4, 1, v10
	v_xor_b32_e32 v5, 2, v10
	v_xor_b32_e32 v6, 4, v10
	v_xor_b32_e32 v7, 8, v10
	v_xor_b32_e32 v8, 16, v10
	v_xor_b32_e32 v9, 32, v10
	v_lshlrev_b32_e32 v4, 2, v4
	v_lshlrev_b32_e32 v5, 2, v5
	v_lshlrev_b32_e32 v6, 2, v6
	v_lshlrev_b32_e32 v7, 2, v7
	v_lshlrev_b32_e32 v8, 2, v8
	v_lshlrev_b32_e32 v9, 2, v9
	global_load_dwordx4 v[20:23], v1, s[8:9] offset:0
	global_load_dwordx4 v[24:27], v1, s[8:9] offset:1024
	global_load_dwordx4 v[28:31], v1, s[8:9] offset:2048
	global_load_dwordx4 v[32:35], v1, s[8:9] offset:3072
	s_lshr_b32 s54, s16, 2
	s_and_b32 s55, s16, 3
	s_lshl_b32 s55, s55, 10
	s_lshl_b32 s18, s54, 12
	s_add_u32 s18, s18, s55
	s_add_u32 s56, s6, s18
	s_addc_u32 s57, s7, 0
	s_add_u32 s56, s56, 0x100000
	s_addc_u32 s57, s57, 0
	global_load_dwordx4 v[208:211], v1, s[56:57]
	s_add_u32 s56, s56, 0x200000
	s_addc_u32 s57, s57, 0
	global_load_dwordx4 v[212:215], v1, s[56:57]
	s_add_u32 s56, s56, 0x200000
	s_addc_u32 s57, s57, 0
	global_load_dwordx4 v[216:219], v1, s[56:57]
	s_add_u32 s56, s56, 0x200000
	s_addc_u32 s57, s57, 0
	global_load_dwordx4 v[220:223], v1, s[56:57]
	s_add_u32 s56, s56, 0x200000
	s_addc_u32 s57, s57, 0
	global_load_dwordx4 v[224:227], v1, s[56:57]
	s_add_u32 s56, s56, 0x200000
	s_addc_u32 s57, s57, 0
	global_load_dwordx4 v[228:231], v1, s[56:57]
	s_add_u32 s56, s56, 0x200000
	s_addc_u32 s57, s57, 0
	global_load_dwordx4 v[232:235], v1, s[56:57]
	s_add_u32 s56, s56, 0x200000
	s_addc_u32 s57, s57, 0
	global_load_dwordx4 v[236:239], v1, s[56:57]
	s_add_u32 s56, s4, s18
	s_addc_u32 s57, s5, 0
	s_add_u32 s56, s56, 0x4000000
	s_addc_u32 s57, s57, 0
	global_load_dwordx4 v[240:243], v1, s[56:57]
	s_add_u32 s56, s8, s55
	s_addc_u32 s57, s9, 0
	global_load_dwordx4 v[244:247], v1, s[56:57]
	s_add_u32 s53, s16, 0x0
	s_lshl_b32 s18, s53, 12
	s_lshl_b32 s19, s53, 11
	s_add_u32 s20, s4, s18
	s_addc_u32 s21, s5, 0
	s_add_u32 s22, s6, s19
	s_addc_u32 s23, s7, 0
	s_add_u32 s22, s22, 0x5200000
	s_addc_u32 s23, s23, 0
	s_add_u32 s24, s4, s18
	s_addc_u32 s25, s5, 0
	global_load_dwordx2 v[66:67], v2, s[22:23] offset:0
	global_load_dwordx2 v[70:71], v2, s[22:23] offset:512
	global_load_dwordx2 v[74:75], v2, s[22:23] offset:1024
	global_load_dwordx2 v[78:79], v2, s[22:23] offset:1536
	global_load_dwordx4 v[80:83], v1, s[20:21] offset:0 nt
	global_load_dwordx4 v[84:87], v1, s[20:21] offset:1024 nt
	global_load_dwordx4 v[88:91], v1, s[20:21] offset:2048 nt
	global_load_dwordx4 v[92:95], v1, s[20:21] offset:3072 nt
	s_add_u32 s53, s16, 0x800
	s_lshl_b32 s18, s53, 12
	s_lshl_b32 s19, s53, 11
	s_add_u32 s28, s4, s18
	s_addc_u32 s29, s5, 0
	s_add_u32 s30, s6, s19
	s_addc_u32 s31, s7, 0
	s_add_u32 s30, s30, 0x5200000
	s_addc_u32 s31, s31, 0
	s_add_u32 s32, s4, s18
	s_addc_u32 s33, s5, 0
	global_load_dwordx2 v[98:99], v2, s[30:31] offset:0
	global_load_dwordx2 v[102:103], v2, s[30:31] offset:512
	global_load_dwordx2 v[106:107], v2, s[30:31] offset:1024
	global_load_dwordx2 v[110:111], v2, s[30:31] offset:1536
	global_load_dwordx4 v[112:115], v1, s[28:29] offset:0 nt
	global_load_dwordx4 v[116:119], v1, s[28:29] offset:1024 nt
	global_load_dwordx4 v[120:123], v1, s[28:29] offset:2048 nt
	global_load_dwordx4 v[124:127], v1, s[28:29] offset:3072 nt
	s_add_u32 s53, s16, 0x1000
	s_lshl_b32 s18, s53, 12
	s_lshl_b32 s19, s53, 11
	s_add_u32 s36, s4, s18
	s_addc_u32 s37, s5, 0
	s_add_u32 s38, s6, s19
	s_addc_u32 s39, s7, 0
	s_add_u32 s38, s38, 0x5200000
	s_addc_u32 s39, s39, 0
	s_add_u32 s40, s4, s18
	s_addc_u32 s41, s5, 0
	global_load_dwordx2 v[130:131], v2, s[38:39] offset:0
	global_load_dwordx2 v[134:135], v2, s[38:39] offset:512
	global_load_dwordx2 v[138:139], v2, s[38:39] offset:1024
	global_load_dwordx2 v[142:143], v2, s[38:39] offset:1536
	global_load_dwordx4 v[144:147], v1, s[36:37] offset:0 nt
	global_load_dwordx4 v[148:151], v1, s[36:37] offset:1024 nt
	global_load_dwordx4 v[152:155], v1, s[36:37] offset:2048 nt
	global_load_dwordx4 v[156:159], v1, s[36:37] offset:3072 nt
	s_add_u32 s53, s16, 0x1800
	s_lshl_b32 s18, s53, 12
	s_lshl_b32 s19, s53, 11
	s_add_u32 s44, s4, s18
	s_addc_u32 s45, s5, 0
	s_add_u32 s46, s6, s19
	s_addc_u32 s47, s7, 0
	s_add_u32 s46, s46, 0x5200000
	s_addc_u32 s47, s47, 0
	s_add_u32 s48, s4, s18
	s_addc_u32 s49, s5, 0
	global_load_dwordx2 v[162:163], v2, s[46:47] offset:0
	global_load_dwordx2 v[166:167], v2, s[46:47] offset:512
	global_load_dwordx2 v[170:171], v2, s[46:47] offset:1024
	global_load_dwordx2 v[174:175], v2, s[46:47] offset:1536
	global_load_dwordx4 v[176:179], v1, s[44:45] offset:0 nt
	global_load_dwordx4 v[180:183], v1, s[44:45] offset:1024 nt
	global_load_dwordx4 v[184:187], v1, s[44:45] offset:2048 nt
	global_load_dwordx4 v[188:191], v1, s[44:45] offset:3072 nt
	s_waitcnt vmcnt(16)
	v_lshlrev_b32_e32 v64, 16, v66
	v_and_b32_e32 v65, 0xffff0000, v66
	v_lshlrev_b32_e32 v66, 16, v67
	v_and_b32_e32 v67, 0xffff0000, v67
	v_lshlrev_b32_e32 v68, 16, v70
	v_and_b32_e32 v69, 0xffff0000, v70
	v_lshlrev_b32_e32 v70, 16, v71
	v_and_b32_e32 v71, 0xffff0000, v71
	v_lshlrev_b32_e32 v72, 16, v74
	v_and_b32_e32 v73, 0xffff0000, v74
	v_lshlrev_b32_e32 v74, 16, v75
	v_and_b32_e32 v75, 0xffff0000, v75
	v_lshlrev_b32_e32 v76, 16, v78
	v_and_b32_e32 v77, 0xffff0000, v78
	v_lshlrev_b32_e32 v78, 16, v79
	v_and_b32_e32 v79, 0xffff0000, v79
	v_lshlrev_b32_e32 v96, 16, v98
	v_and_b32_e32 v97, 0xffff0000, v98
	v_lshlrev_b32_e32 v98, 16, v99
	v_and_b32_e32 v99, 0xffff0000, v99
	v_lshlrev_b32_e32 v100, 16, v102
	v_and_b32_e32 v101, 0xffff0000, v102
	v_lshlrev_b32_e32 v102, 16, v103
	v_and_b32_e32 v103, 0xffff0000, v103
	v_lshlrev_b32_e32 v104, 16, v106
	v_and_b32_e32 v105, 0xffff0000, v106
	v_lshlrev_b32_e32 v106, 16, v107
	v_and_b32_e32 v107, 0xffff0000, v107
	v_lshlrev_b32_e32 v108, 16, v110
	v_and_b32_e32 v109, 0xffff0000, v110
	v_lshlrev_b32_e32 v110, 16, v111
	v_and_b32_e32 v111, 0xffff0000, v111
	v_mul_f32_e32 v10, v64, v64
	v_fmac_f32_e32 v10, v65, v65
	v_fmac_f32_e32 v10, v66, v66
	v_fmac_f32_e32 v10, v67, v67
	v_fmac_f32_e32 v10, v68, v68
	v_fmac_f32_e32 v10, v69, v69
	v_fmac_f32_e32 v10, v70, v70
	v_fmac_f32_e32 v10, v71, v71
	v_fmac_f32_e32 v10, v72, v72
	v_fmac_f32_e32 v10, v73, v73
	v_fmac_f32_e32 v10, v74, v74
	v_fmac_f32_e32 v10, v75, v75
	v_fmac_f32_e32 v10, v76, v76
	v_fmac_f32_e32 v10, v77, v77
	v_fmac_f32_e32 v10, v78, v78
	v_fmac_f32_e32 v10, v79, v79
	v_mul_f32_e32 v11, v96, v96
	v_fmac_f32_e32 v11, v97, v97
	v_fmac_f32_e32 v11, v98, v98
	v_fmac_f32_e32 v11, v99, v99
	v_fmac_f32_e32 v11, v100, v100
	v_fmac_f32_e32 v11, v101, v101
	v_fmac_f32_e32 v11, v102, v102
	v_fmac_f32_e32 v11, v103, v103
	v_fmac_f32_e32 v11, v104, v104
	v_fmac_f32_e32 v11, v105, v105
	v_fmac_f32_e32 v11, v106, v106
	v_fmac_f32_e32 v11, v107, v107
	v_fmac_f32_e32 v11, v108, v108
	v_fmac_f32_e32 v11, v109, v109
	v_fmac_f32_e32 v11, v110, v110
	v_fmac_f32_e32 v11, v111, v111
	ds_bpermute_b32 v12, v4, v10
	ds_bpermute_b32 v13, v4, v11
	s_waitcnt lgkmcnt(0)
	v_add_f32_e32 v10, v10, v12
	v_add_f32_e32 v11, v11, v13
	ds_bpermute_b32 v12, v5, v10
	ds_bpermute_b32 v13, v5, v11
	s_waitcnt lgkmcnt(0)
	v_add_f32_e32 v10, v10, v12
	v_add_f32_e32 v11, v11, v13
	ds_bpermute_b32 v12, v6, v10
	ds_bpermute_b32 v13, v6, v11
	s_waitcnt lgkmcnt(0)
	v_add_f32_e32 v10, v10, v12
	v_add_f32_e32 v11, v11, v13
	ds_bpermute_b32 v12, v7, v10
	ds_bpermute_b32 v13, v7, v11
	s_waitcnt lgkmcnt(0)
	v_add_f32_e32 v10, v10, v12
	v_add_f32_e32 v11, v11, v13
	ds_bpermute_b32 v12, v8, v10
	ds_bpermute_b32 v13, v8, v11
	s_waitcnt lgkmcnt(0)
	v_add_f32_e32 v10, v10, v12
	v_add_f32_e32 v11, v11, v13
	ds_bpermute_b32 v12, v9, v10
	ds_bpermute_b32 v13, v9, v11
	s_waitcnt lgkmcnt(0)
	v_add_f32_e32 v10, v10, v12
	v_add_f32_e32 v11, v11, v13
	v_fma_f32 v14, v10, s17, v3
	v_fma_f32 v15, v11, s17, v3
	v_rsq_f32_e32 v14, v14
	v_rsq_f32_e32 v15, v15
	s_nop 0
	v_mul_f32_e32 v64, v64, v14
	v_mul_f32_e32 v65, v65, v14
	v_mul_f32_e32 v66, v66, v14
	v_mul_f32_e32 v67, v67, v14
	v_mul_f32_e32 v68, v68, v14
	v_mul_f32_e32 v69, v69, v14
	v_mul_f32_e32 v70, v70, v14
	v_mul_f32_e32 v71, v71, v14
	v_mul_f32_e32 v72, v72, v14
	v_mul_f32_e32 v73, v73, v14
	v_mul_f32_e32 v74, v74, v14
	v_mul_f32_e32 v75, v75, v14
	v_mul_f32_e32 v76, v76, v14
	v_mul_f32_e32 v77, v77, v14
	v_mul_f32_e32 v78, v78, v14
	v_mul_f32_e32 v79, v79, v14
	v_fmac_f32_e32 v80, v64, v20
	v_fmac_f32_e32 v81, v65, v21
	v_fmac_f32_e32 v82, v66, v22
	v_fmac_f32_e32 v83, v67, v23
	v_fmac_f32_e32 v84, v68, v24
	v_fmac_f32_e32 v85, v69, v25
	v_fmac_f32_e32 v86, v70, v26
	v_fmac_f32_e32 v87, v71, v27
	v_fmac_f32_e32 v88, v72, v28
	v_fmac_f32_e32 v89, v73, v29
	v_fmac_f32_e32 v90, v74, v30
	v_fmac_f32_e32 v91, v75, v31
	v_fmac_f32_e32 v92, v76, v32
	v_fmac_f32_e32 v93, v77, v33
	v_fmac_f32_e32 v94, v78, v34
	v_fmac_f32_e32 v95, v79, v35
	global_store_dwordx4 v1, v[80:83], s[24:25] offset:0 nt
	global_store_dwordx4 v1, v[84:87], s[24:25] offset:1024 nt
	global_store_dwordx4 v1, v[88:91], s[24:25] offset:2048 nt
	global_store_dwordx4 v1, v[92:95], s[24:25] offset:3072 nt
	v_mul_f32_e32 v96, v96, v15
	v_mul_f32_e32 v97, v97, v15
	v_mul_f32_e32 v98, v98, v15
	v_mul_f32_e32 v99, v99, v15
	v_mul_f32_e32 v100, v100, v15
	v_mul_f32_e32 v101, v101, v15
	v_mul_f32_e32 v102, v102, v15
	v_mul_f32_e32 v103, v103, v15
	v_mul_f32_e32 v104, v104, v15
	v_mul_f32_e32 v105, v105, v15
	v_mul_f32_e32 v106, v106, v15
	v_mul_f32_e32 v107, v107, v15
	v_mul_f32_e32 v108, v108, v15
	v_mul_f32_e32 v109, v109, v15
	v_mul_f32_e32 v110, v110, v15
	v_mul_f32_e32 v111, v111, v15
	v_fmac_f32_e32 v112, v96, v20
	v_fmac_f32_e32 v113, v97, v21
	v_fmac_f32_e32 v114, v98, v22
	v_fmac_f32_e32 v115, v99, v23
	v_fmac_f32_e32 v116, v100, v24
	v_fmac_f32_e32 v117, v101, v25
	v_fmac_f32_e32 v118, v102, v26
	v_fmac_f32_e32 v119, v103, v27
	v_fmac_f32_e32 v120, v104, v28
	v_fmac_f32_e32 v121, v105, v29
	v_fmac_f32_e32 v122, v106, v30
	v_fmac_f32_e32 v123, v107, v31
	v_fmac_f32_e32 v124, v108, v32
	v_fmac_f32_e32 v125, v109, v33
	v_fmac_f32_e32 v126, v110, v34
	v_fmac_f32_e32 v127, v111, v35
	global_store_dwordx4 v1, v[112:115], s[32:33] offset:0 nt
	global_store_dwordx4 v1, v[116:119], s[32:33] offset:1024 nt
	global_store_dwordx4 v1, v[120:123], s[32:33] offset:2048 nt
	global_store_dwordx4 v1, v[124:127], s[32:33] offset:3072 nt
	s_add_u32 s53, s16, 0x2000
	s_lshl_b32 s18, s53, 12
	s_lshl_b32 s19, s53, 11
	s_add_u32 s20, s4, s18
	s_addc_u32 s21, s5, 0
	s_add_u32 s22, s6, s19
	s_addc_u32 s23, s7, 0
	s_add_u32 s22, s22, 0x5200000
	s_addc_u32 s23, s23, 0
	s_add_u32 s24, s4, s18
	s_addc_u32 s25, s5, 0
	global_load_dwordx2 v[66:67], v2, s[22:23] offset:0
	global_load_dwordx2 v[70:71], v2, s[22:23] offset:512
	global_load_dwordx2 v[74:75], v2, s[22:23] offset:1024
	global_load_dwordx2 v[78:79], v2, s[22:23] offset:1536
	global_load_dwordx4 v[80:83], v1, s[20:21] offset:0 nt
	global_load_dwordx4 v[84:87], v1, s[20:21] offset:1024 nt
	global_load_dwordx4 v[88:91], v1, s[20:21] offset:2048 nt
	global_load_dwordx4 v[92:95], v1, s[20:21] offset:3072 nt
	s_add_u32 s53, s16, 0x2800
	s_lshl_b32 s18, s53, 12
	s_lshl_b32 s19, s53, 11
	s_add_u32 s28, s4, s18
	s_addc_u32 s29, s5, 0
	s_add_u32 s30, s6, s19
	s_addc_u32 s31, s7, 0
	s_add_u32 s30, s30, 0x5200000
	s_addc_u32 s31, s31, 0
	s_add_u32 s32, s4, s18
	s_addc_u32 s33, s5, 0
	global_load_dwordx2 v[98:99], v2, s[30:31] offset:0
	global_load_dwordx2 v[102:103], v2, s[30:31] offset:512
	global_load_dwordx2 v[106:107], v2, s[30:31] offset:1024
	global_load_dwordx2 v[110:111], v2, s[30:31] offset:1536
	global_load_dwordx4 v[112:115], v1, s[28:29] offset:0 nt
	global_load_dwordx4 v[116:119], v1, s[28:29] offset:1024 nt
	global_load_dwordx4 v[120:123], v1, s[28:29] offset:2048 nt
	global_load_dwordx4 v[124:127], v1, s[28:29] offset:3072 nt
	s_waitcnt vmcnt(24)
	v_lshlrev_b32_e32 v128, 16, v130
	v_and_b32_e32 v129, 0xffff0000, v130
	v_lshlrev_b32_e32 v130, 16, v131
	v_and_b32_e32 v131, 0xffff0000, v131
	v_lshlrev_b32_e32 v132, 16, v134
	v_and_b32_e32 v133, 0xffff0000, v134
	v_lshlrev_b32_e32 v134, 16, v135
	v_and_b32_e32 v135, 0xffff0000, v135
	v_lshlrev_b32_e32 v136, 16, v138
	v_and_b32_e32 v137, 0xffff0000, v138
	v_lshlrev_b32_e32 v138, 16, v139
	v_and_b32_e32 v139, 0xffff0000, v139
	v_lshlrev_b32_e32 v140, 16, v142
	v_and_b32_e32 v141, 0xffff0000, v142
	v_lshlrev_b32_e32 v142, 16, v143
	v_and_b32_e32 v143, 0xffff0000, v143
	v_lshlrev_b32_e32 v160, 16, v162
	v_and_b32_e32 v161, 0xffff0000, v162
	v_lshlrev_b32_e32 v162, 16, v163
	v_and_b32_e32 v163, 0xffff0000, v163
	v_lshlrev_b32_e32 v164, 16, v166
	v_and_b32_e32 v165, 0xffff0000, v166
	v_lshlrev_b32_e32 v166, 16, v167
	v_and_b32_e32 v167, 0xffff0000, v167
	v_lshlrev_b32_e32 v168, 16, v170
	v_and_b32_e32 v169, 0xffff0000, v170
	v_lshlrev_b32_e32 v170, 16, v171
	v_and_b32_e32 v171, 0xffff0000, v171
	v_lshlrev_b32_e32 v172, 16, v174
	v_and_b32_e32 v173, 0xffff0000, v174
	v_lshlrev_b32_e32 v174, 16, v175
	v_and_b32_e32 v175, 0xffff0000, v175
	v_mul_f32_e32 v10, v128, v128
	v_fmac_f32_e32 v10, v129, v129
	v_fmac_f32_e32 v10, v130, v130
	v_fmac_f32_e32 v10, v131, v131
	v_fmac_f32_e32 v10, v132, v132
	v_fmac_f32_e32 v10, v133, v133
	v_fmac_f32_e32 v10, v134, v134
	v_fmac_f32_e32 v10, v135, v135
	v_fmac_f32_e32 v10, v136, v136
	v_fmac_f32_e32 v10, v137, v137
	v_fmac_f32_e32 v10, v138, v138
	v_fmac_f32_e32 v10, v139, v139
	v_fmac_f32_e32 v10, v140, v140
	v_fmac_f32_e32 v10, v141, v141
	v_fmac_f32_e32 v10, v142, v142
	v_fmac_f32_e32 v10, v143, v143
	v_mul_f32_e32 v11, v160, v160
	v_fmac_f32_e32 v11, v161, v161
	v_fmac_f32_e32 v11, v162, v162
	v_fmac_f32_e32 v11, v163, v163
	v_fmac_f32_e32 v11, v164, v164
	v_fmac_f32_e32 v11, v165, v165
	v_fmac_f32_e32 v11, v166, v166
	v_fmac_f32_e32 v11, v167, v167
	v_fmac_f32_e32 v11, v168, v168
	v_fmac_f32_e32 v11, v169, v169
	v_fmac_f32_e32 v11, v170, v170
	v_fmac_f32_e32 v11, v171, v171
	v_fmac_f32_e32 v11, v172, v172
	v_fmac_f32_e32 v11, v173, v173
	v_fmac_f32_e32 v11, v174, v174
	v_fmac_f32_e32 v11, v175, v175
	ds_bpermute_b32 v12, v4, v10
	ds_bpermute_b32 v13, v4, v11
	s_waitcnt lgkmcnt(0)
	v_add_f32_e32 v10, v10, v12
	v_add_f32_e32 v11, v11, v13
	ds_bpermute_b32 v12, v5, v10
	ds_bpermute_b32 v13, v5, v11
	s_waitcnt lgkmcnt(0)
	v_add_f32_e32 v10, v10, v12
	v_add_f32_e32 v11, v11, v13
	ds_bpermute_b32 v12, v6, v10
	ds_bpermute_b32 v13, v6, v11
	s_waitcnt lgkmcnt(0)
	v_add_f32_e32 v10, v10, v12
	v_add_f32_e32 v11, v11, v13
	ds_bpermute_b32 v12, v7, v10
	ds_bpermute_b32 v13, v7, v11
	s_waitcnt lgkmcnt(0)
	v_add_f32_e32 v10, v10, v12
	v_add_f32_e32 v11, v11, v13
	ds_bpermute_b32 v12, v8, v10
	ds_bpermute_b32 v13, v8, v11
	s_waitcnt lgkmcnt(0)
	v_add_f32_e32 v10, v10, v12
	v_add_f32_e32 v11, v11, v13
	ds_bpermute_b32 v12, v9, v10
	ds_bpermute_b32 v13, v9, v11
	s_waitcnt lgkmcnt(0)
	v_add_f32_e32 v10, v10, v12
	v_add_f32_e32 v11, v11, v13
	v_fma_f32 v14, v10, s17, v3
	v_fma_f32 v15, v11, s17, v3
	v_rsq_f32_e32 v14, v14
	v_rsq_f32_e32 v15, v15
	s_nop 0
	v_mul_f32_e32 v128, v128, v14
	v_mul_f32_e32 v129, v129, v14
	v_mul_f32_e32 v130, v130, v14
	v_mul_f32_e32 v131, v131, v14
	v_mul_f32_e32 v132, v132, v14
	v_mul_f32_e32 v133, v133, v14
	v_mul_f32_e32 v134, v134, v14
	v_mul_f32_e32 v135, v135, v14
	v_mul_f32_e32 v136, v136, v14
	v_mul_f32_e32 v137, v137, v14
	v_mul_f32_e32 v138, v138, v14
	v_mul_f32_e32 v139, v139, v14
	v_mul_f32_e32 v140, v140, v14
	v_mul_f32_e32 v141, v141, v14
	v_mul_f32_e32 v142, v142, v14
	v_mul_f32_e32 v143, v143, v14
	v_fmac_f32_e32 v144, v128, v20
	v_fmac_f32_e32 v145, v129, v21
	v_fmac_f32_e32 v146, v130, v22
	v_fmac_f32_e32 v147, v131, v23
	v_fmac_f32_e32 v148, v132, v24
	v_fmac_f32_e32 v149, v133, v25
	v_fmac_f32_e32 v150, v134, v26
	v_fmac_f32_e32 v151, v135, v27
	v_fmac_f32_e32 v152, v136, v28
	v_fmac_f32_e32 v153, v137, v29
	v_fmac_f32_e32 v154, v138, v30
	v_fmac_f32_e32 v155, v139, v31
	v_fmac_f32_e32 v156, v140, v32
	v_fmac_f32_e32 v157, v141, v33
	v_fmac_f32_e32 v158, v142, v34
	v_fmac_f32_e32 v159, v143, v35
	global_store_dwordx4 v1, v[144:147], s[40:41] offset:0 nt
	global_store_dwordx4 v1, v[148:151], s[40:41] offset:1024 nt
	global_store_dwordx4 v1, v[152:155], s[40:41] offset:2048 nt
	global_store_dwordx4 v1, v[156:159], s[40:41] offset:3072 nt
	v_mul_f32_e32 v160, v160, v15
	v_mul_f32_e32 v161, v161, v15
	v_mul_f32_e32 v162, v162, v15
	v_mul_f32_e32 v163, v163, v15
	v_mul_f32_e32 v164, v164, v15
	v_mul_f32_e32 v165, v165, v15
	v_mul_f32_e32 v166, v166, v15
	v_mul_f32_e32 v167, v167, v15
	v_mul_f32_e32 v168, v168, v15
	v_mul_f32_e32 v169, v169, v15
	v_mul_f32_e32 v170, v170, v15
	v_mul_f32_e32 v171, v171, v15
	v_mul_f32_e32 v172, v172, v15
	v_mul_f32_e32 v173, v173, v15
	v_mul_f32_e32 v174, v174, v15
	v_mul_f32_e32 v175, v175, v15
	v_fmac_f32_e32 v176, v160, v20
	v_fmac_f32_e32 v177, v161, v21
	v_fmac_f32_e32 v178, v162, v22
	v_fmac_f32_e32 v179, v163, v23
	v_fmac_f32_e32 v180, v164, v24
	v_fmac_f32_e32 v181, v165, v25
	v_fmac_f32_e32 v182, v166, v26
	v_fmac_f32_e32 v183, v167, v27
	v_fmac_f32_e32 v184, v168, v28
	v_fmac_f32_e32 v185, v169, v29
	v_fmac_f32_e32 v186, v170, v30
	v_fmac_f32_e32 v187, v171, v31
	v_fmac_f32_e32 v188, v172, v32
	v_fmac_f32_e32 v189, v173, v33
	v_fmac_f32_e32 v190, v174, v34
	v_fmac_f32_e32 v191, v175, v35
	global_store_dwordx4 v1, v[176:179], s[48:49] offset:0 nt
	global_store_dwordx4 v1, v[180:183], s[48:49] offset:1024 nt
	global_store_dwordx4 v1, v[184:187], s[48:49] offset:2048 nt
	global_store_dwordx4 v1, v[188:191], s[48:49] offset:3072 nt
	s_add_u32 s53, s16, 0x3000
	s_lshl_b32 s18, s53, 12
	s_lshl_b32 s19, s53, 11
	s_add_u32 s36, s4, s18
	s_addc_u32 s37, s5, 0
	s_add_u32 s38, s6, s19
	s_addc_u32 s39, s7, 0
	s_add_u32 s38, s38, 0x5200000
	s_addc_u32 s39, s39, 0
	s_add_u32 s40, s4, s18
	s_addc_u32 s41, s5, 0
	global_load_dwordx2 v[130:131], v2, s[38:39] offset:0
	global_load_dwordx2 v[134:135], v2, s[38:39] offset:512
	global_load_dwordx2 v[138:139], v2, s[38:39] offset:1024
	global_load_dwordx2 v[142:143], v2, s[38:39] offset:1536
	global_load_dwordx4 v[144:147], v1, s[36:37] offset:0 nt
	global_load_dwordx4 v[148:151], v1, s[36:37] offset:1024 nt
	global_load_dwordx4 v[152:155], v1, s[36:37] offset:2048 nt
	global_load_dwordx4 v[156:159], v1, s[36:37] offset:3072 nt
	s_add_u32 s53, s16, 0x3800
	s_lshl_b32 s18, s53, 12
	s_lshl_b32 s19, s53, 11
	s_add_u32 s44, s4, s18
	s_addc_u32 s45, s5, 0
	s_add_u32 s46, s6, s19
	s_addc_u32 s47, s7, 0
	s_add_u32 s46, s46, 0x5200000
	s_addc_u32 s47, s47, 0
	s_add_u32 s48, s4, s18
	s_addc_u32 s49, s5, 0
	global_load_dwordx2 v[162:163], v2, s[46:47] offset:0
	global_load_dwordx2 v[166:167], v2, s[46:47] offset:512
	global_load_dwordx2 v[170:171], v2, s[46:47] offset:1024
	global_load_dwordx2 v[174:175], v2, s[46:47] offset:1536
	global_load_dwordx4 v[176:179], v1, s[44:45] offset:0 nt
	global_load_dwordx4 v[180:183], v1, s[44:45] offset:1024 nt
	global_load_dwordx4 v[184:187], v1, s[44:45] offset:2048 nt
	global_load_dwordx4 v[188:191], v1, s[44:45] offset:3072 nt
	s_waitcnt vmcnt(24)
	v_lshlrev_b32_e32 v64, 16, v66
	v_and_b32_e32 v65, 0xffff0000, v66
	v_lshlrev_b32_e32 v66, 16, v67
	v_and_b32_e32 v67, 0xffff0000, v67
	v_lshlrev_b32_e32 v68, 16, v70
	v_and_b32_e32 v69, 0xffff0000, v70
	v_lshlrev_b32_e32 v70, 16, v71
	v_and_b32_e32 v71, 0xffff0000, v71
	v_lshlrev_b32_e32 v72, 16, v74
	v_and_b32_e32 v73, 0xffff0000, v74
	v_lshlrev_b32_e32 v74, 16, v75
	v_and_b32_e32 v75, 0xffff0000, v75
	v_lshlrev_b32_e32 v76, 16, v78
	v_and_b32_e32 v77, 0xffff0000, v78
	v_lshlrev_b32_e32 v78, 16, v79
	v_and_b32_e32 v79, 0xffff0000, v79
	v_lshlrev_b32_e32 v96, 16, v98
	v_and_b32_e32 v97, 0xffff0000, v98
	v_lshlrev_b32_e32 v98, 16, v99
	v_and_b32_e32 v99, 0xffff0000, v99
	v_lshlrev_b32_e32 v100, 16, v102
	v_and_b32_e32 v101, 0xffff0000, v102
	v_lshlrev_b32_e32 v102, 16, v103
	v_and_b32_e32 v103, 0xffff0000, v103
	v_lshlrev_b32_e32 v104, 16, v106
	v_and_b32_e32 v105, 0xffff0000, v106
	v_lshlrev_b32_e32 v106, 16, v107
	v_and_b32_e32 v107, 0xffff0000, v107
	v_lshlrev_b32_e32 v108, 16, v110
	v_and_b32_e32 v109, 0xffff0000, v110
	v_lshlrev_b32_e32 v110, 16, v111
	v_and_b32_e32 v111, 0xffff0000, v111
	v_mul_f32_e32 v10, v64, v64
	v_fmac_f32_e32 v10, v65, v65
	v_fmac_f32_e32 v10, v66, v66
	v_fmac_f32_e32 v10, v67, v67
	v_fmac_f32_e32 v10, v68, v68
	v_fmac_f32_e32 v10, v69, v69
	v_fmac_f32_e32 v10, v70, v70
	v_fmac_f32_e32 v10, v71, v71
	v_fmac_f32_e32 v10, v72, v72
	v_fmac_f32_e32 v10, v73, v73
	v_fmac_f32_e32 v10, v74, v74
	v_fmac_f32_e32 v10, v75, v75
	v_fmac_f32_e32 v10, v76, v76
	v_fmac_f32_e32 v10, v77, v77
	v_fmac_f32_e32 v10, v78, v78
	v_fmac_f32_e32 v10, v79, v79
	v_mul_f32_e32 v11, v96, v96
	v_fmac_f32_e32 v11, v97, v97
	v_fmac_f32_e32 v11, v98, v98
	v_fmac_f32_e32 v11, v99, v99
	v_fmac_f32_e32 v11, v100, v100
	v_fmac_f32_e32 v11, v101, v101
	v_fmac_f32_e32 v11, v102, v102
	v_fmac_f32_e32 v11, v103, v103
	v_fmac_f32_e32 v11, v104, v104
	v_fmac_f32_e32 v11, v105, v105
	v_fmac_f32_e32 v11, v106, v106
	v_fmac_f32_e32 v11, v107, v107
	v_fmac_f32_e32 v11, v108, v108
	v_fmac_f32_e32 v11, v109, v109
	v_fmac_f32_e32 v11, v110, v110
	v_fmac_f32_e32 v11, v111, v111
	ds_bpermute_b32 v12, v4, v10
	ds_bpermute_b32 v13, v4, v11
	s_waitcnt lgkmcnt(0)
	v_add_f32_e32 v10, v10, v12
	v_add_f32_e32 v11, v11, v13
	ds_bpermute_b32 v12, v5, v10
	ds_bpermute_b32 v13, v5, v11
	s_waitcnt lgkmcnt(0)
	v_add_f32_e32 v10, v10, v12
	v_add_f32_e32 v11, v11, v13
	ds_bpermute_b32 v12, v6, v10
	ds_bpermute_b32 v13, v6, v11
	s_waitcnt lgkmcnt(0)
	v_add_f32_e32 v10, v10, v12
	v_add_f32_e32 v11, v11, v13
	ds_bpermute_b32 v12, v7, v10
	ds_bpermute_b32 v13, v7, v11
	s_waitcnt lgkmcnt(0)
	v_add_f32_e32 v10, v10, v12
	v_add_f32_e32 v11, v11, v13
	ds_bpermute_b32 v12, v8, v10
	ds_bpermute_b32 v13, v8, v11
	s_waitcnt lgkmcnt(0)
	v_add_f32_e32 v10, v10, v12
	v_add_f32_e32 v11, v11, v13
	ds_bpermute_b32 v12, v9, v10
	ds_bpermute_b32 v13, v9, v11
	s_waitcnt lgkmcnt(0)
	v_add_f32_e32 v10, v10, v12
	v_add_f32_e32 v11, v11, v13
	v_fma_f32 v14, v10, s17, v3
	v_fma_f32 v15, v11, s17, v3
	v_rsq_f32_e32 v14, v14
	v_rsq_f32_e32 v15, v15
	s_nop 0
	v_mul_f32_e32 v64, v64, v14
	v_mul_f32_e32 v65, v65, v14
	v_mul_f32_e32 v66, v66, v14
	v_mul_f32_e32 v67, v67, v14
	v_mul_f32_e32 v68, v68, v14
	v_mul_f32_e32 v69, v69, v14
	v_mul_f32_e32 v70, v70, v14
	v_mul_f32_e32 v71, v71, v14
	v_mul_f32_e32 v72, v72, v14
	v_mul_f32_e32 v73, v73, v14
	v_mul_f32_e32 v74, v74, v14
	v_mul_f32_e32 v75, v75, v14
	v_mul_f32_e32 v76, v76, v14
	v_mul_f32_e32 v77, v77, v14
	v_mul_f32_e32 v78, v78, v14
	v_mul_f32_e32 v79, v79, v14
	v_fmac_f32_e32 v80, v64, v20
	v_fmac_f32_e32 v81, v65, v21
	v_fmac_f32_e32 v82, v66, v22
	v_fmac_f32_e32 v83, v67, v23
	v_fmac_f32_e32 v84, v68, v24
	v_fmac_f32_e32 v85, v69, v25
	v_fmac_f32_e32 v86, v70, v26
	v_fmac_f32_e32 v87, v71, v27
	v_fmac_f32_e32 v88, v72, v28
	v_fmac_f32_e32 v89, v73, v29
	v_fmac_f32_e32 v90, v74, v30
	v_fmac_f32_e32 v91, v75, v31
	v_fmac_f32_e32 v92, v76, v32
	v_fmac_f32_e32 v93, v77, v33
	v_fmac_f32_e32 v94, v78, v34
	v_fmac_f32_e32 v95, v79, v35
	global_store_dwordx4 v1, v[80:83], s[24:25] offset:0 nt
	global_store_dwordx4 v1, v[84:87], s[24:25] offset:1024 nt
	global_store_dwordx4 v1, v[88:91], s[24:25] offset:2048 nt
	global_store_dwordx4 v1, v[92:95], s[24:25] offset:3072 nt
	v_mul_f32_e32 v96, v96, v15
	v_mul_f32_e32 v97, v97, v15
	v_mul_f32_e32 v98, v98, v15
	v_mul_f32_e32 v99, v99, v15
	v_mul_f32_e32 v100, v100, v15
	v_mul_f32_e32 v101, v101, v15
	v_mul_f32_e32 v102, v102, v15
	v_mul_f32_e32 v103, v103, v15
	v_mul_f32_e32 v104, v104, v15
	v_mul_f32_e32 v105, v105, v15
	v_mul_f32_e32 v106, v106, v15
	v_mul_f32_e32 v107, v107, v15
	v_mul_f32_e32 v108, v108, v15
	v_mul_f32_e32 v109, v109, v15
	v_mul_f32_e32 v110, v110, v15
	v_mul_f32_e32 v111, v111, v15
	v_fmac_f32_e32 v112, v96, v20
	v_fmac_f32_e32 v113, v97, v21
	v_fmac_f32_e32 v114, v98, v22
	v_fmac_f32_e32 v115, v99, v23
	v_fmac_f32_e32 v116, v100, v24
	v_fmac_f32_e32 v117, v101, v25
	v_fmac_f32_e32 v118, v102, v26
	v_fmac_f32_e32 v119, v103, v27
	v_fmac_f32_e32 v120, v104, v28
	v_fmac_f32_e32 v121, v105, v29
	v_fmac_f32_e32 v122, v106, v30
	v_fmac_f32_e32 v123, v107, v31
	v_fmac_f32_e32 v124, v108, v32
	v_fmac_f32_e32 v125, v109, v33
	v_fmac_f32_e32 v126, v110, v34
	v_fmac_f32_e32 v127, v111, v35
	global_store_dwordx4 v1, v[112:115], s[32:33] offset:0 nt
	global_store_dwordx4 v1, v[116:119], s[32:33] offset:1024 nt
	global_store_dwordx4 v1, v[120:123], s[32:33] offset:2048 nt
	global_store_dwordx4 v1, v[124:127], s[32:33] offset:3072 nt
	s_waitcnt vmcnt(8)
	v_lshlrev_b32_e32 v128, 16, v130
	v_and_b32_e32 v129, 0xffff0000, v130
	v_lshlrev_b32_e32 v130, 16, v131
	v_and_b32_e32 v131, 0xffff0000, v131
	v_lshlrev_b32_e32 v132, 16, v134
	v_and_b32_e32 v133, 0xffff0000, v134
	v_lshlrev_b32_e32 v134, 16, v135
	v_and_b32_e32 v135, 0xffff0000, v135
	v_lshlrev_b32_e32 v136, 16, v138
	v_and_b32_e32 v137, 0xffff0000, v138
	v_lshlrev_b32_e32 v138, 16, v139
	v_and_b32_e32 v139, 0xffff0000, v139
	v_lshlrev_b32_e32 v140, 16, v142
	v_and_b32_e32 v141, 0xffff0000, v142
	v_lshlrev_b32_e32 v142, 16, v143
	v_and_b32_e32 v143, 0xffff0000, v143
	v_lshlrev_b32_e32 v160, 16, v162
	v_and_b32_e32 v161, 0xffff0000, v162
	v_lshlrev_b32_e32 v162, 16, v163
	v_and_b32_e32 v163, 0xffff0000, v163
	v_lshlrev_b32_e32 v164, 16, v166
	v_and_b32_e32 v165, 0xffff0000, v166
	v_lshlrev_b32_e32 v166, 16, v167
	v_and_b32_e32 v167, 0xffff0000, v167
	v_lshlrev_b32_e32 v168, 16, v170
	v_and_b32_e32 v169, 0xffff0000, v170
	v_lshlrev_b32_e32 v170, 16, v171
	v_and_b32_e32 v171, 0xffff0000, v171
	v_lshlrev_b32_e32 v172, 16, v174
	v_and_b32_e32 v173, 0xffff0000, v174
	v_lshlrev_b32_e32 v174, 16, v175
	v_and_b32_e32 v175, 0xffff0000, v175
	v_mul_f32_e32 v10, v128, v128
	v_fmac_f32_e32 v10, v129, v129
	v_fmac_f32_e32 v10, v130, v130
	v_fmac_f32_e32 v10, v131, v131
	v_fmac_f32_e32 v10, v132, v132
	v_fmac_f32_e32 v10, v133, v133
	v_fmac_f32_e32 v10, v134, v134
	v_fmac_f32_e32 v10, v135, v135
	v_fmac_f32_e32 v10, v136, v136
	v_fmac_f32_e32 v10, v137, v137
	v_fmac_f32_e32 v10, v138, v138
	v_fmac_f32_e32 v10, v139, v139
	v_fmac_f32_e32 v10, v140, v140
	v_fmac_f32_e32 v10, v141, v141
	v_fmac_f32_e32 v10, v142, v142
	v_fmac_f32_e32 v10, v143, v143
	v_mul_f32_e32 v11, v160, v160
	v_fmac_f32_e32 v11, v161, v161
	v_fmac_f32_e32 v11, v162, v162
	v_fmac_f32_e32 v11, v163, v163
	v_fmac_f32_e32 v11, v164, v164
	v_fmac_f32_e32 v11, v165, v165
	v_fmac_f32_e32 v11, v166, v166
	v_fmac_f32_e32 v11, v167, v167
	v_fmac_f32_e32 v11, v168, v168
	v_fmac_f32_e32 v11, v169, v169
	v_fmac_f32_e32 v11, v170, v170
	v_fmac_f32_e32 v11, v171, v171
	v_fmac_f32_e32 v11, v172, v172
	v_fmac_f32_e32 v11, v173, v173
	v_fmac_f32_e32 v11, v174, v174
	v_fmac_f32_e32 v11, v175, v175
	ds_bpermute_b32 v12, v4, v10
	ds_bpermute_b32 v13, v4, v11
	s_waitcnt lgkmcnt(0)
	v_add_f32_e32 v10, v10, v12
	v_add_f32_e32 v11, v11, v13
	ds_bpermute_b32 v12, v5, v10
	ds_bpermute_b32 v13, v5, v11
	s_waitcnt lgkmcnt(0)
	v_add_f32_e32 v10, v10, v12
	v_add_f32_e32 v11, v11, v13
	ds_bpermute_b32 v12, v6, v10
	ds_bpermute_b32 v13, v6, v11
	s_waitcnt lgkmcnt(0)
	v_add_f32_e32 v10, v10, v12
	v_add_f32_e32 v11, v11, v13
	ds_bpermute_b32 v12, v7, v10
	ds_bpermute_b32 v13, v7, v11
	s_waitcnt lgkmcnt(0)
	v_add_f32_e32 v10, v10, v12
	v_add_f32_e32 v11, v11, v13
	ds_bpermute_b32 v12, v8, v10
	ds_bpermute_b32 v13, v8, v11
	s_waitcnt lgkmcnt(0)
	v_add_f32_e32 v10, v10, v12
	v_add_f32_e32 v11, v11, v13
	ds_bpermute_b32 v12, v9, v10
	ds_bpermute_b32 v13, v9, v11
	s_waitcnt lgkmcnt(0)
	v_add_f32_e32 v10, v10, v12
	v_add_f32_e32 v11, v11, v13
	v_fma_f32 v14, v10, s17, v3
	v_fma_f32 v15, v11, s17, v3
	v_rsq_f32_e32 v14, v14
	v_rsq_f32_e32 v15, v15
	s_nop 0
	v_mul_f32_e32 v128, v128, v14
	v_mul_f32_e32 v129, v129, v14
	v_mul_f32_e32 v130, v130, v14
	v_mul_f32_e32 v131, v131, v14
	v_mul_f32_e32 v132, v132, v14
	v_mul_f32_e32 v133, v133, v14
	v_mul_f32_e32 v134, v134, v14
	v_mul_f32_e32 v135, v135, v14
	v_mul_f32_e32 v136, v136, v14
	v_mul_f32_e32 v137, v137, v14
	v_mul_f32_e32 v138, v138, v14
	v_mul_f32_e32 v139, v139, v14
	v_mul_f32_e32 v140, v140, v14
	v_mul_f32_e32 v141, v141, v14
	v_mul_f32_e32 v142, v142, v14
	v_mul_f32_e32 v143, v143, v14
	v_fmac_f32_e32 v144, v128, v20
	v_fmac_f32_e32 v145, v129, v21
	v_fmac_f32_e32 v146, v130, v22
	v_fmac_f32_e32 v147, v131, v23
	v_fmac_f32_e32 v148, v132, v24
	v_fmac_f32_e32 v149, v133, v25
	v_fmac_f32_e32 v150, v134, v26
	v_fmac_f32_e32 v151, v135, v27
	v_fmac_f32_e32 v152, v136, v28
	v_fmac_f32_e32 v153, v137, v29
	v_fmac_f32_e32 v154, v138, v30
	v_fmac_f32_e32 v155, v139, v31
	v_fmac_f32_e32 v156, v140, v32
	v_fmac_f32_e32 v157, v141, v33
	v_fmac_f32_e32 v158, v142, v34
	v_fmac_f32_e32 v159, v143, v35
	global_store_dwordx4 v1, v[144:147], s[40:41] offset:0 nt
	global_store_dwordx4 v1, v[148:151], s[40:41] offset:1024 nt
	global_store_dwordx4 v1, v[152:155], s[40:41] offset:2048 nt
	global_store_dwordx4 v1, v[156:159], s[40:41] offset:3072 nt
	v_mul_f32_e32 v160, v160, v15
	v_mul_f32_e32 v161, v161, v15
	v_mul_f32_e32 v162, v162, v15
	v_mul_f32_e32 v163, v163, v15
	v_mul_f32_e32 v164, v164, v15
	v_mul_f32_e32 v165, v165, v15
	v_mul_f32_e32 v166, v166, v15
	v_mul_f32_e32 v167, v167, v15
	v_mul_f32_e32 v168, v168, v15
	v_mul_f32_e32 v169, v169, v15
	v_mul_f32_e32 v170, v170, v15
	v_mul_f32_e32 v171, v171, v15
	v_mul_f32_e32 v172, v172, v15
	v_mul_f32_e32 v173, v173, v15
	v_mul_f32_e32 v174, v174, v15
	v_mul_f32_e32 v175, v175, v15
	v_fmac_f32_e32 v176, v160, v20
	v_fmac_f32_e32 v177, v161, v21
	v_fmac_f32_e32 v178, v162, v22
	v_fmac_f32_e32 v179, v163, v23
	v_fmac_f32_e32 v180, v164, v24
	v_fmac_f32_e32 v181, v165, v25
	v_fmac_f32_e32 v182, v166, v26
	v_fmac_f32_e32 v183, v167, v27
	v_fmac_f32_e32 v184, v168, v28
	v_fmac_f32_e32 v185, v169, v29
	v_fmac_f32_e32 v186, v170, v30
	v_fmac_f32_e32 v187, v171, v31
	v_fmac_f32_e32 v188, v172, v32
	v_fmac_f32_e32 v189, v173, v33
	v_fmac_f32_e32 v190, v174, v34
	v_fmac_f32_e32 v191, v175, v35
	global_store_dwordx4 v1, v[176:179], s[48:49] offset:0 nt
	global_store_dwordx4 v1, v[180:183], s[48:49] offset:1024 nt
	global_store_dwordx4 v1, v[184:187], s[48:49] offset:2048 nt
	global_store_dwordx4 v1, v[188:191], s[48:49] offset:3072 nt
	v_add_f32_e32 v208, v208, v212
	v_add_f32_e32 v209, v209, v213
	v_add_f32_e32 v210, v210, v214
	v_add_f32_e32 v211, v211, v215
	v_add_f32_e32 v216, v216, v220
	v_add_f32_e32 v217, v217, v221
	v_add_f32_e32 v218, v218, v222
	v_add_f32_e32 v219, v219, v223
	v_add_f32_e32 v224, v224, v228
	v_add_f32_e32 v225, v225, v229
	v_add_f32_e32 v226, v226, v230
	v_add_f32_e32 v227, v227, v231
	v_add_f32_e32 v232, v232, v236
	v_add_f32_e32 v233, v233, v237
	v_add_f32_e32 v234, v234, v238
	v_add_f32_e32 v235, v235, v239
	v_add_f32_e32 v208, v208, v216
	v_add_f32_e32 v209, v209, v217
	v_add_f32_e32 v210, v210, v218
	v_add_f32_e32 v211, v211, v219
	v_add_f32_e32 v224, v224, v232
	v_add_f32_e32 v225, v225, v233
	v_add_f32_e32 v226, v226, v234
	v_add_f32_e32 v227, v227, v235
	v_add_f32_e32 v208, v208, v224
	v_add_f32_e32 v209, v209, v225
	v_add_f32_e32 v210, v210, v226
	v_add_f32_e32 v211, v211, v227
	v_readfirstlane_b32 s18, v0
	s_lshr_b32 s18, s18, 6
	s_lshl_b32 s19, s18, 2
	s_and_b32 s52, s18, 4
	s_lshl_b32 s52, s52, 2
	v_mov_b32_e32 v16, s19
	v_mov_b32_e32 v17, s52
	v_mul_f32_e32 v10, v208, v208
	v_fmac_f32_e32 v10, v209, v209
	v_fmac_f32_e32 v10, v210, v210
	v_fmac_f32_e32 v10, v211, v211
	ds_bpermute_b32 v11, v4, v10
	s_waitcnt lgkmcnt(0)
	v_add_f32_e32 v10, v10, v11
	ds_bpermute_b32 v11, v5, v10
	s_waitcnt lgkmcnt(0)
	v_add_f32_e32 v10, v10, v11
	ds_bpermute_b32 v11, v6, v10
	s_waitcnt lgkmcnt(0)
	v_add_f32_e32 v10, v10, v11
	ds_bpermute_b32 v11, v7, v10
	s_waitcnt lgkmcnt(0)
	v_add_f32_e32 v10, v10, v11
	ds_bpermute_b32 v11, v8, v10
	s_waitcnt lgkmcnt(0)
	v_add_f32_e32 v10, v10, v11
	ds_bpermute_b32 v11, v9, v10
	s_waitcnt lgkmcnt(0)
	v_add_f32_e32 v10, v10, v11
	ds_write_b32 v16, v10 offset:0
	s_waitcnt lgkmcnt(0)
	s_barrier
	ds_read_b128 v[12:15], v17 offset:0
	s_waitcnt lgkmcnt(0)
	v_add_f32_e32 v12, v12, v13
	v_add_f32_e32 v14, v14, v15
	v_add_f32_e32 v10, v12, v14
	v_fma_f32 v11, v10, s17, v3
	v_rsq_f32_e32 v11, v11
	s_nop 0
	v_mul_f32_e32 v208, v208, v11
	v_mul_f32_e32 v209, v209, v11
	v_mul_f32_e32 v210, v210, v11
	v_mul_f32_e32 v211, v211, v11
	v_fmac_f32_e32 v240, v208, v244
	v_fmac_f32_e32 v241, v209, v245
	v_fmac_f32_e32 v242, v210, v246
	v_fmac_f32_e32 v243, v211, v247
	s_lshl_b32 s18, s54, 12
	s_add_u32 s18, s18, s55
	s_add_u32 s56, s4, s18
	s_addc_u32 s57, s5, 0
	s_add_u32 s56, s56, 0x4000000
	s_addc_u32 s57, s57, 0
	global_store_dwordx4 v1, v[240:243], s[56:57]
